# attention K/V prefetch kept in flight (no drain before issue) + GEMM first K-iteration peeled with SrcC=0 (no acc zeroing)
# speedup vs baseline: 1.0076x; 1.0067x over previous
; #define PG8_STAGE(bufoff, gbase, voff) do { _Pragma("unroll") for (int _i = 0; _i < 2; ++_i) \
;         __builtin_amdgcn_global_load_lds((const unsigned*)((const char*)(gbase) + (voff)[_i]), (LAS unsigned*)(lds + (bufoff) + ldsw + _i * 8192), 16, 0, 0); } while (0)
; #define PG8_LDA(dst, b, h) do { _Pragma("unroll") for (int m = 0; m < 4; ++m) _Pragma("unroll") for (int k = 0; k < 2; ++k) dst[m][k] = *(const LAS bf16x8*)(lds + PG8_SA(b, h) + aoff + m * 2048 + k * 1024); } while (0)
; #define PG8_LDB(dst, b, h) do { _Pragma("unroll") for (int n = 0; n < 2; ++n) _Pragma("unroll") for (int k = 0; k < 2; ++k) dst[n][k] = *(const LAS bf16x8*)(lds + PG8_SB(b, h) + boff + n * 2048 + k * 1024); } while (0)
; #define PG8_MMA(ai, bj, At, Bt) do { __builtin_amdgcn_s_setprio(1); _Pragma("unroll") for (int m = 0; m < 4; ++m) _Pragma("unroll") for (int n = 0; n < 2; ++n) _Pragma("unroll") for (int k = 0; k < 2; ++k) \
;         acc[ai][bj][m][n] = __builtin_amdgcn_mfma_f32_16x16x32_bf16(Bt[n][k], At[m][k], acc[ai][bj][m][n], 0, 0, 0); __builtin_amdgcn_s_setprio(0); } while (0)
; #define PG8_WAIT_V(n) asm volatile("s_waitcnt vmcnt(" #n ")" ::: "memory")
; #define PG8_WAIT_L(n) asm volatile("s_waitcnt lgkmcnt(" #n ")" ::: "memory")
; #define PG8_BAR __builtin_amdgcn_s_barrier()
; #define PG8_SCHED __builtin_amdgcn_sched_barrier(0)
; template <class Epi, bool ALIGN_EPI>
; DI void gemm_phase(LAS unsigned char* lds, const Sched& S, const Epi& E, int tid) {
;     ...
;         for (int t = 0; t < nt; t += 2) {
;             const bool last = (t == nt - 2);
;             const char* a1 = cA + (size_t)(t + 1) * kstep;
;             const char* a2 = last ? nA : cA + (size_t)(t + 2) * kstep; const char* b2 = last ? nB : cB + (size_t)(t + 2) * kstep;
;             const char* a3 = a2 + kstep; const char* b3 = b2 + kstep;
;             PG8_LDB(B0, 0, 0); PG8_LDB(B1, 0, 1); PG8_SCHED; PG8_LDA(At, 0, 0); PG8_STAGE(PG8_SA(1, 1), a1 + hstepA, voffA);
;             PG8_WAIT_V(8); PG8_WAIT_L(0); PG8_BAR; PG8_MMA(0, 0, At, B0); PG8_MMA(0, 1, At, B1); PG8_BAR; PG8_SCHED;
;             PG8_LDA(At, 0, 1); PG8_STAGE(PG8_SB(0, 0), b2, voffB); PG8_STAGE(PG8_SB(0, 1), b2 + hstepB, voffB); PG8_STAGE(PG8_SA(0, 0), a2, voffA);
;             PG8_WAIT_V(8); PG8_WAIT_L(0); PG8_BAR; PG8_MMA(1, 0, At, B0); PG8_MMA(1, 1, At, B1); PG8_BAR; PG8_SCHED;
.LBB0_324:
	s_add_u32 s22, s22, 0x40080
	s_addc_u32 s23, s23, 0
	s_add_u32 s45, s24, 0x100
	s_addc_u32 s46, s25, 0
	s_mov_b32 s47, -2
	s_add_u32 s24, s22, 0xfffc0080
	s_addc_u32 s25, s23, -1
	s_add_i32 s48, 0, 0x10000
	s_cmp_eq_u32 s47, 12
	s_cselect_b32 s27, s19, s25
	s_cselect_b32 s26, s18, s24
	v_add_u32_e32 v161, s48, v144
	s_cselect_b32 s25, s21, s46
	s_cselect_b32 s24, s20, s45
	s_add_i32 s50, 0, 0x14000
	ds_read_b128 v[148:151], v161
	ds_read_b128 v[152:155], v161 offset:1024
	ds_read_b128 v[156:159], v161 offset:2048
	ds_read_b128 v[162:165], v161 offset:3072
	v_add_u32_e32 v161, s50, v144
	ds_read_b128 v[166:169], v161
	ds_read_b128 v[170:173], v161 offset:1024
	ds_read_b128 v[174:177], v161 offset:2048
	ds_read_b128 v[178:181], v161 offset:3072
	v_lshl_add_u64 v[194:195], s[22:23], 0, v[140:141]
	s_add_i32 m0, s17, 0xc000
	ds_read_b128 v[182:185], v147
	ds_read_b128 v[186:189], v147 offset:1024
	ds_read_b128 v[190:193], v147 offset:2048
	ds_read_b128 v[202:205], v147 offset:3072
	ds_read_b128 v[206:209], v147 offset:4096
	ds_read_b128 v[210:213], v147 offset:5120
	ds_read_b128 v[214:217], v147 offset:6144
	ds_read_b128 v[218:221], v147 offset:7168
	global_load_lds_dwordx4 v[194:195], off
	v_lshl_add_u64 v[194:195], s[22:23], 0, v[142:143]
	s_add_i32 m0, s17, 0xe000
	s_nop 0
	global_load_lds_dwordx4 v[194:195], off
	s_waitcnt vmcnt(8)
	s_waitcnt lgkmcnt(0)
	s_barrier
	s_setprio 1
	s_waitcnt lgkmcnt(0)
	v_mfma_f32_16x16x32_bf16 v[128:131], v[148:151], v[182:185], 0
	v_mfma_f32_16x16x32_bf16 v[124:127], v[156:159], v[182:185], 0
	v_mfma_f32_16x16x32_bf16 v[112:115], v[148:151], v[190:193], 0
	v_mfma_f32_16x16x32_bf16 v[108:111], v[156:159], v[190:193], 0
	v_mfma_f32_16x16x32_bf16 v[96:99], v[148:151], v[206:209], 0
	v_mfma_f32_16x16x32_bf16 v[92:95], v[156:159], v[206:209], 0
	v_mfma_f32_16x16x32_bf16 v[80:83], v[148:151], v[214:217], 0
	v_mfma_f32_16x16x32_bf16 v[76:79], v[156:159], v[214:217], 0
	v_mfma_f32_16x16x32_bf16 v[128:131], v[152:155], v[186:189], v[128:131]
	v_mfma_f32_16x16x32_bf16 v[124:127], v[162:165], v[186:189], v[124:127]
	v_mfma_f32_16x16x32_bf16 v[112:115], v[152:155], v[202:205], v[112:115]
	v_mfma_f32_16x16x32_bf16 v[108:111], v[162:165], v[202:205], v[108:111]
	v_mfma_f32_16x16x32_bf16 v[96:99], v[152:155], v[210:213], v[96:99]
	v_mfma_f32_16x16x32_bf16 v[92:95], v[162:165], v[210:213], v[92:95]
	v_mfma_f32_16x16x32_bf16 v[80:83], v[152:155], v[218:221], v[80:83]
	v_mfma_f32_16x16x32_bf16 v[76:79], v[162:165], v[218:221], v[76:79]
	s_setprio 0
	s_setprio 1
	v_mfma_f32_16x16x32_bf16 v[120:123], v[166:169], v[182:185], 0
	v_mfma_f32_16x16x32_bf16 v[116:119], v[174:177], v[182:185], 0
	v_mfma_f32_16x16x32_bf16 v[104:107], v[166:169], v[190:193], 0
	v_mfma_f32_16x16x32_bf16 v[100:103], v[174:177], v[190:193], 0
	v_mfma_f32_16x16x32_bf16 v[88:91], v[166:169], v[206:209], 0
	v_mfma_f32_16x16x32_bf16 v[84:87], v[174:177], v[206:209], 0
	v_mfma_f32_16x16x32_bf16 v[72:75], v[166:169], v[214:217], 0
	v_mfma_f32_16x16x32_bf16 v[68:71], v[174:177], v[214:217], 0
	v_mfma_f32_16x16x32_bf16 v[120:123], v[170:173], v[186:189], v[120:123]
	v_mfma_f32_16x16x32_bf16 v[116:119], v[178:181], v[186:189], v[116:119]
	v_mfma_f32_16x16x32_bf16 v[104:107], v[170:173], v[202:205], v[104:107]
	v_mfma_f32_16x16x32_bf16 v[100:103], v[178:181], v[202:205], v[100:103]
	v_mfma_f32_16x16x32_bf16 v[88:91], v[170:173], v[210:213], v[88:91]
	v_mfma_f32_16x16x32_bf16 v[84:87], v[178:181], v[210:213], v[84:87]
	v_mfma_f32_16x16x32_bf16 v[72:75], v[170:173], v[218:221], v[72:75]
	v_mfma_f32_16x16x32_bf16 v[68:71], v[178:181], v[218:221], v[68:71]
	s_setprio 0
	s_barrier
	s_add_i32 s48, s48, s28
	v_lshl_add_u64 v[194:195], s[24:25], 0, v[136:137]
	s_mov_b32 m0, s48
	ds_read_b128 v[182:185], v147 offset:16384
	ds_read_b128 v[186:189], v147 offset:17408
	ds_read_b128 v[190:193], v147 offset:18432
	ds_read_b128 v[202:205], v147 offset:19456
	ds_read_b128 v[206:209], v147 offset:20480
	ds_read_b128 v[210:213], v147 offset:21504
	ds_read_b128 v[214:217], v147 offset:22528
	ds_read_b128 v[218:221], v147 offset:23552
	global_load_lds_dwordx4 v[194:195], off
	s_add_i32 m0, s48, 0x2000
	s_add_u32 s48, s24, 0x40000
	v_lshl_add_u64 v[222:223], s[24:25], 0, v[132:133]
	s_addc_u32 s49, s25, 0
	s_add_i32 s50, s50, s28
	global_load_lds_dwordx4 v[222:223], off
	v_lshl_add_u64 v[224:225], s[48:49], 0, v[136:137]
	s_mov_b32 m0, s50
	v_lshl_add_u64 v[226:227], s[26:27], 0, v[134:135]
	global_load_lds_dwordx4 v[224:225], off
	v_lshl_add_u64 v[224:225], s[48:49], 0, v[132:133]
	s_add_i32 m0, s50, 0x2000
	s_nop 0
	global_load_lds_dwordx4 v[224:225], off
	v_lshl_add_u64 v[224:225], s[26:27], 0, v[138:139]
	s_mov_b32 m0, s17
	s_nop 0
	global_load_lds_dwordx4 v[224:225], off
	s_mov_b32 m0, s36
	s_nop 0
	global_load_lds_dwordx4 v[226:227], off
	s_waitcnt vmcnt(8)
	s_waitcnt lgkmcnt(0)
	s_barrier
; #define PG8_STAGE(bufoff, gbase, voff) do { _Pragma("unroll") for (int _i = 0; _i < 2; ++_i) \
;         __builtin_amdgcn_global_load_lds((const unsigned*)((const char*)(gbase) + (voff)[_i]), (LAS unsigned*)(lds + (bufoff) + ldsw + _i * 8192), 16, 0, 0); } while (0)
; #define PG8_LDA(dst, b, h) do { _Pragma("unroll") for (int m = 0; m < 4; ++m) _Pragma("unroll") for (int k = 0; k < 2; ++k) dst[m][k] = *(const LAS bf16x8*)(lds + PG8_SA(b, h) + aoff + m * 2048 + k * 1024); } while (0)
; #define PG8_LDB(dst, b, h) do { _Pragma("unroll") for (int n = 0; n < 2; ++n) _Pragma("unroll") for (int k = 0; k < 2; ++k) dst[n][k] = *(const LAS bf16x8*)(lds + PG8_SB(b, h) + boff + n * 2048 + k * 1024); } while (0)
; #define PG8_MMA(ai, bj, At, Bt) do { __builtin_amdgcn_s_setprio(1); _Pragma("unroll") for (int m = 0; m < 4; ++m) _Pragma("unroll") for (int n = 0; n < 2; ++n) _Pragma("unroll") for (int k = 0; k < 2; ++k) \
;         acc[ai][bj][m][n] = __builtin_amdgcn_mfma_f32_16x16x32_bf16(Bt[n][k], At[m][k], acc[ai][bj][m][n], 0, 0, 0); __builtin_amdgcn_s_setprio(0); } while (0)
; #define PG8_WAIT_V(n) asm volatile("s_waitcnt vmcnt(" #n ")" ::: "memory")
; #define PG8_WAIT_L(n) asm volatile("s_waitcnt lgkmcnt(" #n ")" ::: "memory")
; #define PG8_BAR __builtin_amdgcn_s_barrier()
; #define PG8_SCHED __builtin_amdgcn_sched_barrier(0)
; template <class Epi, bool ALIGN_EPI>
; DI void gemm_phase(LAS unsigned char* lds, const Sched& S, const Epi& E, int tid) {
;     ...
;             PG8_WAIT_V(8); PG8_WAIT_L(0); PG8_BAR; PG8_MMA(1, 0, At, B0); PG8_MMA(1, 1, At, B1); PG8_BAR; PG8_SCHED;
;             PG8_LDB(B0, 1, 0); PG8_LDB(B1, 1, 1); PG8_SCHED; PG8_LDA(At, 1, 0); PG8_STAGE(PG8_SA(0, 1), a2 + hstepA, voffA);
;             PG8_WAIT_V(8); PG8_WAIT_L(0); PG8_BAR; PG8_MMA(0, 0, At, B0); PG8_MMA(0, 1, At, B1); PG8_BAR; PG8_SCHED;
	s_setprio 1
	s_waitcnt lgkmcnt(0)
	v_mfma_f32_16x16x32_bf16 v[64:67], v[148:151], v[182:185], 0
	v_mfma_f32_16x16x32_bf16 v[60:63], v[156:159], v[182:185], 0
	v_mfma_f32_16x16x32_bf16 v[48:51], v[148:151], v[190:193], 0
	v_mfma_f32_16x16x32_bf16 v[44:47], v[156:159], v[190:193], 0
	v_mfma_f32_16x16x32_bf16 v[32:35], v[148:151], v[206:209], 0
	v_mfma_f32_16x16x32_bf16 v[28:31], v[156:159], v[206:209], 0
	v_mfma_f32_16x16x32_bf16 v[16:19], v[148:151], v[214:217], 0
	v_mfma_f32_16x16x32_bf16 v[12:15], v[156:159], v[214:217], 0
	v_mfma_f32_16x16x32_bf16 v[64:67], v[152:155], v[186:189], v[64:67]
	v_mfma_f32_16x16x32_bf16 v[60:63], v[162:165], v[186:189], v[60:63]
	v_mfma_f32_16x16x32_bf16 v[48:51], v[152:155], v[202:205], v[48:51]
	v_mfma_f32_16x16x32_bf16 v[44:47], v[162:165], v[202:205], v[44:47]
	v_mfma_f32_16x16x32_bf16 v[32:35], v[152:155], v[210:213], v[32:35]
	v_mfma_f32_16x16x32_bf16 v[28:31], v[162:165], v[210:213], v[28:31]
	v_mfma_f32_16x16x32_bf16 v[16:19], v[152:155], v[218:221], v[16:19]
	v_mfma_f32_16x16x32_bf16 v[12:15], v[162:165], v[218:221], v[12:15]
	s_setprio 0
	s_setprio 1
	v_mfma_f32_16x16x32_bf16 v[56:59], v[166:169], v[182:185], 0
	v_mfma_f32_16x16x32_bf16 v[52:55], v[174:177], v[182:185], 0
	v_mfma_f32_16x16x32_bf16 v[40:43], v[166:169], v[190:193], 0
	v_mfma_f32_16x16x32_bf16 v[36:39], v[174:177], v[190:193], 0
	v_mfma_f32_16x16x32_bf16 v[24:27], v[166:169], v[206:209], 0
	v_mfma_f32_16x16x32_bf16 v[20:23], v[174:177], v[206:209], 0
	v_mfma_f32_16x16x32_bf16 v[8:11], v[166:169], v[214:217], 0
	v_mfma_f32_16x16x32_bf16 v[4:7], v[174:177], v[214:217], 0
	v_mfma_f32_16x16x32_bf16 v[56:59], v[170:173], v[186:189], v[56:59]
	v_mfma_f32_16x16x32_bf16 v[52:55], v[178:181], v[186:189], v[52:55]
	v_mfma_f32_16x16x32_bf16 v[40:43], v[170:173], v[202:205], v[40:43]
	v_mfma_f32_16x16x32_bf16 v[36:39], v[178:181], v[202:205], v[36:39]
	v_mfma_f32_16x16x32_bf16 v[24:27], v[170:173], v[210:213], v[24:27]
	v_mfma_f32_16x16x32_bf16 v[20:23], v[178:181], v[210:213], v[20:23]
	v_mfma_f32_16x16x32_bf16 v[8:11], v[170:173], v[218:221], v[8:11]
	v_mfma_f32_16x16x32_bf16 v[4:7], v[178:181], v[218:221], v[4:7]
	s_setprio 0
	s_barrier
	s_add_i32 s48, 0, 0x18000
	v_add_u32_e32 v161, s48, v144
	s_add_i32 s49, 0, 0x1c000
	ds_read_b128 v[148:151], v161
	ds_read_b128 v[152:155], v161 offset:1024
	ds_read_b128 v[156:159], v161 offset:2048
	ds_read_b128 v[162:165], v161 offset:3072
	v_add_u32_e32 v161, s49, v144
	ds_read_b128 v[166:169], v161
	ds_read_b128 v[170:173], v161 offset:1024
	ds_read_b128 v[174:177], v161 offset:2048
	ds_read_b128 v[178:181], v161 offset:3072
	s_add_u32 s26, s26, 0x40000
	s_addc_u32 s27, s27, 0
	s_mov_b32 m0, s37
	v_lshl_add_u64 v[228:229], s[26:27], 0, v[138:139]
	ds_read_b128 v[182:185], v147 offset:32768
	ds_read_b128 v[186:189], v147 offset:33792
	ds_read_b128 v[190:193], v147 offset:34816
	ds_read_b128 v[202:205], v147 offset:35840
	ds_read_b128 v[206:209], v147 offset:36864
	ds_read_b128 v[210:213], v147 offset:37888
	ds_read_b128 v[214:217], v147 offset:38912
	ds_read_b128 v[218:221], v147 offset:39936
	global_load_lds_dwordx4 v[228:229], off
	v_lshl_add_u64 v[228:229], s[26:27], 0, v[134:135]
	s_mov_b32 m0, s38
	s_nop 0
	global_load_lds_dwordx4 v[228:229], off
	s_waitcnt vmcnt(8)
	s_waitcnt lgkmcnt(0)
	s_barrier
	s_setprio 1
	s_waitcnt lgkmcnt(0)
	v_mfma_f32_16x16x32_bf16 v[128:131], v[148:151], v[182:185], v[128:131]
	v_mfma_f32_16x16x32_bf16 v[124:127], v[156:159], v[182:185], v[124:127]
	v_mfma_f32_16x16x32_bf16 v[112:115], v[148:151], v[190:193], v[112:115]
	v_mfma_f32_16x16x32_bf16 v[108:111], v[156:159], v[190:193], v[108:111]
	v_mfma_f32_16x16x32_bf16 v[96:99], v[148:151], v[206:209], v[96:99]
	v_mfma_f32_16x16x32_bf16 v[92:95], v[156:159], v[206:209], v[92:95]
	v_mfma_f32_16x16x32_bf16 v[80:83], v[148:151], v[214:217], v[80:83]
	v_mfma_f32_16x16x32_bf16 v[76:79], v[156:159], v[214:217], v[76:79]
	v_mfma_f32_16x16x32_bf16 v[128:131], v[152:155], v[186:189], v[128:131]
	v_mfma_f32_16x16x32_bf16 v[124:127], v[162:165], v[186:189], v[124:127]
	v_mfma_f32_16x16x32_bf16 v[112:115], v[152:155], v[202:205], v[112:115]
	v_mfma_f32_16x16x32_bf16 v[108:111], v[162:165], v[202:205], v[108:111]
	v_mfma_f32_16x16x32_bf16 v[96:99], v[152:155], v[210:213], v[96:99]
	v_mfma_f32_16x16x32_bf16 v[92:95], v[162:165], v[210:213], v[92:95]
	v_mfma_f32_16x16x32_bf16 v[80:83], v[152:155], v[218:221], v[80:83]
	v_mfma_f32_16x16x32_bf16 v[76:79], v[162:165], v[218:221], v[76:79]
	s_setprio 0
	s_setprio 1
	v_mfma_f32_16x16x32_bf16 v[120:123], v[166:169], v[182:185], v[120:123]
	v_mfma_f32_16x16x32_bf16 v[116:119], v[174:177], v[182:185], v[116:119]
	v_mfma_f32_16x16x32_bf16 v[104:107], v[166:169], v[190:193], v[104:107]
	v_mfma_f32_16x16x32_bf16 v[100:103], v[174:177], v[190:193], v[100:103]
	v_mfma_f32_16x16x32_bf16 v[88:91], v[166:169], v[206:209], v[88:91]
	v_mfma_f32_16x16x32_bf16 v[84:87], v[174:177], v[206:209], v[84:87]
	v_mfma_f32_16x16x32_bf16 v[72:75], v[166:169], v[214:217], v[72:75]
	v_mfma_f32_16x16x32_bf16 v[68:71], v[174:177], v[214:217], v[68:71]
	v_mfma_f32_16x16x32_bf16 v[120:123], v[170:173], v[186:189], v[120:123]
	v_mfma_f32_16x16x32_bf16 v[116:119], v[178:181], v[186:189], v[116:119]
	v_mfma_f32_16x16x32_bf16 v[104:107], v[170:173], v[202:205], v[104:107]
	v_mfma_f32_16x16x32_bf16 v[100:103], v[178:181], v[202:205], v[100:103]
	v_mfma_f32_16x16x32_bf16 v[88:91], v[170:173], v[210:213], v[88:91]
	v_mfma_f32_16x16x32_bf16 v[84:87], v[178:181], v[210:213], v[84:87]
	v_mfma_f32_16x16x32_bf16 v[72:75], v[170:173], v[218:221], v[72:75]
	v_mfma_f32_16x16x32_bf16 v[68:71], v[178:181], v[218:221], v[68:71]
	s_setprio 0
	s_barrier
; #define PG8_STAGE(bufoff, gbase, voff) do { _Pragma("unroll") for (int _i = 0; _i < 2; ++_i) \
;         __builtin_amdgcn_global_load_lds((const unsigned*)((const char*)(gbase) + (voff)[_i]), (LAS unsigned*)(lds + (bufoff) + ldsw + _i * 8192), 16, 0, 0); } while (0)
; #define PG8_LDA(dst, b, h) do { _Pragma("unroll") for (int m = 0; m < 4; ++m) _Pragma("unroll") for (int k = 0; k < 2; ++k) dst[m][k] = *(const LAS bf16x8*)(lds + PG8_SA(b, h) + aoff + m * 2048 + k * 1024); } while (0)
; #define PG8_MMA(ai, bj, At, Bt) do { __builtin_amdgcn_s_setprio(1); _Pragma("unroll") for (int m = 0; m < 4; ++m) _Pragma("unroll") for (int n = 0; n < 2; ++n) _Pragma("unroll") for (int k = 0; k < 2; ++k) \
;         acc[ai][bj][m][n] = __builtin_amdgcn_mfma_f32_16x16x32_bf16(Bt[n][k], At[m][k], acc[ai][bj][m][n], 0, 0, 0); __builtin_amdgcn_s_setprio(0); } while (0)
; #define PG8_WAIT_V(n) asm volatile("s_waitcnt vmcnt(" #n ")" ::: "memory")
; #define PG8_WAIT_L(n) asm volatile("s_waitcnt lgkmcnt(" #n ")" ::: "memory")
; #define PG8_BAR __builtin_amdgcn_s_barrier()
; #define PG8_SCHED __builtin_amdgcn_sched_barrier(0)
; template <class Epi, bool ALIGN_EPI>
; DI void gemm_phase(LAS unsigned char* lds, const Sched& S, const Epi& E, int tid) {
;     ...
;             PG8_LDA(At, 1, 1); PG8_STAGE(PG8_SB(1, 0), b3, voffB); PG8_STAGE(PG8_SB(1, 1), b3 + hstepB, voffB); PG8_STAGE(PG8_SA(1, 0), a3, voffA);
;             PG8_WAIT_V(8); PG8_WAIT_L(0); PG8_BAR; PG8_MMA(1, 0, At, B0); PG8_MMA(1, 1, At, B1); PG8_BAR; PG8_SCHED;
;         }
	s_add_i32 s26, s48, s28
	v_lshl_add_u64 v[194:195], v[194:195], 0, s[84:85]
	s_mov_b32 m0, s26
	ds_read_b128 v[182:185], v147 offset:49152
	ds_read_b128 v[186:189], v147 offset:50176
	ds_read_b128 v[190:193], v147 offset:51200
	ds_read_b128 v[202:205], v147 offset:52224
	ds_read_b128 v[206:209], v147 offset:53248
	ds_read_b128 v[210:213], v147 offset:54272
	ds_read_b128 v[214:217], v147 offset:55296
	ds_read_b128 v[218:221], v147 offset:56320
	global_load_lds_dwordx4 v[194:195], off
	s_add_i32 m0, s26, 0x2000
	s_add_u32 s24, s24, 0x40080
	v_lshl_add_u64 v[194:195], v[222:223], 0, s[84:85]
	s_addc_u32 s25, s25, 0
	s_add_i32 s26, s49, s28
	global_load_lds_dwordx4 v[194:195], off
	v_lshl_add_u64 v[194:195], s[24:25], 0, v[136:137]
	s_mov_b32 m0, s26
	s_nop 0
	global_load_lds_dwordx4 v[194:195], off
	v_lshl_add_u64 v[194:195], s[24:25], 0, v[132:133]
	s_add_i32 m0, s26, 0x2000
	s_nop 0
	global_load_lds_dwordx4 v[194:195], off
	v_lshl_add_u64 v[194:195], v[224:225], 0, s[84:85]
	s_mov_b32 m0, s39
	s_nop 0
	global_load_lds_dwordx4 v[194:195], off
	v_lshl_add_u64 v[194:195], v[226:227], 0, s[84:85]
	s_mov_b32 m0, s40
	s_nop 0
	global_load_lds_dwordx4 v[194:195], off
	s_waitcnt vmcnt(8)
	s_waitcnt lgkmcnt(0)
	s_barrier
	s_setprio 1
	s_waitcnt lgkmcnt(0)
	v_mfma_f32_16x16x32_bf16 v[64:67], v[148:151], v[182:185], v[64:67]
	v_mfma_f32_16x16x32_bf16 v[60:63], v[156:159], v[182:185], v[60:63]
	v_mfma_f32_16x16x32_bf16 v[48:51], v[148:151], v[190:193], v[48:51]
	v_mfma_f32_16x16x32_bf16 v[44:47], v[156:159], v[190:193], v[44:47]
	v_mfma_f32_16x16x32_bf16 v[32:35], v[148:151], v[206:209], v[32:35]
	v_mfma_f32_16x16x32_bf16 v[28:31], v[156:159], v[206:209], v[28:31]
	v_mfma_f32_16x16x32_bf16 v[16:19], v[148:151], v[214:217], v[16:19]
	v_mfma_f32_16x16x32_bf16 v[12:15], v[156:159], v[214:217], v[12:15]
	v_mfma_f32_16x16x32_bf16 v[64:67], v[152:155], v[186:189], v[64:67]
	v_mfma_f32_16x16x32_bf16 v[60:63], v[162:165], v[186:189], v[60:63]
	v_mfma_f32_16x16x32_bf16 v[48:51], v[152:155], v[202:205], v[48:51]
	v_mfma_f32_16x16x32_bf16 v[44:47], v[162:165], v[202:205], v[44:47]
	v_mfma_f32_16x16x32_bf16 v[32:35], v[152:155], v[210:213], v[32:35]
	v_mfma_f32_16x16x32_bf16 v[28:31], v[162:165], v[210:213], v[28:31]
	v_mfma_f32_16x16x32_bf16 v[16:19], v[152:155], v[218:221], v[16:19]
	v_mfma_f32_16x16x32_bf16 v[12:15], v[162:165], v[218:221], v[12:15]
	s_setprio 0
	s_setprio 1
	v_mfma_f32_16x16x32_bf16 v[56:59], v[166:169], v[182:185], v[56:59]
	v_mfma_f32_16x16x32_bf16 v[52:55], v[174:177], v[182:185], v[52:55]
	v_mfma_f32_16x16x32_bf16 v[40:43], v[166:169], v[190:193], v[40:43]
	v_mfma_f32_16x16x32_bf16 v[36:39], v[174:177], v[190:193], v[36:39]
	v_mfma_f32_16x16x32_bf16 v[24:27], v[166:169], v[206:209], v[24:27]
	v_mfma_f32_16x16x32_bf16 v[20:23], v[174:177], v[206:209], v[20:23]
	v_mfma_f32_16x16x32_bf16 v[8:11], v[166:169], v[214:217], v[8:11]
	v_mfma_f32_16x16x32_bf16 v[4:7], v[174:177], v[214:217], v[4:7]
	v_mfma_f32_16x16x32_bf16 v[56:59], v[170:173], v[186:189], v[56:59]
	v_mfma_f32_16x16x32_bf16 v[52:55], v[178:181], v[186:189], v[52:55]
	v_mfma_f32_16x16x32_bf16 v[40:43], v[170:173], v[202:205], v[40:43]
	v_mfma_f32_16x16x32_bf16 v[36:39], v[178:181], v[202:205], v[36:39]
	v_mfma_f32_16x16x32_bf16 v[24:27], v[170:173], v[210:213], v[24:27]
	v_mfma_f32_16x16x32_bf16 v[20:23], v[178:181], v[210:213], v[20:23]
	v_mfma_f32_16x16x32_bf16 v[8:11], v[170:173], v[218:221], v[8:11]
	v_mfma_f32_16x16x32_bf16 v[4:7], v[178:181], v[218:221], v[4:7]
	s_setprio 0
	s_barrier
	s_add_i32 s47, s47, 2
	s_add_u32 s22, s22, 0x100
	s_addc_u32 s23, s23, 0
	s_add_u32 s45, s45, 0x100
	s_addc_u32 s46, s46, 0
	s_cmp_gt_u32 s47, 13

; #define PG8_STAGE(bufoff, gbase, voff) do { _Pragma("unroll") for (int _i = 0; _i < 2; ++_i) \
;         __builtin_amdgcn_global_load_lds((const unsigned*)((const char*)(gbase) + (voff)[_i]), (LAS unsigned*)(lds + (bufoff) + ldsw + _i * 8192), 16, 0, 0); } while (0)
; #define PG8_LDA(dst, b, h) do { _Pragma("unroll") for (int m = 0; m < 4; ++m) _Pragma("unroll") for (int k = 0; k < 2; ++k) dst[m][k] = *(const LAS bf16x8*)(lds + PG8_SA(b, h) + aoff + m * 2048 + k * 1024); } while (0)
; #define PG8_LDB(dst, b, h) do { _Pragma("unroll") for (int n = 0; n < 2; ++n) _Pragma("unroll") for (int k = 0; k < 2; ++k) dst[n][k] = *(const LAS bf16x8*)(lds + PG8_SB(b, h) + boff + n * 2048 + k * 1024); } while (0)
; #define PG8_MMA(ai, bj, At, Bt) do { __builtin_amdgcn_s_setprio(1); _Pragma("unroll") for (int m = 0; m < 4; ++m) _Pragma("unroll") for (int n = 0; n < 2; ++n) _Pragma("unroll") for (int k = 0; k < 2; ++k) \
;         acc[ai][bj][m][n] = __builtin_amdgcn_mfma_f32_16x16x32_bf16(Bt[n][k], At[m][k], acc[ai][bj][m][n], 0, 0, 0); __builtin_amdgcn_s_setprio(0); } while (0)
; #define PG8_WAIT_V(n) asm volatile("s_waitcnt vmcnt(" #n ")" ::: "memory")
; #define PG8_BAR __builtin_amdgcn_s_barrier()
; template <class Epi, bool ALIGN_EPI>
; DI void gemm_phase(LAS unsigned char* lds, const Sched& S, const Epi& E, int tid) {
;     ...
;         const bool has_next = S.next(ui + 1, nxt);
;         const char* nA = has_next ? nxt.a : cA; const char* nB = has_next ? nxt.b : cB;
;         const int nt = cur.nt;
;         for (int t = 0; t < nt; t += 2) {
;             const bool last = (t == nt - 2);
;             const char* a1 = cA + (size_t)(t + 1) * kstep;
;             const char* a2 = last ? nA : cA + (size_t)(t + 2) * kstep; const char* b2 = last ? nB : cB + (size_t)(t + 2) * kstep;
;             const char* a3 = a2 + kstep; const char* b3 = b2 + kstep;
;             PG8_LDB(B0, 0, 0); PG8_LDB(B1, 0, 1); PG8_SCHED; PG8_LDA(At, 0, 0); PG8_STAGE(PG8_SA(1, 1), a1 + hstepA, voffA);
;             PG8_WAIT_V(8); PG8_WAIT_L(0); PG8_BAR; PG8_MMA(0, 0, At, B0); PG8_MMA(0, 1, At, B1); PG8_BAR; PG8_SCHED;
;             PG8_LDA(At, 0, 1); PG8_STAGE(PG8_SB(0, 0), b2, voffB); PG8_STAGE(PG8_SB(0, 1), b2 + hstepB, voffB); PG8_STAGE(PG8_SA(0, 0), a2, voffA);
;             PG8_WAIT_V(8); PG8_WAIT_L(0); PG8_BAR; PG8_MMA(1, 0, At, B0); PG8_MMA(1, 1, At, B1); PG8_BAR; PG8_SCHED;
.LBB0_411:
	s_and_b64 s[24:25], s[16:17], exec
	s_cselect_b32 s56, s13, s21
	s_cselect_b32 s57, s12, s20
	s_cselect_b32 s58, s15, s23
	s_cselect_b32 s59, s14, s22
	s_add_i32 s60, s55, -2
	s_add_u32 s61, s22, 0x100
	s_mov_b32 s81, s63
	s_addc_u32 s62, s23, 0
	s_mov_b32 s24, 0
	s_waitcnt lgkmcnt(0)
	s_waitcnt lgkmcnt(0)
	s_add_i32 s63, s24, 2
	s_add_u32 s22, s20, 0x100
	s_addc_u32 s23, s21, 0
	s_add_i32 s64, 0, 0x10000
	s_cmp_eq_u32 s60, s24
	s_cselect_b32 s27, s56, s23
	s_cselect_b32 s26, s57, s22
	s_cselect_b32 s25, s58, s62
	s_cselect_b32 s24, s59, s61
	s_add_i32 s65, 0, 0x14000
	v_add_u32_e32 v144, s64, v161
	v_add_u32_e32 v174, s65, v161
	ds_read_b128 v[132:135], v144
	ds_read_b128 v[136:139], v144 offset:1024
	ds_read_b128 v[140:143], v144 offset:2048
	ds_read_b128 v[144:147], v144 offset:3072
	ds_read_b128 v[148:151], v174
	ds_read_b128 v[152:155], v174 offset:1024
	ds_read_b128 v[156:159], v174 offset:2048
	ds_read_b128 v[174:177], v174 offset:3072
	v_lshl_add_u64 v[190:191], s[20:21], 0, v[170:171]
	s_add_i32 m0, s39, 0xc000
	ds_read_b128 v[178:181], v193
	ds_read_b128 v[182:185], v193 offset:1024
	ds_read_b128 v[186:189], v193 offset:2048
	ds_read_b128 v[202:205], v193 offset:3072
	ds_read_b128 v[206:209], v193 offset:4096
	ds_read_b128 v[210:213], v193 offset:5120
	ds_read_b128 v[214:217], v193 offset:6144
	ds_read_b128 v[218:221], v193 offset:7168
	global_load_lds_dwordx4 v[190:191], off
	v_lshl_add_u64 v[190:191], s[20:21], 0, v[172:173]
	s_add_i32 m0, s39, 0xe000
	s_nop 0
	global_load_lds_dwordx4 v[190:191], off
	s_waitcnt vmcnt(8)
	s_waitcnt lgkmcnt(0)
	s_barrier
	s_setprio 1
	s_waitcnt lgkmcnt(0)
	v_mfma_f32_16x16x32_bf16 v[128:131], v[132:135], v[178:181], 0
	v_mfma_f32_16x16x32_bf16 v[124:127], v[140:143], v[178:181], 0
	v_mfma_f32_16x16x32_bf16 v[112:115], v[132:135], v[186:189], 0
	v_mfma_f32_16x16x32_bf16 v[108:111], v[140:143], v[186:189], 0
	v_mfma_f32_16x16x32_bf16 v[96:99], v[132:135], v[206:209], 0
	v_mfma_f32_16x16x32_bf16 v[92:95], v[140:143], v[206:209], 0
	v_mfma_f32_16x16x32_bf16 v[80:83], v[132:135], v[214:217], 0
	v_mfma_f32_16x16x32_bf16 v[76:79], v[140:143], v[214:217], 0
	v_mfma_f32_16x16x32_bf16 v[128:131], v[136:139], v[182:185], v[128:131]
	v_mfma_f32_16x16x32_bf16 v[124:127], v[144:147], v[182:185], v[124:127]
	v_mfma_f32_16x16x32_bf16 v[112:115], v[136:139], v[202:205], v[112:115]
	v_mfma_f32_16x16x32_bf16 v[108:111], v[144:147], v[202:205], v[108:111]
	v_mfma_f32_16x16x32_bf16 v[96:99], v[136:139], v[210:213], v[96:99]
	v_mfma_f32_16x16x32_bf16 v[92:95], v[144:147], v[210:213], v[92:95]
	v_mfma_f32_16x16x32_bf16 v[80:83], v[136:139], v[218:221], v[80:83]
	v_mfma_f32_16x16x32_bf16 v[76:79], v[144:147], v[218:221], v[76:79]
	s_setprio 0
	s_setprio 1
	v_mfma_f32_16x16x32_bf16 v[120:123], v[148:151], v[178:181], 0
	v_mfma_f32_16x16x32_bf16 v[116:119], v[156:159], v[178:181], 0
	v_mfma_f32_16x16x32_bf16 v[104:107], v[148:151], v[186:189], 0
	v_mfma_f32_16x16x32_bf16 v[100:103], v[156:159], v[186:189], 0
	v_mfma_f32_16x16x32_bf16 v[88:91], v[148:151], v[206:209], 0
	v_mfma_f32_16x16x32_bf16 v[84:87], v[156:159], v[206:209], 0
	v_mfma_f32_16x16x32_bf16 v[72:75], v[148:151], v[214:217], 0
	v_mfma_f32_16x16x32_bf16 v[68:71], v[156:159], v[214:217], 0
	v_mfma_f32_16x16x32_bf16 v[120:123], v[152:155], v[182:185], v[120:123]
	v_mfma_f32_16x16x32_bf16 v[116:119], v[174:177], v[182:185], v[116:119]
	v_mfma_f32_16x16x32_bf16 v[104:107], v[152:155], v[202:205], v[104:107]
	v_mfma_f32_16x16x32_bf16 v[100:103], v[174:177], v[202:205], v[100:103]
	v_mfma_f32_16x16x32_bf16 v[88:91], v[152:155], v[210:213], v[88:91]
	v_mfma_f32_16x16x32_bf16 v[84:87], v[174:177], v[210:213], v[84:87]
	v_mfma_f32_16x16x32_bf16 v[72:75], v[152:155], v[218:221], v[72:75]
	v_mfma_f32_16x16x32_bf16 v[68:71], v[174:177], v[218:221], v[68:71]
	s_setprio 0
	s_barrier
	s_add_i32 s20, s64, s38
	v_lshl_add_u64 v[190:191], s[24:25], 0, v[164:165]
	s_mov_b32 m0, s20
	ds_read_b128 v[178:181], v193 offset:16384
	ds_read_b128 v[182:185], v193 offset:17408
	ds_read_b128 v[186:189], v193 offset:18432
	ds_read_b128 v[202:205], v193 offset:19456
	ds_read_b128 v[206:209], v193 offset:20480
	ds_read_b128 v[210:213], v193 offset:21504
	ds_read_b128 v[214:217], v193 offset:22528
	ds_read_b128 v[218:221], v193 offset:23552
	global_load_lds_dwordx4 v[190:191], off
	s_add_i32 m0, s20, 0x2000
	s_add_u32 s20, s24, 0x104000
	v_lshl_add_u64 v[194:195], s[24:25], 0, v[168:169]
	s_addc_u32 s21, s25, 0
	s_add_i32 s64, s65, s38
	global_load_lds_dwordx4 v[194:195], off
	v_lshl_add_u64 v[222:223], s[20:21], 0, v[164:165]
	s_mov_b32 m0, s64
	v_lshl_add_u64 v[224:225], s[26:27], 0, v[166:167]
	global_load_lds_dwordx4 v[222:223], off
	v_lshl_add_u64 v[222:223], s[20:21], 0, v[168:169]
	s_add_i32 m0, s64, 0x2000
	s_nop 0
	global_load_lds_dwordx4 v[222:223], off
	v_lshl_add_u64 v[222:223], s[26:27], 0, v[162:163]
	s_mov_b32 m0, s39
	s_nop 0
	global_load_lds_dwordx4 v[222:223], off
	s_mov_b32 m0, s40
	s_nop 0
	global_load_lds_dwordx4 v[224:225], off
	s_waitcnt vmcnt(8)
	s_waitcnt lgkmcnt(0)
	s_barrier
; #define PG8_STAGE(bufoff, gbase, voff) do { _Pragma("unroll") for (int _i = 0; _i < 2; ++_i) \
;         __builtin_amdgcn_global_load_lds((const unsigned*)((const char*)(gbase) + (voff)[_i]), (LAS unsigned*)(lds + (bufoff) + ldsw + _i * 8192), 16, 0, 0); } while (0)
; #define PG8_LDA(dst, b, h) do { _Pragma("unroll") for (int m = 0; m < 4; ++m) _Pragma("unroll") for (int k = 0; k < 2; ++k) dst[m][k] = *(const LAS bf16x8*)(lds + PG8_SA(b, h) + aoff + m * 2048 + k * 1024); } while (0)
; #define PG8_LDB(dst, b, h) do { _Pragma("unroll") for (int n = 0; n < 2; ++n) _Pragma("unroll") for (int k = 0; k < 2; ++k) dst[n][k] = *(const LAS bf16x8*)(lds + PG8_SB(b, h) + boff + n * 2048 + k * 1024); } while (0)
; #define PG8_MMA(ai, bj, At, Bt) do { __builtin_amdgcn_s_setprio(1); _Pragma("unroll") for (int m = 0; m < 4; ++m) _Pragma("unroll") for (int n = 0; n < 2; ++n) _Pragma("unroll") for (int k = 0; k < 2; ++k) \
;         acc[ai][bj][m][n] = __builtin_amdgcn_mfma_f32_16x16x32_bf16(Bt[n][k], At[m][k], acc[ai][bj][m][n], 0, 0, 0); __builtin_amdgcn_s_setprio(0); } while (0)
; #define PG8_WAIT_V(n) asm volatile("s_waitcnt vmcnt(" #n ")" ::: "memory")
; #define PG8_WAIT_L(n) asm volatile("s_waitcnt lgkmcnt(" #n ")" ::: "memory")
; #define PG8_BAR __builtin_amdgcn_s_barrier()
; #define PG8_SCHED __builtin_amdgcn_sched_barrier(0)
; template <class Epi, bool ALIGN_EPI>
; DI void gemm_phase(LAS unsigned char* lds, const Sched& S, const Epi& E, int tid) {
;     ...
;             PG8_WAIT_V(8); PG8_WAIT_L(0); PG8_BAR; PG8_MMA(1, 0, At, B0); PG8_MMA(1, 1, At, B1); PG8_BAR; PG8_SCHED;
;             PG8_LDB(B0, 1, 0); PG8_LDB(B1, 1, 1); PG8_SCHED; PG8_LDA(At, 1, 0); PG8_STAGE(PG8_SA(0, 1), a2 + hstepA, voffA);
;             PG8_WAIT_V(8); PG8_WAIT_L(0); PG8_BAR; PG8_MMA(0, 0, At, B0); PG8_MMA(0, 1, At, B1); PG8_BAR; PG8_SCHED;
	s_setprio 1
	s_waitcnt lgkmcnt(0)
	v_mfma_f32_16x16x32_bf16 v[64:67], v[132:135], v[178:181], 0
	v_mfma_f32_16x16x32_bf16 v[60:63], v[140:143], v[178:181], 0
	v_mfma_f32_16x16x32_bf16 v[48:51], v[132:135], v[186:189], 0
	v_mfma_f32_16x16x32_bf16 v[44:47], v[140:143], v[186:189], 0
	v_mfma_f32_16x16x32_bf16 v[32:35], v[132:135], v[206:209], 0
	v_mfma_f32_16x16x32_bf16 v[28:31], v[140:143], v[206:209], 0
	v_mfma_f32_16x16x32_bf16 v[16:19], v[132:135], v[214:217], 0
	v_mfma_f32_16x16x32_bf16 v[12:15], v[140:143], v[214:217], 0
	v_mfma_f32_16x16x32_bf16 v[64:67], v[136:139], v[182:185], v[64:67]
	v_mfma_f32_16x16x32_bf16 v[60:63], v[144:147], v[182:185], v[60:63]
	v_mfma_f32_16x16x32_bf16 v[48:51], v[136:139], v[202:205], v[48:51]
	v_mfma_f32_16x16x32_bf16 v[44:47], v[144:147], v[202:205], v[44:47]
	v_mfma_f32_16x16x32_bf16 v[32:35], v[136:139], v[210:213], v[32:35]
	v_mfma_f32_16x16x32_bf16 v[28:31], v[144:147], v[210:213], v[28:31]
	v_mfma_f32_16x16x32_bf16 v[16:19], v[136:139], v[218:221], v[16:19]
	v_mfma_f32_16x16x32_bf16 v[12:15], v[144:147], v[218:221], v[12:15]
	s_setprio 0
	s_setprio 1
	v_mfma_f32_16x16x32_bf16 v[56:59], v[148:151], v[178:181], 0
	v_mfma_f32_16x16x32_bf16 v[52:55], v[156:159], v[178:181], 0
	v_mfma_f32_16x16x32_bf16 v[40:43], v[148:151], v[186:189], 0
	v_mfma_f32_16x16x32_bf16 v[36:39], v[156:159], v[186:189], 0
	v_mfma_f32_16x16x32_bf16 v[24:27], v[148:151], v[206:209], 0
	v_mfma_f32_16x16x32_bf16 v[20:23], v[156:159], v[206:209], 0
	v_mfma_f32_16x16x32_bf16 v[8:11], v[148:151], v[214:217], 0
	v_mfma_f32_16x16x32_bf16 v[4:7], v[156:159], v[214:217], 0
	v_mfma_f32_16x16x32_bf16 v[56:59], v[152:155], v[182:185], v[56:59]
	v_mfma_f32_16x16x32_bf16 v[52:55], v[174:177], v[182:185], v[52:55]
	v_mfma_f32_16x16x32_bf16 v[40:43], v[152:155], v[202:205], v[40:43]
	v_mfma_f32_16x16x32_bf16 v[36:39], v[174:177], v[202:205], v[36:39]
	v_mfma_f32_16x16x32_bf16 v[24:27], v[152:155], v[210:213], v[24:27]
	v_mfma_f32_16x16x32_bf16 v[20:23], v[174:177], v[210:213], v[20:23]
	v_mfma_f32_16x16x32_bf16 v[8:11], v[152:155], v[218:221], v[8:11]
	v_mfma_f32_16x16x32_bf16 v[4:7], v[174:177], v[218:221], v[4:7]
	s_setprio 0
	s_barrier
	s_add_i32 s64, 0, 0x18000
	s_add_i32 s65, 0, 0x1c000
	v_add_u32_e32 v144, s64, v161
	v_add_u32_e32 v174, s65, v161
	ds_read_b128 v[132:135], v144
	ds_read_b128 v[136:139], v144 offset:1024
	ds_read_b128 v[140:143], v144 offset:2048
	ds_read_b128 v[144:147], v144 offset:3072
	ds_read_b128 v[148:151], v174
	ds_read_b128 v[152:155], v174 offset:1024
	ds_read_b128 v[156:159], v174 offset:2048
	ds_read_b128 v[174:177], v174 offset:3072
	s_add_u32 s20, s26, 0x104000
	s_addc_u32 s21, s27, 0
	s_mov_b32 m0, s41
	v_lshl_add_u64 v[226:227], s[20:21], 0, v[162:163]
	ds_read_b128 v[178:181], v193 offset:32768
	ds_read_b128 v[182:185], v193 offset:33792
	ds_read_b128 v[186:189], v193 offset:34816
	ds_read_b128 v[202:205], v193 offset:35840
	ds_read_b128 v[206:209], v193 offset:36864
	ds_read_b128 v[210:213], v193 offset:37888
	ds_read_b128 v[214:217], v193 offset:38912
	ds_read_b128 v[218:221], v193 offset:39936
	global_load_lds_dwordx4 v[226:227], off
	v_lshl_add_u64 v[226:227], s[20:21], 0, v[166:167]
	s_mov_b32 m0, s42
	s_nop 0
	global_load_lds_dwordx4 v[226:227], off
	s_waitcnt vmcnt(8)
	s_waitcnt lgkmcnt(0)
	s_barrier
	s_setprio 1
	s_waitcnt lgkmcnt(0)
	v_mfma_f32_16x16x32_bf16 v[128:131], v[132:135], v[178:181], v[128:131]
	v_mfma_f32_16x16x32_bf16 v[124:127], v[140:143], v[178:181], v[124:127]
	v_mfma_f32_16x16x32_bf16 v[112:115], v[132:135], v[186:189], v[112:115]
	v_mfma_f32_16x16x32_bf16 v[108:111], v[140:143], v[186:189], v[108:111]
	v_mfma_f32_16x16x32_bf16 v[96:99], v[132:135], v[206:209], v[96:99]
	v_mfma_f32_16x16x32_bf16 v[92:95], v[140:143], v[206:209], v[92:95]
	v_mfma_f32_16x16x32_bf16 v[80:83], v[132:135], v[214:217], v[80:83]
	v_mfma_f32_16x16x32_bf16 v[76:79], v[140:143], v[214:217], v[76:79]
	v_mfma_f32_16x16x32_bf16 v[128:131], v[136:139], v[182:185], v[128:131]
	v_mfma_f32_16x16x32_bf16 v[124:127], v[144:147], v[182:185], v[124:127]
	v_mfma_f32_16x16x32_bf16 v[112:115], v[136:139], v[202:205], v[112:115]
	v_mfma_f32_16x16x32_bf16 v[108:111], v[144:147], v[202:205], v[108:111]
	v_mfma_f32_16x16x32_bf16 v[96:99], v[136:139], v[210:213], v[96:99]
	v_mfma_f32_16x16x32_bf16 v[92:95], v[144:147], v[210:213], v[92:95]
	v_mfma_f32_16x16x32_bf16 v[80:83], v[136:139], v[218:221], v[80:83]
	v_mfma_f32_16x16x32_bf16 v[76:79], v[144:147], v[218:221], v[76:79]
	s_setprio 0
	s_setprio 1
	v_mfma_f32_16x16x32_bf16 v[120:123], v[148:151], v[178:181], v[120:123]
	v_mfma_f32_16x16x32_bf16 v[116:119], v[156:159], v[178:181], v[116:119]
	v_mfma_f32_16x16x32_bf16 v[104:107], v[148:151], v[186:189], v[104:107]
	v_mfma_f32_16x16x32_bf16 v[100:103], v[156:159], v[186:189], v[100:103]
	v_mfma_f32_16x16x32_bf16 v[88:91], v[148:151], v[206:209], v[88:91]
	v_mfma_f32_16x16x32_bf16 v[84:87], v[156:159], v[206:209], v[84:87]
	v_mfma_f32_16x16x32_bf16 v[72:75], v[148:151], v[214:217], v[72:75]
	v_mfma_f32_16x16x32_bf16 v[68:71], v[156:159], v[214:217], v[68:71]
	v_mfma_f32_16x16x32_bf16 v[120:123], v[152:155], v[182:185], v[120:123]
	v_mfma_f32_16x16x32_bf16 v[116:119], v[174:177], v[182:185], v[116:119]
	v_mfma_f32_16x16x32_bf16 v[104:107], v[152:155], v[202:205], v[104:107]
	v_mfma_f32_16x16x32_bf16 v[100:103], v[174:177], v[202:205], v[100:103]
	v_mfma_f32_16x16x32_bf16 v[88:91], v[152:155], v[210:213], v[88:91]
	v_mfma_f32_16x16x32_bf16 v[84:87], v[174:177], v[210:213], v[84:87]
	v_mfma_f32_16x16x32_bf16 v[72:75], v[152:155], v[218:221], v[72:75]
	v_mfma_f32_16x16x32_bf16 v[68:71], v[174:177], v[218:221], v[68:71]
	s_setprio 0
	s_barrier
; #define PG8_STAGE(bufoff, gbase, voff) do { _Pragma("unroll") for (int _i = 0; _i < 2; ++_i) \
;         __builtin_amdgcn_global_load_lds((const unsigned*)((const char*)(gbase) + (voff)[_i]), (LAS unsigned*)(lds + (bufoff) + ldsw + _i * 8192), 16, 0, 0); } while (0)
; #define PG8_LDA(dst, b, h) do { _Pragma("unroll") for (int m = 0; m < 4; ++m) _Pragma("unroll") for (int k = 0; k < 2; ++k) dst[m][k] = *(const LAS bf16x8*)(lds + PG8_SA(b, h) + aoff + m * 2048 + k * 1024); } while (0)
; #define PG8_MMA(ai, bj, At, Bt) do { __builtin_amdgcn_s_setprio(1); _Pragma("unroll") for (int m = 0; m < 4; ++m) _Pragma("unroll") for (int n = 0; n < 2; ++n) _Pragma("unroll") for (int k = 0; k < 2; ++k) \
;         acc[ai][bj][m][n] = __builtin_amdgcn_mfma_f32_16x16x32_bf16(Bt[n][k], At[m][k], acc[ai][bj][m][n], 0, 0, 0); __builtin_amdgcn_s_setprio(0); } while (0)
; #define PG8_WAIT_V(n) asm volatile("s_waitcnt vmcnt(" #n ")" ::: "memory")
; #define PG8_WAIT_L(n) asm volatile("s_waitcnt lgkmcnt(" #n ")" ::: "memory")
; #define PG8_BAR __builtin_amdgcn_s_barrier()
; #define PG8_SCHED __builtin_amdgcn_sched_barrier(0)
; template <class Epi, bool ALIGN_EPI>
; DI void gemm_phase(LAS unsigned char* lds, const Sched& S, const Epi& E, int tid) {
;     ...
;             PG8_LDA(At, 1, 1); PG8_STAGE(PG8_SB(1, 0), b3, voffB); PG8_STAGE(PG8_SB(1, 1), b3 + hstepB, voffB); PG8_STAGE(PG8_SA(1, 0), a3, voffA);
;             PG8_WAIT_V(8); PG8_WAIT_L(0); PG8_BAR; PG8_MMA(1, 0, At, B0); PG8_MMA(1, 1, At, B1); PG8_BAR; PG8_SCHED;
;         }
	s_add_i32 s20, s64, s38
	v_lshl_add_u64 v[190:191], v[190:191], 0, s[84:85]
	s_mov_b32 m0, s20
	ds_read_b128 v[178:181], v193 offset:49152
	ds_read_b128 v[182:185], v193 offset:50176
	ds_read_b128 v[186:189], v193 offset:51200
	ds_read_b128 v[202:205], v193 offset:52224
	ds_read_b128 v[206:209], v193 offset:53248
	ds_read_b128 v[210:213], v193 offset:54272
	ds_read_b128 v[214:217], v193 offset:55296
	ds_read_b128 v[218:221], v193 offset:56320
	global_load_lds_dwordx4 v[190:191], off
	s_add_i32 m0, s20, 0x2000
	s_add_u32 s20, s24, 0x104080
	v_lshl_add_u64 v[190:191], v[194:195], 0, s[84:85]
	s_addc_u32 s21, s25, 0
	s_add_i32 s24, s65, s38
	global_load_lds_dwordx4 v[190:191], off
	v_lshl_add_u64 v[190:191], s[20:21], 0, v[164:165]
	s_mov_b32 m0, s24
	s_nop 0
	global_load_lds_dwordx4 v[190:191], off
	v_lshl_add_u64 v[190:191], s[20:21], 0, v[168:169]
	s_add_i32 m0, s24, 0x2000
	s_nop 0
	global_load_lds_dwordx4 v[190:191], off
	v_lshl_add_u64 v[190:191], v[222:223], 0, s[84:85]
	s_mov_b32 m0, s44
	s_nop 0
	global_load_lds_dwordx4 v[190:191], off
	v_lshl_add_u64 v[190:191], v[224:225], 0, s[84:85]
	s_mov_b32 m0, s45
	s_nop 0
	global_load_lds_dwordx4 v[190:191], off
	s_waitcnt vmcnt(8)
	s_waitcnt lgkmcnt(0)
	s_barrier
	s_setprio 1
	s_waitcnt lgkmcnt(0)
	v_mfma_f32_16x16x32_bf16 v[64:67], v[132:135], v[178:181], v[64:67]
	v_mfma_f32_16x16x32_bf16 v[60:63], v[140:143], v[178:181], v[60:63]
	v_mfma_f32_16x16x32_bf16 v[48:51], v[132:135], v[186:189], v[48:51]
	v_mfma_f32_16x16x32_bf16 v[44:47], v[140:143], v[186:189], v[44:47]
	v_mfma_f32_16x16x32_bf16 v[32:35], v[132:135], v[206:209], v[32:35]
	v_mfma_f32_16x16x32_bf16 v[28:31], v[140:143], v[206:209], v[28:31]
	v_mfma_f32_16x16x32_bf16 v[16:19], v[132:135], v[214:217], v[16:19]
	v_mfma_f32_16x16x32_bf16 v[12:15], v[140:143], v[214:217], v[12:15]
	v_mfma_f32_16x16x32_bf16 v[64:67], v[136:139], v[182:185], v[64:67]
	v_mfma_f32_16x16x32_bf16 v[60:63], v[144:147], v[182:185], v[60:63]
	v_mfma_f32_16x16x32_bf16 v[48:51], v[136:139], v[202:205], v[48:51]
	v_mfma_f32_16x16x32_bf16 v[44:47], v[144:147], v[202:205], v[44:47]
	v_mfma_f32_16x16x32_bf16 v[32:35], v[136:139], v[210:213], v[32:35]
	v_mfma_f32_16x16x32_bf16 v[28:31], v[144:147], v[210:213], v[28:31]
	v_mfma_f32_16x16x32_bf16 v[16:19], v[136:139], v[218:221], v[16:19]
	v_mfma_f32_16x16x32_bf16 v[12:15], v[144:147], v[218:221], v[12:15]
	s_setprio 0
	s_setprio 1
	v_mfma_f32_16x16x32_bf16 v[56:59], v[148:151], v[178:181], v[56:59]
	v_mfma_f32_16x16x32_bf16 v[52:55], v[156:159], v[178:181], v[52:55]
	v_mfma_f32_16x16x32_bf16 v[40:43], v[148:151], v[186:189], v[40:43]
	v_mfma_f32_16x16x32_bf16 v[36:39], v[156:159], v[186:189], v[36:39]
	v_mfma_f32_16x16x32_bf16 v[24:27], v[148:151], v[206:209], v[24:27]
	v_mfma_f32_16x16x32_bf16 v[20:23], v[156:159], v[206:209], v[20:23]
	v_mfma_f32_16x16x32_bf16 v[8:11], v[148:151], v[214:217], v[8:11]
	v_mfma_f32_16x16x32_bf16 v[4:7], v[156:159], v[214:217], v[4:7]
	v_mfma_f32_16x16x32_bf16 v[56:59], v[152:155], v[182:185], v[56:59]
	v_mfma_f32_16x16x32_bf16 v[52:55], v[174:177], v[182:185], v[52:55]
	v_mfma_f32_16x16x32_bf16 v[40:43], v[152:155], v[202:205], v[40:43]
	v_mfma_f32_16x16x32_bf16 v[36:39], v[174:177], v[202:205], v[36:39]
	v_mfma_f32_16x16x32_bf16 v[24:27], v[152:155], v[210:213], v[24:27]
	v_mfma_f32_16x16x32_bf16 v[20:23], v[174:177], v[210:213], v[20:23]
	v_mfma_f32_16x16x32_bf16 v[8:11], v[152:155], v[218:221], v[8:11]
	v_mfma_f32_16x16x32_bf16 v[4:7], v[174:177], v[218:221], v[4:7]
	s_setprio 0
	s_barrier
	s_add_u32 s61, s61, 0x100
	s_addc_u32 s62, s62, 0
	s_cmp_ge_i32 s63, s55
	s_mov_b64 s[20:21], s[22:23]
	s_mov_b32 s24, s63

; #define PG8_STAGE(bufoff, gbase, voff) do { _Pragma("unroll") for (int _i = 0; _i < 2; ++_i) \
;         __builtin_amdgcn_global_load_lds((const unsigned*)((const char*)(gbase) + (voff)[_i]), (LAS unsigned*)(lds + (bufoff) + ldsw + _i * 8192), 16, 0, 0); } while (0)
; #define PG8_LDA(dst, b, h) do { _Pragma("unroll") for (int m = 0; m < 4; ++m) _Pragma("unroll") for (int k = 0; k < 2; ++k) dst[m][k] = *(const LAS bf16x8*)(lds + PG8_SA(b, h) + aoff + m * 2048 + k * 1024); } while (0)
; #define PG8_LDB(dst, b, h) do { _Pragma("unroll") for (int n = 0; n < 2; ++n) _Pragma("unroll") for (int k = 0; k < 2; ++k) dst[n][k] = *(const LAS bf16x8*)(lds + PG8_SB(b, h) + boff + n * 2048 + k * 1024); } while (0)
; #define PG8_MMA(ai, bj, At, Bt) do { __builtin_amdgcn_s_setprio(1); _Pragma("unroll") for (int m = 0; m < 4; ++m) _Pragma("unroll") for (int n = 0; n < 2; ++n) _Pragma("unroll") for (int k = 0; k < 2; ++k) \
;         acc[ai][bj][m][n] = __builtin_amdgcn_mfma_f32_16x16x32_bf16(Bt[n][k], At[m][k], acc[ai][bj][m][n], 0, 0, 0); __builtin_amdgcn_s_setprio(0); } while (0)
; #define PG8_WAIT_V(n) asm volatile("s_waitcnt vmcnt(" #n ")" ::: "memory")
; #define PG8_WAIT_L(n) asm volatile("s_waitcnt lgkmcnt(" #n ")" ::: "memory")
; #define PG8_BAR __builtin_amdgcn_s_barrier()
; #define PG8_SCHED __builtin_amdgcn_sched_barrier(0)
; template <class Epi, bool ALIGN_EPI>
; DI void gemm_phase(LAS unsigned char* lds, const Sched& S, const Epi& E, int tid) {
;     ...
;         for (int t = 0; t < nt; t += 2) {
;             const bool last = (t == nt - 2);
;             const char* a1 = cA + (size_t)(t + 1) * kstep;
;             const char* a2 = last ? nA : cA + (size_t)(t + 2) * kstep; const char* b2 = last ? nB : cB + (size_t)(t + 2) * kstep;
;             const char* a3 = a2 + kstep; const char* b3 = b2 + kstep;
;             PG8_LDB(B0, 0, 0); PG8_LDB(B1, 0, 1); PG8_SCHED; PG8_LDA(At, 0, 0); PG8_STAGE(PG8_SA(1, 1), a1 + hstepA, voffA);
;             PG8_WAIT_V(8); PG8_WAIT_L(0); PG8_BAR; PG8_MMA(0, 0, At, B0); PG8_MMA(0, 1, At, B1); PG8_BAR; PG8_SCHED;
;             PG8_LDA(At, 0, 1); PG8_STAGE(PG8_SB(0, 0), b2, voffB); PG8_STAGE(PG8_SB(0, 1), b2 + hstepB, voffB); PG8_STAGE(PG8_SA(0, 0), a2, voffA);
;             PG8_WAIT_V(8); PG8_WAIT_L(0); PG8_BAR; PG8_MMA(1, 0, At, B0); PG8_MMA(1, 1, At, B1); PG8_BAR; PG8_SCHED;
.LBB0_652:
	s_add_u32 s22, s22, 0x40080
	s_addc_u32 s23, s23, 0
	s_add_u32 s37, s24, 0x100
	s_addc_u32 s38, s25, 0
	s_mov_b32 s39, -2
	s_add_u32 s24, s22, 0xfffc0080
	s_addc_u32 s25, s23, -1
	s_add_i32 s40, 0, 0x10000
	s_cmp_eq_u32 s39, 12
	s_cselect_b32 s29, s3, s25
	s_cselect_b32 s28, s2, s24
	v_add_u32_e32 v154, s40, v141
	s_cselect_b32 s25, s21, s38
	s_cselect_b32 s24, s20, s37
	s_add_i32 s58, 0, 0x14000
	ds_read_b128 v[146:149], v154
	ds_read_b128 v[150:153], v154 offset:1024
	ds_read_b128 v[162:165], v154 offset:2048
	ds_read_b128 v[166:169], v154 offset:3072
	v_add_u32_e32 v154, s58, v141
	ds_read_b128 v[170:173], v154
	ds_read_b128 v[174:177], v154 offset:1024
	ds_read_b128 v[178:181], v154 offset:2048
	ds_read_b128 v[182:185], v154 offset:3072
	v_lshl_add_u64 v[154:155], s[22:23], 0, v[142:143]
	s_add_i32 m0, s50, 0xc000
	ds_read_b128 v[186:189], v157
	ds_read_b128 v[190:193], v157 offset:1024
	ds_read_b128 v[202:205], v157 offset:2048
	ds_read_b128 v[206:209], v157 offset:3072
	ds_read_b128 v[210:213], v157 offset:4096
	ds_read_b128 v[214:217], v157 offset:5120
	ds_read_b128 v[218:221], v157 offset:6144
	ds_read_b128 v[222:225], v157 offset:7168
	global_load_lds_dwordx4 v[154:155], off
	v_lshl_add_u64 v[154:155], s[22:23], 0, v[144:145]
	s_add_i32 m0, s50, 0xe000
	s_nop 0
	global_load_lds_dwordx4 v[154:155], off
	s_waitcnt vmcnt(8)
	s_waitcnt lgkmcnt(0)
	s_barrier
	s_setprio 1
	s_waitcnt lgkmcnt(0)
	v_mfma_f32_16x16x32_bf16 v[128:131], v[146:149], v[186:189], 0
	v_mfma_f32_16x16x32_bf16 v[124:127], v[162:165], v[186:189], 0
	v_mfma_f32_16x16x32_bf16 v[112:115], v[146:149], v[202:205], 0
	v_mfma_f32_16x16x32_bf16 v[108:111], v[162:165], v[202:205], 0
	v_mfma_f32_16x16x32_bf16 v[96:99], v[146:149], v[210:213], 0
	v_mfma_f32_16x16x32_bf16 v[92:95], v[162:165], v[210:213], 0
	v_mfma_f32_16x16x32_bf16 v[80:83], v[146:149], v[218:221], 0
	v_mfma_f32_16x16x32_bf16 v[76:79], v[162:165], v[218:221], 0
	v_mfma_f32_16x16x32_bf16 v[128:131], v[150:153], v[190:193], v[128:131]
	v_mfma_f32_16x16x32_bf16 v[124:127], v[166:169], v[190:193], v[124:127]
	v_mfma_f32_16x16x32_bf16 v[112:115], v[150:153], v[206:209], v[112:115]
	v_mfma_f32_16x16x32_bf16 v[108:111], v[166:169], v[206:209], v[108:111]
	v_mfma_f32_16x16x32_bf16 v[96:99], v[150:153], v[214:217], v[96:99]
	v_mfma_f32_16x16x32_bf16 v[92:95], v[166:169], v[214:217], v[92:95]
	v_mfma_f32_16x16x32_bf16 v[80:83], v[150:153], v[222:225], v[80:83]
	v_mfma_f32_16x16x32_bf16 v[76:79], v[166:169], v[222:225], v[76:79]
	s_setprio 0
	s_setprio 1
	v_mfma_f32_16x16x32_bf16 v[120:123], v[170:173], v[186:189], 0
	v_mfma_f32_16x16x32_bf16 v[116:119], v[178:181], v[186:189], 0
	v_mfma_f32_16x16x32_bf16 v[104:107], v[170:173], v[202:205], 0
	v_mfma_f32_16x16x32_bf16 v[100:103], v[178:181], v[202:205], 0
	v_mfma_f32_16x16x32_bf16 v[88:91], v[170:173], v[210:213], 0
	v_mfma_f32_16x16x32_bf16 v[84:87], v[178:181], v[210:213], 0
	v_mfma_f32_16x16x32_bf16 v[72:75], v[170:173], v[218:221], 0
	v_mfma_f32_16x16x32_bf16 v[68:71], v[178:181], v[218:221], 0
	v_mfma_f32_16x16x32_bf16 v[120:123], v[174:177], v[190:193], v[120:123]
	v_mfma_f32_16x16x32_bf16 v[116:119], v[182:185], v[190:193], v[116:119]
	v_mfma_f32_16x16x32_bf16 v[104:107], v[174:177], v[206:209], v[104:107]
	v_mfma_f32_16x16x32_bf16 v[100:103], v[182:185], v[206:209], v[100:103]
	v_mfma_f32_16x16x32_bf16 v[88:91], v[174:177], v[214:217], v[88:91]
	v_mfma_f32_16x16x32_bf16 v[84:87], v[182:185], v[214:217], v[84:87]
	v_mfma_f32_16x16x32_bf16 v[72:75], v[174:177], v[222:225], v[72:75]
	v_mfma_f32_16x16x32_bf16 v[68:71], v[182:185], v[222:225], v[68:71]
	s_setprio 0
	s_barrier
	s_add_i32 s40, s40, s49
	v_lshl_add_u64 v[154:155], s[24:25], 0, v[134:135]
	s_mov_b32 m0, s40
	ds_read_b128 v[186:189], v157 offset:16384
	ds_read_b128 v[190:193], v157 offset:17408
	ds_read_b128 v[202:205], v157 offset:18432
	ds_read_b128 v[206:209], v157 offset:19456
	ds_read_b128 v[210:213], v157 offset:20480
	ds_read_b128 v[214:217], v157 offset:21504
	ds_read_b128 v[218:221], v157 offset:22528
	ds_read_b128 v[222:225], v157 offset:23552
	global_load_lds_dwordx4 v[154:155], off
	s_add_i32 m0, s40, 0x2000
	s_add_u32 s40, s24, 0x40000
	v_lshl_add_u64 v[158:159], s[24:25], 0, v[138:139]
	s_addc_u32 s41, s25, 0
	s_add_i32 s58, s58, s49
	global_load_lds_dwordx4 v[158:159], off
	v_lshl_add_u64 v[194:195], s[40:41], 0, v[134:135]
	s_mov_b32 m0, s58
	v_lshl_add_u64 v[226:227], s[28:29], 0, v[136:137]
	global_load_lds_dwordx4 v[194:195], off
	v_lshl_add_u64 v[194:195], s[40:41], 0, v[138:139]
	s_add_i32 m0, s58, 0x2000
	s_nop 0
	global_load_lds_dwordx4 v[194:195], off
	v_lshl_add_u64 v[194:195], s[28:29], 0, v[132:133]
	s_mov_b32 m0, s50
	s_nop 0
	global_load_lds_dwordx4 v[194:195], off
	s_mov_b32 m0, s51
	s_nop 0
	global_load_lds_dwordx4 v[226:227], off
	s_waitcnt vmcnt(8)
	s_waitcnt lgkmcnt(0)
	s_barrier
; #define PG8_STAGE(bufoff, gbase, voff) do { _Pragma("unroll") for (int _i = 0; _i < 2; ++_i) \
;         __builtin_amdgcn_global_load_lds((const unsigned*)((const char*)(gbase) + (voff)[_i]), (LAS unsigned*)(lds + (bufoff) + ldsw + _i * 8192), 16, 0, 0); } while (0)
; #define PG8_LDA(dst, b, h) do { _Pragma("unroll") for (int m = 0; m < 4; ++m) _Pragma("unroll") for (int k = 0; k < 2; ++k) dst[m][k] = *(const LAS bf16x8*)(lds + PG8_SA(b, h) + aoff + m * 2048 + k * 1024); } while (0)
; #define PG8_LDB(dst, b, h) do { _Pragma("unroll") for (int n = 0; n < 2; ++n) _Pragma("unroll") for (int k = 0; k < 2; ++k) dst[n][k] = *(const LAS bf16x8*)(lds + PG8_SB(b, h) + boff + n * 2048 + k * 1024); } while (0)
; #define PG8_MMA(ai, bj, At, Bt) do { __builtin_amdgcn_s_setprio(1); _Pragma("unroll") for (int m = 0; m < 4; ++m) _Pragma("unroll") for (int n = 0; n < 2; ++n) _Pragma("unroll") for (int k = 0; k < 2; ++k) \
;         acc[ai][bj][m][n] = __builtin_amdgcn_mfma_f32_16x16x32_bf16(Bt[n][k], At[m][k], acc[ai][bj][m][n], 0, 0, 0); __builtin_amdgcn_s_setprio(0); } while (0)
; #define PG8_WAIT_V(n) asm volatile("s_waitcnt vmcnt(" #n ")" ::: "memory")
; #define PG8_WAIT_L(n) asm volatile("s_waitcnt lgkmcnt(" #n ")" ::: "memory")
; #define PG8_BAR __builtin_amdgcn_s_barrier()
; #define PG8_SCHED __builtin_amdgcn_sched_barrier(0)
; template <class Epi, bool ALIGN_EPI>
; DI void gemm_phase(LAS unsigned char* lds, const Sched& S, const Epi& E, int tid) {
;     ...
;             PG8_WAIT_V(8); PG8_WAIT_L(0); PG8_BAR; PG8_MMA(1, 0, At, B0); PG8_MMA(1, 1, At, B1); PG8_BAR; PG8_SCHED;
;             PG8_LDB(B0, 1, 0); PG8_LDB(B1, 1, 1); PG8_SCHED; PG8_LDA(At, 1, 0); PG8_STAGE(PG8_SA(0, 1), a2 + hstepA, voffA);
;             PG8_WAIT_V(8); PG8_WAIT_L(0); PG8_BAR; PG8_MMA(0, 0, At, B0); PG8_MMA(0, 1, At, B1); PG8_BAR; PG8_SCHED;
	s_setprio 1
	s_waitcnt lgkmcnt(0)
	v_mfma_f32_16x16x32_bf16 v[64:67], v[146:149], v[186:189], 0
	v_mfma_f32_16x16x32_bf16 v[60:63], v[162:165], v[186:189], 0
	v_mfma_f32_16x16x32_bf16 v[48:51], v[146:149], v[202:205], 0
	v_mfma_f32_16x16x32_bf16 v[44:47], v[162:165], v[202:205], 0
	v_mfma_f32_16x16x32_bf16 v[32:35], v[146:149], v[210:213], 0
	v_mfma_f32_16x16x32_bf16 v[28:31], v[162:165], v[210:213], 0
	v_mfma_f32_16x16x32_bf16 v[16:19], v[146:149], v[218:221], 0
	v_mfma_f32_16x16x32_bf16 v[12:15], v[162:165], v[218:221], 0
	v_mfma_f32_16x16x32_bf16 v[64:67], v[150:153], v[190:193], v[64:67]
	v_mfma_f32_16x16x32_bf16 v[60:63], v[166:169], v[190:193], v[60:63]
	v_mfma_f32_16x16x32_bf16 v[48:51], v[150:153], v[206:209], v[48:51]
	v_mfma_f32_16x16x32_bf16 v[44:47], v[166:169], v[206:209], v[44:47]
	v_mfma_f32_16x16x32_bf16 v[32:35], v[150:153], v[214:217], v[32:35]
	v_mfma_f32_16x16x32_bf16 v[28:31], v[166:169], v[214:217], v[28:31]
	v_mfma_f32_16x16x32_bf16 v[16:19], v[150:153], v[222:225], v[16:19]
	v_mfma_f32_16x16x32_bf16 v[12:15], v[166:169], v[222:225], v[12:15]
	s_setprio 0
	s_setprio 1
	v_mfma_f32_16x16x32_bf16 v[56:59], v[170:173], v[186:189], 0
	v_mfma_f32_16x16x32_bf16 v[52:55], v[178:181], v[186:189], 0
	v_mfma_f32_16x16x32_bf16 v[40:43], v[170:173], v[202:205], 0
	v_mfma_f32_16x16x32_bf16 v[36:39], v[178:181], v[202:205], 0
	v_mfma_f32_16x16x32_bf16 v[24:27], v[170:173], v[210:213], 0
	v_mfma_f32_16x16x32_bf16 v[20:23], v[178:181], v[210:213], 0
	v_mfma_f32_16x16x32_bf16 v[8:11], v[170:173], v[218:221], 0
	v_mfma_f32_16x16x32_bf16 v[4:7], v[178:181], v[218:221], 0
	v_mfma_f32_16x16x32_bf16 v[56:59], v[174:177], v[190:193], v[56:59]
	v_mfma_f32_16x16x32_bf16 v[52:55], v[182:185], v[190:193], v[52:55]
	v_mfma_f32_16x16x32_bf16 v[40:43], v[174:177], v[206:209], v[40:43]
	v_mfma_f32_16x16x32_bf16 v[36:39], v[182:185], v[206:209], v[36:39]
	v_mfma_f32_16x16x32_bf16 v[24:27], v[174:177], v[214:217], v[24:27]
	v_mfma_f32_16x16x32_bf16 v[20:23], v[182:185], v[214:217], v[20:23]
	v_mfma_f32_16x16x32_bf16 v[8:11], v[174:177], v[222:225], v[8:11]
	v_mfma_f32_16x16x32_bf16 v[4:7], v[182:185], v[222:225], v[4:7]
	s_setprio 0
	s_barrier
	s_add_i32 s40, 0, 0x18000
	v_add_u32_e32 v161, s40, v141
	s_add_i32 s41, 0, 0x1c000
	ds_read_b128 v[146:149], v161
	ds_read_b128 v[150:153], v161 offset:1024
	ds_read_b128 v[162:165], v161 offset:2048
	ds_read_b128 v[166:169], v161 offset:3072
	v_add_u32_e32 v161, s41, v141
	ds_read_b128 v[170:173], v161
	ds_read_b128 v[174:177], v161 offset:1024
	ds_read_b128 v[178:181], v161 offset:2048
	ds_read_b128 v[182:185], v161 offset:3072
	s_add_u32 s28, s28, 0x40000
	s_addc_u32 s29, s29, 0
	s_mov_b32 m0, s52
	v_lshl_add_u64 v[228:229], s[28:29], 0, v[132:133]
	ds_read_b128 v[186:189], v157 offset:32768
	ds_read_b128 v[190:193], v157 offset:33792
	ds_read_b128 v[202:205], v157 offset:34816
	ds_read_b128 v[206:209], v157 offset:35840
	ds_read_b128 v[210:213], v157 offset:36864
	ds_read_b128 v[214:217], v157 offset:37888
	ds_read_b128 v[218:221], v157 offset:38912
	ds_read_b128 v[222:225], v157 offset:39936
	global_load_lds_dwordx4 v[228:229], off
	v_lshl_add_u64 v[228:229], s[28:29], 0, v[136:137]
	s_mov_b32 m0, s53
	s_nop 0
	global_load_lds_dwordx4 v[228:229], off
	s_waitcnt vmcnt(8)
	s_waitcnt lgkmcnt(0)
	s_barrier
	s_setprio 1
	s_waitcnt lgkmcnt(0)
	v_mfma_f32_16x16x32_bf16 v[128:131], v[146:149], v[186:189], v[128:131]
	v_mfma_f32_16x16x32_bf16 v[124:127], v[162:165], v[186:189], v[124:127]
	v_mfma_f32_16x16x32_bf16 v[112:115], v[146:149], v[202:205], v[112:115]
	v_mfma_f32_16x16x32_bf16 v[108:111], v[162:165], v[202:205], v[108:111]
	v_mfma_f32_16x16x32_bf16 v[96:99], v[146:149], v[210:213], v[96:99]
	v_mfma_f32_16x16x32_bf16 v[92:95], v[162:165], v[210:213], v[92:95]
	v_mfma_f32_16x16x32_bf16 v[80:83], v[146:149], v[218:221], v[80:83]
	v_mfma_f32_16x16x32_bf16 v[76:79], v[162:165], v[218:221], v[76:79]
	v_mfma_f32_16x16x32_bf16 v[128:131], v[150:153], v[190:193], v[128:131]
	v_mfma_f32_16x16x32_bf16 v[124:127], v[166:169], v[190:193], v[124:127]
	v_mfma_f32_16x16x32_bf16 v[112:115], v[150:153], v[206:209], v[112:115]
	v_mfma_f32_16x16x32_bf16 v[108:111], v[166:169], v[206:209], v[108:111]
	v_mfma_f32_16x16x32_bf16 v[96:99], v[150:153], v[214:217], v[96:99]
	v_mfma_f32_16x16x32_bf16 v[92:95], v[166:169], v[214:217], v[92:95]
	v_mfma_f32_16x16x32_bf16 v[80:83], v[150:153], v[222:225], v[80:83]
	v_mfma_f32_16x16x32_bf16 v[76:79], v[166:169], v[222:225], v[76:79]
	s_setprio 0
	s_setprio 1
	v_mfma_f32_16x16x32_bf16 v[120:123], v[170:173], v[186:189], v[120:123]
	v_mfma_f32_16x16x32_bf16 v[116:119], v[178:181], v[186:189], v[116:119]
	v_mfma_f32_16x16x32_bf16 v[104:107], v[170:173], v[202:205], v[104:107]
	v_mfma_f32_16x16x32_bf16 v[100:103], v[178:181], v[202:205], v[100:103]
	v_mfma_f32_16x16x32_bf16 v[88:91], v[170:173], v[210:213], v[88:91]
	v_mfma_f32_16x16x32_bf16 v[84:87], v[178:181], v[210:213], v[84:87]
	v_mfma_f32_16x16x32_bf16 v[72:75], v[170:173], v[218:221], v[72:75]
	v_mfma_f32_16x16x32_bf16 v[68:71], v[178:181], v[218:221], v[68:71]
	v_mfma_f32_16x16x32_bf16 v[120:123], v[174:177], v[190:193], v[120:123]
	v_mfma_f32_16x16x32_bf16 v[116:119], v[182:185], v[190:193], v[116:119]
	v_mfma_f32_16x16x32_bf16 v[104:107], v[174:177], v[206:209], v[104:107]
	v_mfma_f32_16x16x32_bf16 v[100:103], v[182:185], v[206:209], v[100:103]
	v_mfma_f32_16x16x32_bf16 v[88:91], v[174:177], v[214:217], v[88:91]
	v_mfma_f32_16x16x32_bf16 v[84:87], v[182:185], v[214:217], v[84:87]
	v_mfma_f32_16x16x32_bf16 v[72:75], v[174:177], v[222:225], v[72:75]
	v_mfma_f32_16x16x32_bf16 v[68:71], v[182:185], v[222:225], v[68:71]
	s_setprio 0
	s_barrier
; #define PG8_STAGE(bufoff, gbase, voff) do { _Pragma("unroll") for (int _i = 0; _i < 2; ++_i) \
;         __builtin_amdgcn_global_load_lds((const unsigned*)((const char*)(gbase) + (voff)[_i]), (LAS unsigned*)(lds + (bufoff) + ldsw + _i * 8192), 16, 0, 0); } while (0)
; #define PG8_LDA(dst, b, h) do { _Pragma("unroll") for (int m = 0; m < 4; ++m) _Pragma("unroll") for (int k = 0; k < 2; ++k) dst[m][k] = *(const LAS bf16x8*)(lds + PG8_SA(b, h) + aoff + m * 2048 + k * 1024); } while (0)
; #define PG8_MMA(ai, bj, At, Bt) do { __builtin_amdgcn_s_setprio(1); _Pragma("unroll") for (int m = 0; m < 4; ++m) _Pragma("unroll") for (int n = 0; n < 2; ++n) _Pragma("unroll") for (int k = 0; k < 2; ++k) \
;         acc[ai][bj][m][n] = __builtin_amdgcn_mfma_f32_16x16x32_bf16(Bt[n][k], At[m][k], acc[ai][bj][m][n], 0, 0, 0); __builtin_amdgcn_s_setprio(0); } while (0)
; #define PG8_WAIT_V(n) asm volatile("s_waitcnt vmcnt(" #n ")" ::: "memory")
; #define PG8_WAIT_L(n) asm volatile("s_waitcnt lgkmcnt(" #n ")" ::: "memory")
; #define PG8_BAR __builtin_amdgcn_s_barrier()
; #define PG8_SCHED __builtin_amdgcn_sched_barrier(0)
; template <class Epi, bool ALIGN_EPI>
; DI void gemm_phase(LAS unsigned char* lds, const Sched& S, const Epi& E, int tid) {
;     ...
;             PG8_LDA(At, 1, 1); PG8_STAGE(PG8_SB(1, 0), b3, voffB); PG8_STAGE(PG8_SB(1, 1), b3 + hstepB, voffB); PG8_STAGE(PG8_SA(1, 0), a3, voffA);
;             PG8_WAIT_V(8); PG8_WAIT_L(0); PG8_BAR; PG8_MMA(1, 0, At, B0); PG8_MMA(1, 1, At, B1); PG8_BAR; PG8_SCHED;
;         }
	s_add_i32 s28, s40, s49
	v_lshl_add_u64 v[154:155], v[154:155], 0, s[84:85]
	s_mov_b32 m0, s28
	ds_read_b128 v[186:189], v157 offset:49152
	ds_read_b128 v[190:193], v157 offset:50176
	ds_read_b128 v[202:205], v157 offset:51200
	ds_read_b128 v[206:209], v157 offset:52224
	ds_read_b128 v[210:213], v157 offset:53248
	ds_read_b128 v[214:217], v157 offset:54272
	ds_read_b128 v[218:221], v157 offset:55296
	ds_read_b128 v[222:225], v157 offset:56320
	global_load_lds_dwordx4 v[154:155], off
	s_add_i32 m0, s28, 0x2000
	s_add_u32 s24, s24, 0x40080
	v_lshl_add_u64 v[154:155], v[158:159], 0, s[84:85]
	s_addc_u32 s25, s25, 0
	s_add_i32 s28, s41, s49
	global_load_lds_dwordx4 v[154:155], off
	v_lshl_add_u64 v[154:155], s[24:25], 0, v[134:135]
	s_mov_b32 m0, s28
	s_nop 0
	global_load_lds_dwordx4 v[154:155], off
	v_lshl_add_u64 v[154:155], s[24:25], 0, v[138:139]
	s_add_i32 m0, s28, 0x2000
	s_nop 0
	global_load_lds_dwordx4 v[154:155], off
	v_lshl_add_u64 v[154:155], v[194:195], 0, s[84:85]
	s_mov_b32 m0, s54
	s_nop 0
	global_load_lds_dwordx4 v[154:155], off
	v_lshl_add_u64 v[154:155], v[226:227], 0, s[84:85]
	s_mov_b32 m0, s55
	s_nop 0
	global_load_lds_dwordx4 v[154:155], off
	s_waitcnt vmcnt(8)
	s_waitcnt lgkmcnt(0)
	s_barrier
	s_setprio 1
	s_waitcnt lgkmcnt(0)
	v_mfma_f32_16x16x32_bf16 v[64:67], v[146:149], v[186:189], v[64:67]
	v_mfma_f32_16x16x32_bf16 v[60:63], v[162:165], v[186:189], v[60:63]
	v_mfma_f32_16x16x32_bf16 v[48:51], v[146:149], v[202:205], v[48:51]
	v_mfma_f32_16x16x32_bf16 v[44:47], v[162:165], v[202:205], v[44:47]
	v_mfma_f32_16x16x32_bf16 v[32:35], v[146:149], v[210:213], v[32:35]
	v_mfma_f32_16x16x32_bf16 v[28:31], v[162:165], v[210:213], v[28:31]
	v_mfma_f32_16x16x32_bf16 v[16:19], v[146:149], v[218:221], v[16:19]
	v_mfma_f32_16x16x32_bf16 v[12:15], v[162:165], v[218:221], v[12:15]
	v_mfma_f32_16x16x32_bf16 v[64:67], v[150:153], v[190:193], v[64:67]
	v_mfma_f32_16x16x32_bf16 v[60:63], v[166:169], v[190:193], v[60:63]
	v_mfma_f32_16x16x32_bf16 v[48:51], v[150:153], v[206:209], v[48:51]
	v_mfma_f32_16x16x32_bf16 v[44:47], v[166:169], v[206:209], v[44:47]
	v_mfma_f32_16x16x32_bf16 v[32:35], v[150:153], v[214:217], v[32:35]
	v_mfma_f32_16x16x32_bf16 v[28:31], v[166:169], v[214:217], v[28:31]
	v_mfma_f32_16x16x32_bf16 v[16:19], v[150:153], v[222:225], v[16:19]
	v_mfma_f32_16x16x32_bf16 v[12:15], v[166:169], v[222:225], v[12:15]
	s_setprio 0
	s_setprio 1
	v_mfma_f32_16x16x32_bf16 v[56:59], v[170:173], v[186:189], v[56:59]
	v_mfma_f32_16x16x32_bf16 v[52:55], v[178:181], v[186:189], v[52:55]
	v_mfma_f32_16x16x32_bf16 v[40:43], v[170:173], v[202:205], v[40:43]
	v_mfma_f32_16x16x32_bf16 v[36:39], v[178:181], v[202:205], v[36:39]
	v_mfma_f32_16x16x32_bf16 v[24:27], v[170:173], v[210:213], v[24:27]
	v_mfma_f32_16x16x32_bf16 v[20:23], v[178:181], v[210:213], v[20:23]
	v_mfma_f32_16x16x32_bf16 v[8:11], v[170:173], v[218:221], v[8:11]
	v_mfma_f32_16x16x32_bf16 v[4:7], v[178:181], v[218:221], v[4:7]
	v_mfma_f32_16x16x32_bf16 v[56:59], v[174:177], v[190:193], v[56:59]
	v_mfma_f32_16x16x32_bf16 v[52:55], v[182:185], v[190:193], v[52:55]
	v_mfma_f32_16x16x32_bf16 v[40:43], v[174:177], v[206:209], v[40:43]
	v_mfma_f32_16x16x32_bf16 v[36:39], v[182:185], v[206:209], v[36:39]
	v_mfma_f32_16x16x32_bf16 v[24:27], v[174:177], v[214:217], v[24:27]
	v_mfma_f32_16x16x32_bf16 v[20:23], v[182:185], v[214:217], v[20:23]
	v_mfma_f32_16x16x32_bf16 v[8:11], v[174:177], v[222:225], v[8:11]
	v_mfma_f32_16x16x32_bf16 v[4:7], v[182:185], v[222:225], v[4:7]
	s_setprio 0
	s_barrier
	s_add_i32 s39, s39, 2
	s_add_u32 s22, s22, 0x100
	s_addc_u32 s23, s23, 0
	s_add_u32 s37, s37, 0x100
	s_addc_u32 s38, s38, 0
	s_cmp_gt_u32 s39, 13

; #define PG8_STAGE(bufoff, gbase, voff) do { _Pragma("unroll") for (int _i = 0; _i < 2; ++_i) \
;         __builtin_amdgcn_global_load_lds((const unsigned*)((const char*)(gbase) + (voff)[_i]), (LAS unsigned*)(lds + (bufoff) + ldsw + _i * 8192), 16, 0, 0); } while (0)
; #define PG8_LDA(dst, b, h) do { _Pragma("unroll") for (int m = 0; m < 4; ++m) _Pragma("unroll") for (int k = 0; k < 2; ++k) dst[m][k] = *(const LAS bf16x8*)(lds + PG8_SA(b, h) + aoff + m * 2048 + k * 1024); } while (0)
; #define PG8_LDB(dst, b, h) do { _Pragma("unroll") for (int n = 0; n < 2; ++n) _Pragma("unroll") for (int k = 0; k < 2; ++k) dst[n][k] = *(const LAS bf16x8*)(lds + PG8_SB(b, h) + boff + n * 2048 + k * 1024); } while (0)
; #define PG8_MMA(ai, bj, At, Bt) do { __builtin_amdgcn_s_setprio(1); _Pragma("unroll") for (int m = 0; m < 4; ++m) _Pragma("unroll") for (int n = 0; n < 2; ++n) _Pragma("unroll") for (int k = 0; k < 2; ++k) \
;         acc[ai][bj][m][n] = __builtin_amdgcn_mfma_f32_16x16x32_bf16(Bt[n][k], At[m][k], acc[ai][bj][m][n], 0, 0, 0); __builtin_amdgcn_s_setprio(0); } while (0)
; #define PG8_WAIT_V(n) asm volatile("s_waitcnt vmcnt(" #n ")" ::: "memory")
; #define PG8_BAR __builtin_amdgcn_s_barrier()
; template <class Epi, bool ALIGN_EPI>
; DI void gemm_phase(LAS unsigned char* lds, const Sched& S, const Epi& E, int tid) {
;     ...
;         const bool has_next = S.next(ui + 1, nxt);
;         const char* nA = has_next ? nxt.a : cA; const char* nB = has_next ? nxt.b : cB;
;         const int nt = cur.nt;
;         for (int t = 0; t < nt; t += 2) {
;             const bool last = (t == nt - 2);
;             const char* a1 = cA + (size_t)(t + 1) * kstep;
;             const char* a2 = last ? nA : cA + (size_t)(t + 2) * kstep; const char* b2 = last ? nB : cB + (size_t)(t + 2) * kstep;
;             const char* a3 = a2 + kstep; const char* b3 = b2 + kstep;
;             PG8_LDB(B0, 0, 0); PG8_LDB(B1, 0, 1); PG8_SCHED; PG8_LDA(At, 0, 0); PG8_STAGE(PG8_SA(1, 1), a1 + hstepA, voffA);
;             PG8_WAIT_V(8); PG8_WAIT_L(0); PG8_BAR; PG8_MMA(0, 0, At, B0); PG8_MMA(0, 1, At, B1); PG8_BAR; PG8_SCHED;
;             PG8_LDA(At, 0, 1); PG8_STAGE(PG8_SB(0, 0), b2, voffB); PG8_STAGE(PG8_SB(0, 1), b2 + hstepB, voffB); PG8_STAGE(PG8_SA(0, 0), a2, voffA);
;             PG8_WAIT_V(8); PG8_WAIT_L(0); PG8_BAR; PG8_MMA(1, 0, At, B0); PG8_MMA(1, 1, At, B1); PG8_BAR; PG8_SCHED;
.LBB0_1048:
	s_and_b64 s[22:23], s[44:45], exec
	s_cselect_b32 s1, s35, s3
	s_cselect_b32 s37, s34, s2
	s_cselect_b32 s38, s43, s21
	s_cselect_b32 s39, s42, s20
	s_add_u32 s2, s2, 0x40080
	s_addc_u32 s3, s3, 0
	s_add_u32 s40, s20, 0x100
	s_addc_u32 s41, s21, 0
	s_mov_b32 s46, -2
	s_add_u32 s20, s2, 0xfffc0080
	s_addc_u32 s21, s3, -1
	s_add_i32 s47, 0, 0x10000
	s_cmp_eq_u32 s46, 12
	s_cselect_b32 s23, s1, s21
	s_cselect_b32 s22, s37, s20
	v_add_u32_e32 v158, s47, v141
	s_cselect_b32 s21, s38, s41
	s_cselect_b32 s20, s39, s40
	s_add_i32 s68, 0, 0x14000
	ds_read_b128 v[146:149], v158
	ds_read_b128 v[150:153], v158 offset:1024
	ds_read_b128 v[154:157], v158 offset:2048
	ds_read_b128 v[162:165], v158 offset:3072
	v_add_u32_e32 v158, s68, v141
	ds_read_b128 v[166:169], v158
	ds_read_b128 v[174:177], v158 offset:1024
	ds_read_b128 v[178:181], v158 offset:2048
	ds_read_b128 v[182:185], v158 offset:3072
	v_lshl_add_u64 v[158:159], s[2:3], 0, v[142:143]
	s_add_i32 m0, s55, 0xc000
	ds_read_b128 v[186:189], v172
	ds_read_b128 v[190:193], v172 offset:1024
	ds_read_b128 v[202:205], v172 offset:2048
	ds_read_b128 v[206:209], v172 offset:3072
	ds_read_b128 v[210:213], v172 offset:4096
	ds_read_b128 v[214:217], v172 offset:5120
	ds_read_b128 v[218:221], v172 offset:6144
	ds_read_b128 v[222:225], v172 offset:7168
	global_load_lds_dwordx4 v[158:159], off
	v_lshl_add_u64 v[158:159], s[2:3], 0, v[144:145]
	s_add_i32 m0, s55, 0xe000
	s_nop 0
	global_load_lds_dwordx4 v[158:159], off
	s_waitcnt vmcnt(8)
	s_waitcnt lgkmcnt(0)
	s_barrier
	s_setprio 1
	s_waitcnt lgkmcnt(0)
	v_mfma_f32_16x16x32_bf16 v[128:131], v[146:149], v[186:189], 0
	v_mfma_f32_16x16x32_bf16 v[124:127], v[154:157], v[186:189], 0
	v_mfma_f32_16x16x32_bf16 v[112:115], v[146:149], v[202:205], 0
	v_mfma_f32_16x16x32_bf16 v[108:111], v[154:157], v[202:205], 0
	v_mfma_f32_16x16x32_bf16 v[96:99], v[146:149], v[210:213], 0
	v_mfma_f32_16x16x32_bf16 v[92:95], v[154:157], v[210:213], 0
	v_mfma_f32_16x16x32_bf16 v[80:83], v[146:149], v[218:221], 0
	v_mfma_f32_16x16x32_bf16 v[76:79], v[154:157], v[218:221], 0
	v_mfma_f32_16x16x32_bf16 v[128:131], v[150:153], v[190:193], v[128:131]
	v_mfma_f32_16x16x32_bf16 v[124:127], v[162:165], v[190:193], v[124:127]
	v_mfma_f32_16x16x32_bf16 v[112:115], v[150:153], v[206:209], v[112:115]
	v_mfma_f32_16x16x32_bf16 v[108:111], v[162:165], v[206:209], v[108:111]
	v_mfma_f32_16x16x32_bf16 v[96:99], v[150:153], v[214:217], v[96:99]
	v_mfma_f32_16x16x32_bf16 v[92:95], v[162:165], v[214:217], v[92:95]
	v_mfma_f32_16x16x32_bf16 v[80:83], v[150:153], v[222:225], v[80:83]
	v_mfma_f32_16x16x32_bf16 v[76:79], v[162:165], v[222:225], v[76:79]
	s_setprio 0
	s_setprio 1
	v_mfma_f32_16x16x32_bf16 v[120:123], v[166:169], v[186:189], 0
	v_mfma_f32_16x16x32_bf16 v[116:119], v[178:181], v[186:189], 0
	v_mfma_f32_16x16x32_bf16 v[104:107], v[166:169], v[202:205], 0
	v_mfma_f32_16x16x32_bf16 v[100:103], v[178:181], v[202:205], 0
	v_mfma_f32_16x16x32_bf16 v[88:91], v[166:169], v[210:213], 0
	v_mfma_f32_16x16x32_bf16 v[84:87], v[178:181], v[210:213], 0
	v_mfma_f32_16x16x32_bf16 v[72:75], v[166:169], v[218:221], 0
	v_mfma_f32_16x16x32_bf16 v[68:71], v[178:181], v[218:221], 0
	v_mfma_f32_16x16x32_bf16 v[120:123], v[174:177], v[190:193], v[120:123]
	v_mfma_f32_16x16x32_bf16 v[116:119], v[182:185], v[190:193], v[116:119]
	v_mfma_f32_16x16x32_bf16 v[104:107], v[174:177], v[206:209], v[104:107]
	v_mfma_f32_16x16x32_bf16 v[100:103], v[182:185], v[206:209], v[100:103]
	v_mfma_f32_16x16x32_bf16 v[88:91], v[174:177], v[214:217], v[88:91]
	v_mfma_f32_16x16x32_bf16 v[84:87], v[182:185], v[214:217], v[84:87]
	v_mfma_f32_16x16x32_bf16 v[72:75], v[174:177], v[222:225], v[72:75]
	v_mfma_f32_16x16x32_bf16 v[68:71], v[182:185], v[222:225], v[68:71]
	s_setprio 0
	s_barrier
	s_add_i32 s47, s47, s54
	v_lshl_add_u64 v[158:159], s[20:21], 0, v[134:135]
	s_mov_b32 m0, s47
	ds_read_b128 v[186:189], v172 offset:16384
	ds_read_b128 v[190:193], v172 offset:17408
	ds_read_b128 v[202:205], v172 offset:18432
	ds_read_b128 v[206:209], v172 offset:19456
	ds_read_b128 v[210:213], v172 offset:20480
	ds_read_b128 v[214:217], v172 offset:21504
	ds_read_b128 v[218:221], v172 offset:22528
	ds_read_b128 v[222:225], v172 offset:23552
	global_load_lds_dwordx4 v[158:159], off
	s_add_i32 m0, s47, 0x2000
	s_add_u32 s48, s20, 0x40000
	v_lshl_add_u64 v[170:171], s[20:21], 0, v[138:139]
	s_addc_u32 s49, s21, 0
	s_add_i32 s47, s68, s54
	global_load_lds_dwordx4 v[170:171], off
	v_lshl_add_u64 v[194:195], s[48:49], 0, v[134:135]
	s_mov_b32 m0, s47
	v_lshl_add_u64 v[226:227], s[22:23], 0, v[136:137]
	global_load_lds_dwordx4 v[194:195], off
	v_lshl_add_u64 v[194:195], s[48:49], 0, v[138:139]
	s_add_i32 m0, s47, 0x2000
	s_nop 0
	global_load_lds_dwordx4 v[194:195], off
	v_lshl_add_u64 v[194:195], s[22:23], 0, v[132:133]
	s_mov_b32 m0, s55
	s_nop 0
	global_load_lds_dwordx4 v[194:195], off
	s_mov_b32 m0, s56
	s_nop 0
	global_load_lds_dwordx4 v[226:227], off
	s_waitcnt vmcnt(8)
	s_waitcnt lgkmcnt(0)
	s_barrier
; #define PG8_STAGE(bufoff, gbase, voff) do { _Pragma("unroll") for (int _i = 0; _i < 2; ++_i) \
;         __builtin_amdgcn_global_load_lds((const unsigned*)((const char*)(gbase) + (voff)[_i]), (LAS unsigned*)(lds + (bufoff) + ldsw + _i * 8192), 16, 0, 0); } while (0)
; #define PG8_LDA(dst, b, h) do { _Pragma("unroll") for (int m = 0; m < 4; ++m) _Pragma("unroll") for (int k = 0; k < 2; ++k) dst[m][k] = *(const LAS bf16x8*)(lds + PG8_SA(b, h) + aoff + m * 2048 + k * 1024); } while (0)
; #define PG8_LDB(dst, b, h) do { _Pragma("unroll") for (int n = 0; n < 2; ++n) _Pragma("unroll") for (int k = 0; k < 2; ++k) dst[n][k] = *(const LAS bf16x8*)(lds + PG8_SB(b, h) + boff + n * 2048 + k * 1024); } while (0)
; #define PG8_MMA(ai, bj, At, Bt) do { __builtin_amdgcn_s_setprio(1); _Pragma("unroll") for (int m = 0; m < 4; ++m) _Pragma("unroll") for (int n = 0; n < 2; ++n) _Pragma("unroll") for (int k = 0; k < 2; ++k) \
;         acc[ai][bj][m][n] = __builtin_amdgcn_mfma_f32_16x16x32_bf16(Bt[n][k], At[m][k], acc[ai][bj][m][n], 0, 0, 0); __builtin_amdgcn_s_setprio(0); } while (0)
; #define PG8_WAIT_V(n) asm volatile("s_waitcnt vmcnt(" #n ")" ::: "memory")
; #define PG8_WAIT_L(n) asm volatile("s_waitcnt lgkmcnt(" #n ")" ::: "memory")
; #define PG8_BAR __builtin_amdgcn_s_barrier()
; #define PG8_SCHED __builtin_amdgcn_sched_barrier(0)
; template <class Epi, bool ALIGN_EPI>
; DI void gemm_phase(LAS unsigned char* lds, const Sched& S, const Epi& E, int tid) {
;     ...
;             PG8_WAIT_V(8); PG8_WAIT_L(0); PG8_BAR; PG8_MMA(1, 0, At, B0); PG8_MMA(1, 1, At, B1); PG8_BAR; PG8_SCHED;
;             PG8_LDB(B0, 1, 0); PG8_LDB(B1, 1, 1); PG8_SCHED; PG8_LDA(At, 1, 0); PG8_STAGE(PG8_SA(0, 1), a2 + hstepA, voffA);
;             PG8_WAIT_V(8); PG8_WAIT_L(0); PG8_BAR; PG8_MMA(0, 0, At, B0); PG8_MMA(0, 1, At, B1); PG8_BAR; PG8_SCHED;
	s_setprio 1
	s_waitcnt lgkmcnt(0)
	v_mfma_f32_16x16x32_bf16 v[64:67], v[146:149], v[186:189], 0
	v_mfma_f32_16x16x32_bf16 v[60:63], v[154:157], v[186:189], 0
	v_mfma_f32_16x16x32_bf16 v[48:51], v[146:149], v[202:205], 0
	v_mfma_f32_16x16x32_bf16 v[44:47], v[154:157], v[202:205], 0
	v_mfma_f32_16x16x32_bf16 v[32:35], v[146:149], v[210:213], 0
	v_mfma_f32_16x16x32_bf16 v[28:31], v[154:157], v[210:213], 0
	v_mfma_f32_16x16x32_bf16 v[16:19], v[146:149], v[218:221], 0
	v_mfma_f32_16x16x32_bf16 v[12:15], v[154:157], v[218:221], 0
	v_mfma_f32_16x16x32_bf16 v[64:67], v[150:153], v[190:193], v[64:67]
	v_mfma_f32_16x16x32_bf16 v[60:63], v[162:165], v[190:193], v[60:63]
	v_mfma_f32_16x16x32_bf16 v[48:51], v[150:153], v[206:209], v[48:51]
	v_mfma_f32_16x16x32_bf16 v[44:47], v[162:165], v[206:209], v[44:47]
	v_mfma_f32_16x16x32_bf16 v[32:35], v[150:153], v[214:217], v[32:35]
	v_mfma_f32_16x16x32_bf16 v[28:31], v[162:165], v[214:217], v[28:31]
	v_mfma_f32_16x16x32_bf16 v[16:19], v[150:153], v[222:225], v[16:19]
	v_mfma_f32_16x16x32_bf16 v[12:15], v[162:165], v[222:225], v[12:15]
	s_setprio 0
	s_setprio 1
	v_mfma_f32_16x16x32_bf16 v[56:59], v[166:169], v[186:189], 0
	v_mfma_f32_16x16x32_bf16 v[52:55], v[178:181], v[186:189], 0
	v_mfma_f32_16x16x32_bf16 v[40:43], v[166:169], v[202:205], 0
	v_mfma_f32_16x16x32_bf16 v[36:39], v[178:181], v[202:205], 0
	v_mfma_f32_16x16x32_bf16 v[24:27], v[166:169], v[210:213], 0
	v_mfma_f32_16x16x32_bf16 v[20:23], v[178:181], v[210:213], 0
	v_mfma_f32_16x16x32_bf16 v[8:11], v[166:169], v[218:221], 0
	v_mfma_f32_16x16x32_bf16 v[4:7], v[178:181], v[218:221], 0
	v_mfma_f32_16x16x32_bf16 v[56:59], v[174:177], v[190:193], v[56:59]
	v_mfma_f32_16x16x32_bf16 v[52:55], v[182:185], v[190:193], v[52:55]
	v_mfma_f32_16x16x32_bf16 v[40:43], v[174:177], v[206:209], v[40:43]
	v_mfma_f32_16x16x32_bf16 v[36:39], v[182:185], v[206:209], v[36:39]
	v_mfma_f32_16x16x32_bf16 v[24:27], v[174:177], v[214:217], v[24:27]
	v_mfma_f32_16x16x32_bf16 v[20:23], v[182:185], v[214:217], v[20:23]
	v_mfma_f32_16x16x32_bf16 v[8:11], v[174:177], v[222:225], v[8:11]
	v_mfma_f32_16x16x32_bf16 v[4:7], v[182:185], v[222:225], v[4:7]
	s_setprio 0
	s_barrier
	s_add_i32 s47, 0, 0x18000
	s_add_i32 s48, 0, 0x1c000
	v_add_u32_e32 v162, s47, v141
	v_add_u32_e32 v173, s48, v141
	ds_read_b128 v[146:149], v162
	ds_read_b128 v[150:153], v162 offset:1024
	ds_read_b128 v[154:157], v162 offset:2048
	ds_read_b128 v[162:165], v162 offset:3072
	ds_read_b128 v[166:169], v173
	ds_read_b128 v[174:177], v173 offset:1024
	ds_read_b128 v[178:181], v173 offset:2048
	ds_read_b128 v[182:185], v173 offset:3072
	s_add_u32 s22, s22, 0x40000
	s_addc_u32 s23, s23, 0
	s_mov_b32 m0, s57
	v_lshl_add_u64 v[228:229], s[22:23], 0, v[132:133]
	ds_read_b128 v[186:189], v172 offset:32768
	ds_read_b128 v[190:193], v172 offset:33792
	ds_read_b128 v[202:205], v172 offset:34816
	ds_read_b128 v[206:209], v172 offset:35840
	ds_read_b128 v[210:213], v172 offset:36864
	ds_read_b128 v[214:217], v172 offset:37888
	ds_read_b128 v[218:221], v172 offset:38912
	ds_read_b128 v[222:225], v172 offset:39936
	global_load_lds_dwordx4 v[228:229], off
	v_lshl_add_u64 v[228:229], s[22:23], 0, v[136:137]
	s_mov_b32 m0, s58
	s_nop 0
	global_load_lds_dwordx4 v[228:229], off
	s_waitcnt vmcnt(8)
	s_waitcnt lgkmcnt(0)
	s_barrier
	s_setprio 1
	s_waitcnt lgkmcnt(0)
	v_mfma_f32_16x16x32_bf16 v[128:131], v[146:149], v[186:189], v[128:131]
	v_mfma_f32_16x16x32_bf16 v[124:127], v[154:157], v[186:189], v[124:127]
	v_mfma_f32_16x16x32_bf16 v[112:115], v[146:149], v[202:205], v[112:115]
	v_mfma_f32_16x16x32_bf16 v[108:111], v[154:157], v[202:205], v[108:111]
	v_mfma_f32_16x16x32_bf16 v[96:99], v[146:149], v[210:213], v[96:99]
	v_mfma_f32_16x16x32_bf16 v[92:95], v[154:157], v[210:213], v[92:95]
	v_mfma_f32_16x16x32_bf16 v[80:83], v[146:149], v[218:221], v[80:83]
	v_mfma_f32_16x16x32_bf16 v[76:79], v[154:157], v[218:221], v[76:79]
	v_mfma_f32_16x16x32_bf16 v[128:131], v[150:153], v[190:193], v[128:131]
	v_mfma_f32_16x16x32_bf16 v[124:127], v[162:165], v[190:193], v[124:127]
	v_mfma_f32_16x16x32_bf16 v[112:115], v[150:153], v[206:209], v[112:115]
	v_mfma_f32_16x16x32_bf16 v[108:111], v[162:165], v[206:209], v[108:111]
	v_mfma_f32_16x16x32_bf16 v[96:99], v[150:153], v[214:217], v[96:99]
	v_mfma_f32_16x16x32_bf16 v[92:95], v[162:165], v[214:217], v[92:95]
	v_mfma_f32_16x16x32_bf16 v[80:83], v[150:153], v[222:225], v[80:83]
	v_mfma_f32_16x16x32_bf16 v[76:79], v[162:165], v[222:225], v[76:79]
	s_setprio 0
	s_setprio 1
	v_mfma_f32_16x16x32_bf16 v[120:123], v[166:169], v[186:189], v[120:123]
	v_mfma_f32_16x16x32_bf16 v[116:119], v[178:181], v[186:189], v[116:119]
	v_mfma_f32_16x16x32_bf16 v[104:107], v[166:169], v[202:205], v[104:107]
	v_mfma_f32_16x16x32_bf16 v[100:103], v[178:181], v[202:205], v[100:103]
	v_mfma_f32_16x16x32_bf16 v[88:91], v[166:169], v[210:213], v[88:91]
	v_mfma_f32_16x16x32_bf16 v[84:87], v[178:181], v[210:213], v[84:87]
	v_mfma_f32_16x16x32_bf16 v[72:75], v[166:169], v[218:221], v[72:75]
	v_mfma_f32_16x16x32_bf16 v[68:71], v[178:181], v[218:221], v[68:71]
	v_mfma_f32_16x16x32_bf16 v[120:123], v[174:177], v[190:193], v[120:123]
	v_mfma_f32_16x16x32_bf16 v[116:119], v[182:185], v[190:193], v[116:119]
	v_mfma_f32_16x16x32_bf16 v[104:107], v[174:177], v[206:209], v[104:107]
	v_mfma_f32_16x16x32_bf16 v[100:103], v[182:185], v[206:209], v[100:103]
	v_mfma_f32_16x16x32_bf16 v[88:91], v[174:177], v[214:217], v[88:91]
	v_mfma_f32_16x16x32_bf16 v[84:87], v[182:185], v[214:217], v[84:87]
	v_mfma_f32_16x16x32_bf16 v[72:75], v[174:177], v[222:225], v[72:75]
	v_mfma_f32_16x16x32_bf16 v[68:71], v[182:185], v[222:225], v[68:71]
	s_setprio 0
	s_barrier
; #define PG8_STAGE(bufoff, gbase, voff) do { _Pragma("unroll") for (int _i = 0; _i < 2; ++_i) \
;         __builtin_amdgcn_global_load_lds((const unsigned*)((const char*)(gbase) + (voff)[_i]), (LAS unsigned*)(lds + (bufoff) + ldsw + _i * 8192), 16, 0, 0); } while (0)
; #define PG8_LDA(dst, b, h) do { _Pragma("unroll") for (int m = 0; m < 4; ++m) _Pragma("unroll") for (int k = 0; k < 2; ++k) dst[m][k] = *(const LAS bf16x8*)(lds + PG8_SA(b, h) + aoff + m * 2048 + k * 1024); } while (0)
; #define PG8_MMA(ai, bj, At, Bt) do { __builtin_amdgcn_s_setprio(1); _Pragma("unroll") for (int m = 0; m < 4; ++m) _Pragma("unroll") for (int n = 0; n < 2; ++n) _Pragma("unroll") for (int k = 0; k < 2; ++k) \
;         acc[ai][bj][m][n] = __builtin_amdgcn_mfma_f32_16x16x32_bf16(Bt[n][k], At[m][k], acc[ai][bj][m][n], 0, 0, 0); __builtin_amdgcn_s_setprio(0); } while (0)
; #define PG8_WAIT_V(n) asm volatile("s_waitcnt vmcnt(" #n ")" ::: "memory")
; #define PG8_WAIT_L(n) asm volatile("s_waitcnt lgkmcnt(" #n ")" ::: "memory")
; #define PG8_BAR __builtin_amdgcn_s_barrier()
; #define PG8_SCHED __builtin_amdgcn_sched_barrier(0)
; template <class Epi, bool ALIGN_EPI>
; DI void gemm_phase(LAS unsigned char* lds, const Sched& S, const Epi& E, int tid) {
;     ...
;             PG8_LDA(At, 1, 1); PG8_STAGE(PG8_SB(1, 0), b3, voffB); PG8_STAGE(PG8_SB(1, 1), b3 + hstepB, voffB); PG8_STAGE(PG8_SA(1, 0), a3, voffA);
;             PG8_WAIT_V(8); PG8_WAIT_L(0); PG8_BAR; PG8_MMA(1, 0, At, B0); PG8_MMA(1, 1, At, B1); PG8_BAR; PG8_SCHED;
;         }
	s_add_i32 s22, s47, s54
	v_lshl_add_u64 v[158:159], v[158:159], 0, s[84:85]
	s_mov_b32 m0, s22
	ds_read_b128 v[186:189], v172 offset:49152
	ds_read_b128 v[190:193], v172 offset:50176
	ds_read_b128 v[202:205], v172 offset:51200
	ds_read_b128 v[206:209], v172 offset:52224
	ds_read_b128 v[210:213], v172 offset:53248
	ds_read_b128 v[214:217], v172 offset:54272
	ds_read_b128 v[218:221], v172 offset:55296
	ds_read_b128 v[222:225], v172 offset:56320
	global_load_lds_dwordx4 v[158:159], off
	s_add_i32 m0, s22, 0x2000
	s_add_u32 s20, s20, 0x40080
	v_lshl_add_u64 v[158:159], v[170:171], 0, s[84:85]
	s_addc_u32 s21, s21, 0
	s_add_i32 s22, s48, s54
	global_load_lds_dwordx4 v[158:159], off
	v_lshl_add_u64 v[158:159], s[20:21], 0, v[134:135]
	s_mov_b32 m0, s22
	s_nop 0
	global_load_lds_dwordx4 v[158:159], off
	v_lshl_add_u64 v[158:159], s[20:21], 0, v[138:139]
	s_add_i32 m0, s22, 0x2000
	s_nop 0
	global_load_lds_dwordx4 v[158:159], off
	v_lshl_add_u64 v[158:159], v[194:195], 0, s[84:85]
	s_mov_b32 m0, s59
	s_nop 0
	global_load_lds_dwordx4 v[158:159], off
	v_lshl_add_u64 v[158:159], v[226:227], 0, s[84:85]
	s_mov_b32 m0, s60
	s_nop 0
	global_load_lds_dwordx4 v[158:159], off
	s_waitcnt vmcnt(8)
	s_waitcnt lgkmcnt(0)
	s_barrier
	s_setprio 1
	s_waitcnt lgkmcnt(0)
	v_mfma_f32_16x16x32_bf16 v[64:67], v[146:149], v[186:189], v[64:67]
	v_mfma_f32_16x16x32_bf16 v[60:63], v[154:157], v[186:189], v[60:63]
	v_mfma_f32_16x16x32_bf16 v[48:51], v[146:149], v[202:205], v[48:51]
	v_mfma_f32_16x16x32_bf16 v[44:47], v[154:157], v[202:205], v[44:47]
	v_mfma_f32_16x16x32_bf16 v[32:35], v[146:149], v[210:213], v[32:35]
	v_mfma_f32_16x16x32_bf16 v[28:31], v[154:157], v[210:213], v[28:31]
	v_mfma_f32_16x16x32_bf16 v[16:19], v[146:149], v[218:221], v[16:19]
	v_mfma_f32_16x16x32_bf16 v[12:15], v[154:157], v[218:221], v[12:15]
	v_mfma_f32_16x16x32_bf16 v[64:67], v[150:153], v[190:193], v[64:67]
	v_mfma_f32_16x16x32_bf16 v[60:63], v[162:165], v[190:193], v[60:63]
	v_mfma_f32_16x16x32_bf16 v[48:51], v[150:153], v[206:209], v[48:51]
	v_mfma_f32_16x16x32_bf16 v[44:47], v[162:165], v[206:209], v[44:47]
	v_mfma_f32_16x16x32_bf16 v[32:35], v[150:153], v[214:217], v[32:35]
	v_mfma_f32_16x16x32_bf16 v[28:31], v[162:165], v[214:217], v[28:31]
	v_mfma_f32_16x16x32_bf16 v[16:19], v[150:153], v[222:225], v[16:19]
	v_mfma_f32_16x16x32_bf16 v[12:15], v[162:165], v[222:225], v[12:15]
	s_setprio 0
	s_setprio 1
	v_mfma_f32_16x16x32_bf16 v[56:59], v[166:169], v[186:189], v[56:59]
	v_mfma_f32_16x16x32_bf16 v[52:55], v[178:181], v[186:189], v[52:55]
	v_mfma_f32_16x16x32_bf16 v[40:43], v[166:169], v[202:205], v[40:43]
	v_mfma_f32_16x16x32_bf16 v[36:39], v[178:181], v[202:205], v[36:39]
	v_mfma_f32_16x16x32_bf16 v[24:27], v[166:169], v[210:213], v[24:27]
	v_mfma_f32_16x16x32_bf16 v[20:23], v[178:181], v[210:213], v[20:23]
	v_mfma_f32_16x16x32_bf16 v[8:11], v[166:169], v[218:221], v[8:11]
	v_mfma_f32_16x16x32_bf16 v[4:7], v[178:181], v[218:221], v[4:7]
	v_mfma_f32_16x16x32_bf16 v[56:59], v[174:177], v[190:193], v[56:59]
	v_mfma_f32_16x16x32_bf16 v[52:55], v[182:185], v[190:193], v[52:55]
	v_mfma_f32_16x16x32_bf16 v[40:43], v[174:177], v[206:209], v[40:43]
	v_mfma_f32_16x16x32_bf16 v[36:39], v[182:185], v[206:209], v[36:39]
	v_mfma_f32_16x16x32_bf16 v[24:27], v[174:177], v[214:217], v[24:27]
	v_mfma_f32_16x16x32_bf16 v[20:23], v[182:185], v[214:217], v[20:23]
	v_mfma_f32_16x16x32_bf16 v[8:11], v[174:177], v[222:225], v[8:11]
	v_mfma_f32_16x16x32_bf16 v[4:7], v[182:185], v[222:225], v[4:7]
	s_setprio 0
	s_barrier
	s_add_i32 s46, s46, 2
	s_add_u32 s2, s2, 0x100
	s_addc_u32 s3, s3, 0
	s_add_u32 s40, s40, 0x100
	s_addc_u32 s41, s41, 0
	s_cmp_gt_u32 s46, 13

; template <int VAR>
; DI void attn_tile(AtState& S, const LAS unsigned char* buf, const bf16x8 q1, const bf16x8 q2, int kt, bool diag, int qpos0, int qpos_l, float slope2, float adv, float decay, int hh, int fr, int fq) {
;     ...
;         asm volatile("; attention: fast tile" ::: "memory");
;         at_qk(s1, s2, buf, q1, q2, S.cinit, hh, fr, fq);
;         S.ref += adv;
;         at_exp(s1, s2, ps1, ps2);
;         if (__any(!(ps1 + ps2 < 0x1p60f))) {
;             asm volatile("; attention: bump" ::: "memory");
;             at_qk(s1, s2, buf, q1, q2, S.cinit, hh, fr, fq);
;             float lm = -1e30f;
; #pragma unroll
;             for (int k4 = 0; k4 < 4; ++k4)
; #pragma unroll
;                 for (int j = 0; j < 4; ++j) lm = fmaxf(lm, fmaxf(s1[k4][j], s2[k4][j]));
;             lm = fmaxf(lm, __shfl_xor(lm, 16)); lm = fmaxf(lm, __shfl_xor(lm, 32));
; template <int VAR>
; DI void attn_segment(const Args& a, const Frame& F, int l, int qrow0, int qpos0, int hp, int ntile, int nf32, const float* ck, const float* cv, int prow0) {
;     ...
;             atb_issue(rb, pb + (size_t)(kt + 2 < nl ? kt + 2 : nl) * TSTR, voff);
;             attn_tile<VAR>(S, F.lds + (kt & 1) * AT_BUF, q1, q2, kt, kt + 1 == ntile, qpos0, qpos_l, slope2, adv, decay, hh, fr, fq);
.LBB0_1376:
	s_add_i32 s27, s26, -1
	s_min_i32 s14, s27, s25
	s_ashr_i32 s15, s14, 31
	s_add_i32 s28, s22, s26
	s_lshl_b64 s[14:15], s[14:15], 18
	s_add_u32 s14, s0, s14
	s_addc_u32 s15, s1, s15
	global_load_dwordx4 v[28:31], v144, s[14:15] offset:1024
	global_load_dwordx4 v[32:35], v144, s[14:15] offset:1536
	global_load_dwordx4 v[36:39], v146, s[14:15] offset:1024
	global_load_dwordx4 v[40:43], v146, s[14:15] offset:1536
	s_cmpk_eq_i32 s28, 0x42
	s_cselect_b64 s[16:17], -1, 0
	s_cmp_eq_u32 s26, 3
	s_cselect_b64 s[14:15], -1, 0
	s_or_b64 s[18:19], s[14:15], s[16:17]
	s_andn2_b64 vcc, exec, s[18:19]
	s_mov_b64 s[18:19], -1
	s_cbranch_vccz .LBB0_1381
	ds_read_b128 v[76:79], v213
	ds_read_b128 v[80:83], v213 offset:64
	ds_read_b128 v[96:99], v213 offset:4352
	ds_read_b128 v[104:107], v213 offset:4416
	ds_read_b128 v[108:111], v213 offset:8704
	ds_read_b128 v[112:115], v213 offset:8768
	ds_read_b128 v[116:119], v213 offset:13056
	ds_read_b128 v[120:123], v213 offset:13120
	s_waitcnt lgkmcnt(7)
	v_mfma_f32_16x16x32_bf16 v[76:79], v[76:79], v[4:7], v[44:47]
	v_add_f32_e32 v215, v205, v214
	s_waitcnt lgkmcnt(6)
	v_mfma_f32_16x16x32_bf16 v[80:83], v[80:83], v[8:11], v[44:47]
	s_waitcnt lgkmcnt(5)
	v_mfma_f32_16x16x32_bf16 v[96:99], v[96:99], v[4:7], v[48:51]
	s_nop 2
	v_exp_f32_e32 v164, v76
	v_exp_f32_e32 v165, v77
	v_exp_f32_e32 v168, v78
	s_waitcnt lgkmcnt(4)
	v_mfma_f32_16x16x32_bf16 v[104:107], v[104:107], v[8:11], v[48:51]
	v_exp_f32_e32 v169, v79
	v_exp_f32_e32 v162, v80
	v_exp_f32_e32 v163, v81
	s_waitcnt lgkmcnt(3)
	v_mfma_f32_16x16x32_bf16 v[108:111], v[108:111], v[4:7], v[52:55]
	v_exp_f32_e32 v166, v82
	v_exp_f32_e32 v167, v83
	v_exp_f32_e32 v172, v96
	s_waitcnt lgkmcnt(2)
	v_mfma_f32_16x16x32_bf16 v[76:79], v[112:115], v[8:11], v[52:55]
	v_exp_f32_e32 v170, v104
	v_exp_f32_e32 v173, v97
	v_exp_f32_e32 v176, v98
	s_waitcnt lgkmcnt(1)
	v_mfma_f32_16x16x32_bf16 v[80:83], v[116:119], v[4:7], v[56:59]
	v_exp_f32_e32 v177, v99
	v_exp_f32_e32 v174, v106
	v_exp_f32_e32 v175, v107
	s_waitcnt lgkmcnt(0)
	v_mfma_f32_16x16x32_bf16 v[112:115], v[120:123], v[8:11], v[56:59]
	v_exp_f32_e32 v171, v105
	v_exp_f32_e32 v180, v108
	v_exp_f32_e32 v178, v76
	v_exp_f32_e32 v181, v109
	v_exp_f32_e32 v179, v77
	v_exp_f32_e32 v184, v110
	v_exp_f32_e32 v185, v111
	v_exp_f32_e32 v182, v78
	v_exp_f32_e32 v183, v79
	v_exp_f32_e32 v188, v80
	v_exp_f32_e32 v186, v112
	v_exp_f32_e32 v189, v81
	v_exp_f32_e32 v192, v82
	v_exp_f32_e32 v193, v83
	v_exp_f32_e32 v190, v114
	v_exp_f32_e32 v191, v115
	v_exp_f32_e32 v187, v113
	v_pk_add_f32 v[124:125], v[164:165], 0 op_sel_hi:[1,0]
	v_pk_add_f32 v[126:127], v[168:169], 0 op_sel_hi:[1,0]
	v_pk_add_f32 v[116:117], v[162:163], 0 op_sel_hi:[1,0]
	v_pk_add_f32 v[118:119], v[166:167], 0 op_sel_hi:[1,0]
	v_pk_add_f32 v[96:97], v[126:127], v[176:177]
	v_pk_add_f32 v[98:99], v[124:125], v[172:173]
	v_pk_add_f32 v[104:105], v[118:119], v[174:175]
	v_pk_add_f32 v[106:107], v[116:117], v[170:171]
	v_pk_add_f32 v[76:77], v[98:99], v[180:181]
	v_pk_add_f32 v[78:79], v[96:97], v[184:185]
	v_pk_add_f32 v[96:97], v[106:107], v[178:179]
	v_pk_add_f32 v[98:99], v[104:105], v[182:183]
	v_pk_add_f32 v[78:79], v[78:79], v[192:193]
	v_pk_add_f32 v[76:77], v[76:77], v[188:189]
	v_pk_add_f32 v[80:81], v[98:99], v[190:191]
	v_pk_add_f32 v[82:83], v[96:97], v[186:187]
	v_mov_b32_e32 v97, v76
	v_mov_b32_e32 v96, v82
	v_mov_b32_e32 v76, v83
	v_mov_b32_e32 v82, v80
	v_mov_b32_e32 v83, v78
	v_mov_b32_e32 v78, v81
	v_pk_add_f32 v[76:77], v[96:97], v[76:77]
	v_pk_add_f32 v[78:79], v[82:83], v[78:79]
	s_nop 0
	v_pk_add_f32 v[194:195], v[76:77], v[78:79]
	s_nop 0
	v_add_f32_e32 v3, v195, v194
	v_cmp_ngt_f32_e32 vcc, s65, v3
	s_cbranch_vccz .LBB0_1394
	ds_read_b128 v[76:79], v213
	ds_read_b128 v[80:83], v213 offset:64
	ds_read_b128 v[96:99], v213 offset:4352
	ds_read_b128 v[104:107], v213 offset:4416
	ds_read_b128 v[108:111], v213 offset:8704
	ds_read_b128 v[112:115], v213 offset:8768
	ds_read_b128 v[116:119], v213 offset:13056
	ds_read_b128 v[120:123], v213 offset:13120
	s_waitcnt lgkmcnt(7)
	v_mfma_f32_16x16x32_bf16 v[76:79], v[76:79], v[4:7], v[44:47]
	s_waitcnt lgkmcnt(6)
	v_mfma_f32_16x16x32_bf16 v[80:83], v[80:83], v[8:11], v[44:47]
	s_nop 5
	v_max_f32_e32 v124, v76, v76
	v_max_f32_e32 v125, v77, v77
	v_max_f32_e32 v126, v79, v79
	s_waitcnt lgkmcnt(5)
	v_mfma_f32_16x16x32_bf16 v[96:99], v[96:99], v[4:7], v[48:51]
	s_waitcnt lgkmcnt(4)
	v_mfma_f32_16x16x32_bf16 v[104:107], v[104:107], v[8:11], v[48:51]
	v_max_f32_e32 v3, v80, v80
	v_max_f32_e32 v3, v124, v3
	v_max_f32_e32 v124, v81, v81
	v_max_f32_e32 v124, v125, v124
	v_max3_f32 v3, v3, s60, v124
	v_max_f32_e32 v124, v82, v82
	v_max_f32_e32 v125, v78, v78
	v_max_f32_e32 v124, v125, v124
	v_max_f32_e32 v125, v83, v83
	v_max_f32_e32 v125, v126, v125
	v_max3_f32 v3, v3, v124, v125
	v_max_f32_e32 v124, v104, v104
	v_max_f32_e32 v125, v96, v96
	v_max_f32_e32 v124, v125, v124
	v_max_f32_e32 v125, v105, v105
	v_max_f32_e32 v126, v97, v97
	s_waitcnt lgkmcnt(3)
	v_mfma_f32_16x16x32_bf16 v[108:111], v[108:111], v[4:7], v[52:55]
	v_max_f32_e32 v125, v126, v125
	v_max3_f32 v3, v3, v124, v125
	v_max_f32_e32 v124, v106, v106
	s_waitcnt lgkmcnt(2)
	v_mfma_f32_16x16x32_bf16 v[112:115], v[112:115], v[8:11], v[52:55]
	v_max_f32_e32 v125, v98, v98
	v_max_f32_e32 v124, v125, v124
	v_max_f32_e32 v125, v107, v107
	v_max_f32_e32 v126, v99, v99
	v_max_f32_e32 v125, v126, v125
	v_max3_f32 v3, v3, v124, v125
	s_nop 1
	v_max_f32_e32 v124, v112, v112
	v_max_f32_e32 v125, v108, v108
	v_max_f32_e32 v124, v125, v124
	v_max_f32_e32 v125, v113, v113
	v_max_f32_e32 v126, v109, v109
	s_waitcnt lgkmcnt(1)
; #define LAS __attribute__((address_space(3)))
; DI float fast_exp2(float x) { return __builtin_amdgcn_exp2f(x); }
; DI bf16x8 packp(f32x4 a, f32x4 b) { return __builtin_bit_cast(bf16x8, pack8(a, b)); }
; DI void at_exp(f32x4 (&s1)[4], f32x4 (&s2)[4], float& ps1, float& ps2) {
;     f32x4 a1 = (f32x4){0.f, 0.f, 0.f, 0.f}, a2 = a1;
; #pragma unroll
;     for (int k4 = 0; k4 < 4; ++k4) {
; #pragma unroll
;         for (int j = 0; j < 4; ++j) { s1[k4][j] = fast_exp2(s1[k4][j]); s2[k4][j] = fast_exp2(s2[k4][j]); }
;         a1 = a1 + s1[k4]; a2 = a2 + s2[k4]; }
;     ps1 = (a1[0] + a1[1]) + (a1[2] + a1[3]); ps2 = (a2[0] + a2[1]) + (a2[2] + a2[3]);
; }
; DI void at_pv(AtState& S, const f32x4 (&s1)[4], const f32x4 (&s2)[4], float alpha, float ps1, float ps2, const LAS unsigned char* buf, int hh, int fq, int tq, int tp) {
;     S.l1 = S.l1 * alpha + ps1; S.l2 = S.l2 * alpha + ps2;
; #pragma unroll
;     for (int dt = 0; dt < 4; ++dt) { S.O1[dt] = S.O1[dt] * alpha; S.O2[dt] = S.O2[dt] * alpha; }
;     bf16x8 p1[2], p2[2];
; #pragma unroll
;     for (int s = 0; s < 2; ++s) { p1[s] = packp(s1[2 * s], s1[2 * s + 1]); p2[s] = packp(s2[2 * s], s2[2 * s + 1]); }
; template <int VAR>
; DI void attn_tile(AtState& S, const LAS unsigned char* buf, const bf16x8 q1, const bf16x8 q2, int kt, bool diag, int qpos0, int qpos_l, float slope2, float adv, float decay, int hh, int fr, int fq) {
;     ...
;             float lm = -1e30f;
; #pragma unroll
;             for (int k4 = 0; k4 < 4; ++k4)
; #pragma unroll
;                 for (int j = 0; j < 4; ++j) lm = fmaxf(lm, fmaxf(s1[k4][j], s2[k4][j]));
;             lm = fmaxf(lm, __shfl_xor(lm, 16)); lm = fmaxf(lm, __shfl_xor(lm, 32));
;             const float bump = fmaxf(lm, 0.f);
;             const float alpha = decay * fast_exp2(-bump); S.ref += bump;
; #pragma unroll
;             for (int k4 = 0; k4 < 4; ++k4) { s1[k4] = s1[k4] - bump; s2[k4] = s2[k4] - bump; S.cinit[k4] = S.cinit[k4] - bump; }
;             at_exp(s1, s2, ps1, ps2);
	v_mfma_f32_16x16x32_bf16 v[116:119], v[116:119], v[4:7], v[56:59]
	v_max_f32_e32 v125, v126, v125
	v_max3_f32 v3, v3, v124, v125
	v_max_f32_e32 v124, v114, v114
	s_waitcnt lgkmcnt(0)
	v_mfma_f32_16x16x32_bf16 v[120:123], v[120:123], v[8:11], v[56:59]
	v_max_f32_e32 v125, v110, v110
	v_max_f32_e32 v124, v125, v124
	v_max_f32_e32 v125, v115, v115
	v_max_f32_e32 v126, v111, v111
	v_max_f32_e32 v125, v126, v125
	v_max3_f32 v3, v3, v124, v125
	s_nop 1
	v_max_f32_e32 v124, v120, v120
	v_max_f32_e32 v125, v116, v116
	v_max_f32_e32 v124, v125, v124
	v_max_f32_e32 v125, v121, v121
	v_max_f32_e32 v126, v117, v117
	v_max_f32_e32 v125, v126, v125
	v_max3_f32 v3, v3, v124, v125
	v_max_f32_e32 v124, v122, v122
	v_max_f32_e32 v125, v118, v118
	v_max_f32_e32 v124, v125, v124
	v_max_f32_e32 v125, v123, v123
	v_max_f32_e32 v126, v119, v119
	v_max_f32_e32 v125, v126, v125
	v_max3_f32 v3, v3, v124, v125
	v_and_b32_e32 v125, 64, v198
	v_xor_b32_e32 v124, 16, v198
	v_add_u32_e32 v125, 64, v125
	v_cmp_lt_i32_e32 vcc, v124, v125
	s_nop 1
	v_cndmask_b32_e32 v124, v198, v124, vcc
	v_lshlrev_b32_e32 v124, 2, v124
	ds_bpermute_b32 v124, v124, v3
	s_waitcnt lgkmcnt(0)
	v_max_f32_e32 v124, v124, v124
	v_max_f32_e32 v3, v3, v124
	v_xor_b32_e32 v124, 32, v198
	v_cmp_lt_i32_e32 vcc, v124, v125
	s_nop 1
	v_cndmask_b32_e32 v124, v198, v124, vcc
	v_lshlrev_b32_e32 v124, 2, v124
	ds_bpermute_b32 v124, v124, v3
	s_waitcnt lgkmcnt(0)
	v_max3_f32 v124, v3, v124, 0
	v_sub_f32_e32 v126, v79, v124
	v_sub_f32_e32 v127, v78, v124
	v_sub_f32_e32 v128, v77, v124
	v_sub_f32_e32 v129, v76, v124
	v_sub_f32_e32 v130, v83, v124
	v_sub_f32_e32 v131, v82, v124
	v_sub_f32_e32 v132, v81, v124
	v_sub_f32_e32 v133, v80, v124
	v_sub_f32_e32 v134, v99, v124
	v_sub_f32_e32 v135, v98, v124
	v_sub_f32_e32 v137, v97, v124
	v_sub_f32_e32 v138, v96, v124
	v_sub_f32_e32 v139, v107, v124
	v_sub_f32_e32 v151, v106, v124
	v_sub_f32_e32 v158, v105, v124
	v_sub_f32_e32 v159, v104, v124
	v_exp_f32_e32 v216, v129
	v_exp_f32_e32 v220, v133
	v_exp_f32_e32 v217, v128
	v_exp_f32_e32 v221, v132
	v_exp_f32_e32 v218, v127
	v_exp_f32_e32 v222, v131
	v_exp_f32_e32 v219, v126
	v_exp_f32_e32 v223, v130
	v_sub_f32_e32 v237, v111, v124
	v_sub_f32_e32 v236, v110, v124
	v_sub_f32_e32 v233, v109, v124
	v_sub_f32_e32 v232, v108, v124
	v_sub_f32_e32 v239, v115, v124
	v_sub_f32_e32 v238, v114, v124
	v_sub_f32_e32 v235, v113, v124
	v_sub_f32_e32 v234, v112, v124
	v_exp_f32_e32 v224, v138
	v_exp_f32_e32 v226, v159
	v_exp_f32_e32 v225, v137
	v_exp_f32_e32 v227, v158
	v_exp_f32_e32 v228, v135
	v_exp_f32_e32 v230, v151
	v_exp_f32_e32 v229, v134
	v_exp_f32_e32 v231, v139
	v_sub_f32_e32 v119, v119, v124
	v_sub_f32_e32 v118, v118, v124
	v_sub_f32_e32 v117, v117, v124
	v_sub_f32_e32 v116, v116, v124
	v_sub_f32_e32 v123, v123, v124
	v_sub_f32_e32 v122, v122, v124
	v_sub_f32_e32 v121, v121, v124
	v_sub_f32_e32 v120, v120, v124
	v_exp_f32_e32 v232, v232
	v_exp_f32_e32 v234, v234
	v_exp_f32_e32 v233, v233
	v_exp_f32_e32 v235, v235
	v_exp_f32_e32 v236, v236
	v_exp_f32_e32 v238, v238
	v_exp_f32_e32 v237, v237
	v_exp_f32_e32 v239, v239
	v_exp_f32_e32 v240, v116
	v_exp_f32_e32 v242, v120
	v_exp_f32_e32 v241, v117
	v_exp_f32_e32 v243, v121
	v_exp_f32_e32 v244, v118
	v_exp_f32_e32 v246, v122
	v_exp_f32_e32 v245, v119
	v_exp_f32_e32 v247, v123
	v_pk_add_f32 v[108:109], v[216:217], 0 op_sel_hi:[1,0]
	v_pk_add_f32 v[110:111], v[218:219], 0 op_sel_hi:[1,0]
	v_pk_add_f32 v[112:113], v[220:221], 0 op_sel_hi:[1,0]
	v_pk_add_f32 v[114:115], v[222:223], 0 op_sel_hi:[1,0]
	v_pk_add_f32 v[110:111], v[228:229], v[110:111]
	v_pk_add_f32 v[108:109], v[224:225], v[108:109]
	v_pk_add_f32 v[114:115], v[230:231], v[114:115]
	v_pk_add_f32 v[112:113], v[226:227], v[112:113]
	v_pk_add_f32 v[108:109], v[232:233], v[108:109]
	v_pk_add_f32 v[110:111], v[236:237], v[110:111]
	v_pk_add_f32 v[112:113], v[234:235], v[112:113]
	v_pk_add_f32 v[114:115], v[238:239], v[114:115]
	v_pk_add_f32 v[110:111], v[244:245], v[110:111]
	v_pk_add_f32 v[108:109], v[240:241], v[108:109]
	v_pk_add_f32 v[114:115], v[246:247], v[114:115]
	v_pk_add_f32 v[112:113], v[242:243], v[112:113]
	v_cvt_pk_bf16_f32 v216, v216, v217
	v_cvt_pk_bf16_f32 v217, v218, v219
	v_cvt_pk_bf16_f32 v218, v224, v225
	v_cvt_pk_bf16_f32 v219, v228, v229
	v_cvt_pk_bf16_f32 v220, v220, v221
	v_cvt_pk_bf16_f32 v221, v222, v223
	v_cvt_pk_bf16_f32 v222, v226, v227
	v_cvt_pk_bf16_f32 v223, v230, v231
	v_cvt_pk_bf16_f32 v224, v232, v233
; #define LAS __attribute__((address_space(3)))
; #define MFMA16(a, b, c) __builtin_amdgcn_mfma_f32_16x16x32_bf16((a), (b), (c), 0, 0, 0)
; DI u32x2 tr4(const LAS unsigned char* p) { return __builtin_bit_cast(u32x2, __builtin_amdgcn_ds_read_tr16_b64_v4i16((LAS v4i16_t*)p)); }
; DI bf16x8 packp(f32x4 a, f32x4 b) { return __builtin_bit_cast(bf16x8, pack8(a, b)); }
; DI void at_pv(AtState& S, const f32x4 (&s1)[4], const f32x4 (&s2)[4], float alpha, float ps1, float ps2, const LAS unsigned char* buf, int hh, int fq, int tq, int tp) {
;     S.l1 = S.l1 * alpha + ps1; S.l2 = S.l2 * alpha + ps2;
; #pragma unroll
;     for (int dt = 0; dt < 4; ++dt) { S.O1[dt] = S.O1[dt] * alpha; S.O2[dt] = S.O2[dt] * alpha; }
;     bf16x8 p1[2], p2[2];
; #pragma unroll
;     for (int s = 0; s < 2; ++s) { p1[s] = packp(s1[2 * s], s1[2 * s + 1]); p2[s] = packp(s2[2 * s], s2[2 * s + 1]); }
; #pragma unroll
;     for (int dh = 0; dh < 2; ++dh) {
;         bf16x8 vt[2][2];
; #pragma unroll
;         for (int d2 = 0; d2 < 2; ++d2)
; #pragma unroll
;             for (int s = 0; s < 2; ++s) { const int dt = 2 * dh + d2; const LAS unsigned char* vr = buf + AT_V + (32 * s + 4 * fq + tq) * 288 + (hh * 64 + 16 * dt + 4 * tp) * 2; vt[d2][s] = cat44(tr4(vr), tr4(vr + 16 * 288)); }
;         __builtin_amdgcn_s_setprio(1);
; #pragma unroll
;         for (int s = 0; s < 2; ++s)
; #pragma unroll
;             for (int d2 = 0; d2 < 2; ++d2) { const int dt = 2 * dh + d2; S.O1[dt] = MFMA16(vt[d2][s], p1[s], S.O1[dt]); S.O2[dt] = MFMA16(vt[d2][s], p2[s], S.O2[dt]); }
;         __builtin_amdgcn_s_setprio(0);
;         __builtin_amdgcn_sched_barrier(0);
;     }
; }
	v_cvt_pk_bf16_f32 v225, v236, v237
	v_cvt_pk_bf16_f32 v226, v240, v241
	v_cvt_pk_bf16_f32 v227, v244, v245
	v_cvt_pk_bf16_f32 v228, v234, v235
	v_cvt_pk_bf16_f32 v229, v238, v239
	v_cvt_pk_bf16_f32 v230, v242, v243
	v_cvt_pk_bf16_f32 v231, v246, v247
	ds_read_b64_tr_b16 v[232:233], v208 offset:17408
	ds_read_b64_tr_b16 v[236:237], v208 offset:17440
	ds_read_b64_tr_b16 v[234:235], v208 offset:22016
	ds_read_b64_tr_b16 v[240:241], v208 offset:26624
	ds_read_b64_tr_b16 v[242:243], v208 offset:31232
	ds_read_b64_tr_b16 v[238:239], v208 offset:22048
	ds_read_b64_tr_b16 v[244:245], v208 offset:26656
	ds_read_b64_tr_b16 v[246:247], v208 offset:31264
	v_exp_f32_e64 v125, -v124
	v_mov_b32_e32 v116, v112
	v_mov_b32_e32 v117, v108
	v_mov_b32_e32 v108, v113
	v_mov_b32_e32 v112, v114
	v_mov_b32_e32 v113, v110
	v_mov_b32_e32 v110, v115
	v_pk_add_f32 v[108:109], v[116:117], v[108:109]
	v_pk_add_f32 v[110:111], v[112:113], v[110:111]
	v_mul_f32_e32 v136, v150, v125
	v_pk_add_f32 v[108:109], v[108:109], v[110:111]
	v_add_f32_e32 v3, v215, v124
	v_sub_f32_e32 v79, v47, v124
	v_sub_f32_e32 v78, v46, v124
	v_sub_f32_e32 v77, v45, v124
	v_sub_f32_e32 v76, v44, v124
	v_sub_f32_e32 v99, v51, v124
	v_sub_f32_e32 v98, v50, v124
	v_sub_f32_e32 v97, v49, v124
	v_sub_f32_e32 v96, v48, v124
	v_sub_f32_e32 v107, v55, v124
	v_sub_f32_e32 v106, v54, v124
	v_sub_f32_e32 v105, v53, v124
	v_sub_f32_e32 v104, v52, v124
	v_sub_f32_e32 v83, v59, v124
	v_sub_f32_e32 v82, v58, v124
	v_sub_f32_e32 v81, v57, v124
	v_sub_f32_e32 v80, v56, v124
	v_pk_fma_f32 v[158:159], v[156:157], v[136:137], v[108:109] op_sel_hi:[1,0,1]
	v_pk_mul_f32 v[110:111], v[66:67], v[136:137] op_sel_hi:[1,0]
	v_pk_mul_f32 v[108:109], v[64:65], v[136:137] op_sel_hi:[1,0]
	v_pk_mul_f32 v[114:115], v[74:75], v[136:137] op_sel_hi:[1,0]
	v_pk_mul_f32 v[112:113], v[72:73], v[136:137] op_sel_hi:[1,0]
	v_pk_mul_f32 v[118:119], v[62:63], v[136:137] op_sel_hi:[1,0]
	v_pk_mul_f32 v[116:117], v[60:61], v[136:137] op_sel_hi:[1,0]
	v_pk_mul_f32 v[122:123], v[70:71], v[136:137] op_sel_hi:[1,0]
	v_pk_mul_f32 v[120:121], v[68:69], v[136:137] op_sel_hi:[1,0]
	v_pk_mul_f32 v[126:127], v[90:91], v[136:137] op_sel_hi:[1,0]
	v_pk_mul_f32 v[124:125], v[88:89], v[136:137] op_sel_hi:[1,0]
	v_pk_mul_f32 v[130:131], v[102:103], v[136:137] op_sel_hi:[1,0]
	v_pk_mul_f32 v[128:129], v[100:101], v[136:137] op_sel_hi:[1,0]
	v_pk_mul_f32 v[134:135], v[86:87], v[136:137] op_sel_hi:[1,0]
	v_pk_mul_f32 v[132:133], v[84:85], v[136:137] op_sel_hi:[1,0]
	v_pk_mul_f32 v[138:139], v[94:95], v[136:137] op_sel_hi:[1,0]
	v_pk_mul_f32 v[136:137], v[92:93], v[136:137] op_sel_hi:[1,0]
	s_setprio 1
	s_waitcnt lgkmcnt(5)
	v_mfma_f32_16x16x32_bf16 v[108:111], v[232:235], v[216:219], v[108:111]
	v_mfma_f32_16x16x32_bf16 v[112:115], v[232:235], v[220:223], v[112:115]
	s_waitcnt lgkmcnt(2)
	v_mfma_f32_16x16x32_bf16 v[232:235], v[236:239], v[216:219], v[116:119]
	v_mfma_f32_16x16x32_bf16 v[236:239], v[236:239], v[220:223], v[120:123]
	v_mfma_f32_16x16x32_bf16 v[120:123], v[240:243], v[224:227], v[108:111]
	v_mfma_f32_16x16x32_bf16 v[116:119], v[240:243], v[228:231], v[112:115]
	s_waitcnt lgkmcnt(0)
	v_mfma_f32_16x16x32_bf16 v[112:115], v[244:247], v[224:227], v[232:235]
	v_mfma_f32_16x16x32_bf16 v[108:111], v[244:247], v[228:231], v[236:239]
	s_setprio 0
	s_nop 0
	ds_read_b64_tr_b16 v[232:233], v208 offset:17472
	ds_read_b64_tr_b16 v[236:237], v208 offset:17504
	ds_read_b64_tr_b16 v[234:235], v208 offset:22080
	ds_read_b64_tr_b16 v[238:239], v208 offset:22112
	ds_read_b64_tr_b16 v[240:241], v208 offset:26688
	ds_read_b64_tr_b16 v[242:243], v208 offset:31296
	ds_read_b64_tr_b16 v[246:247], v208 offset:31328
	ds_read_b64_tr_b16 v[244:245], v208 offset:26720
	s_setprio 1
	s_waitcnt lgkmcnt(5)
	v_mfma_f32_16x16x32_bf16 v[124:127], v[232:235], v[216:219], v[124:127]
	v_mfma_f32_16x16x32_bf16 v[128:131], v[232:235], v[220:223], v[128:131]
	s_waitcnt lgkmcnt(4)
	v_mfma_f32_16x16x32_bf16 v[216:219], v[236:239], v[216:219], v[132:135]
	v_mfma_f32_16x16x32_bf16 v[220:223], v[236:239], v[220:223], v[136:139]
	s_waitcnt lgkmcnt(2)
	v_mfma_f32_16x16x32_bf16 v[136:139], v[240:243], v[224:227], v[124:127]
	v_mfma_f32_16x16x32_bf16 v[132:135], v[240:243], v[228:231], v[128:131]
	s_waitcnt lgkmcnt(0)
	v_mfma_f32_16x16x32_bf16 v[128:131], v[244:247], v[224:227], v[216:219]
	v_mfma_f32_16x16x32_bf16 v[124:127], v[244:247], v[228:231], v[220:223]
	s_setprio 0
	s_cbranch_execnz .LBB0_1380

; DI void lds_barrier() { asm volatile("s_waitcnt lgkmcnt(0)" ::: "memory"); __builtin_amdgcn_s_barrier(); asm volatile("" ::: "memory"); }
; template <int VAR>
; DI void attn_tile(AtState& S, const LAS unsigned char* buf, const bf16x8 q1, const bf16x8 q2, int kt, bool diag, int qpos0, int qpos_l, float slope2, float adv, float decay, int hh, int fr, int fq) {
;     ...
;         asm volatile("; attention: fast tile" ::: "memory");
;         at_qk(s1, s2, buf, q1, q2, S.cinit, hh, fr, fq);
;         S.ref += adv;
;         at_exp(s1, s2, ps1, ps2);
;         if (__any(!(ps1 + ps2 < 0x1p60f))) {
;             asm volatile("; attention: bump" ::: "memory");
;             at_qk(s1, s2, buf, q1, q2, S.cinit, hh, fr, fq);
;             float lm = -1e30f;
; #pragma unroll
;             for (int k4 = 0; k4 < 4; ++k4)
; #pragma unroll
;                 for (int j = 0; j < 4; ++j) lm = fmaxf(lm, fmaxf(s1[k4][j], s2[k4][j]));
; template <int VAR>
; DI void attn_segment(const Args& a, const Frame& F, int l, int qrow0, int qpos0, int hp, int ntile, int nf32, const float* ck, const float* cv, int prow0) {
;     ...
;             atb_commit(ra, F.lds + ((kt + 1) & 1) * AT_BUF, tid);
;             lds_barrier();
;             if (kt + 1 >= ntile) break;
;             atb_issue(ra, pb + (size_t)(kt + 3 < nl ? kt + 3 : nl) * TSTR, voff);
;             attn_tile<VAR>(S, F.lds + ((kt + 1) & 1) * AT_BUF, q1, q2, kt + 1, kt + 2 == ntile, qpos0, qpos_l, slope2, adv, decay, hh, fr, fq);
.LBB0_1385:
	s_waitcnt vmcnt(4)
	ds_write_b128 v143, v[12:15] offset:35840
	ds_write_b128 v202, v[16:19] offset:53248
	ds_write_b128 v203, v[20:23] offset:35840
	ds_write_b128 v204, v[24:27] offset:53248
	s_waitcnt lgkmcnt(0)
	s_barrier
	s_add_i32 s14, s26, -2
	s_cmp_ge_i32 s14, s24
	s_mov_b64 s[14:15], -1
	s_cbranch_scc1 .LBB0_1375
	s_min_i32 s14, s26, s25
	s_ashr_i32 s15, s14, 31
	s_lshl_b64 s[14:15], s[14:15], 18
	s_add_u32 s14, s0, s14
	s_addc_u32 s15, s1, s15
	v_lshl_add_u64 v[16:17], s[14:15], 0, v[144:145]
	v_lshl_add_u64 v[24:25], s[14:15], 0, v[146:147]
	global_load_dwordx4 v[12:15], v[16:17], off offset:1024
	s_nop 0
	global_load_dwordx4 v[16:19], v[16:17], off offset:1536
	s_nop 0
	global_load_dwordx4 v[20:23], v[24:25], off offset:1024
	s_nop 0
	global_load_dwordx4 v[24:27], v[24:25], off offset:1536
	s_cmpk_lg_i32 s28, 0x41
	s_mov_b64 s[14:15], -1
	s_cbranch_scc0 .LBB0_1391
	ds_read_b128 v[44:47], v213 offset:35840
	ds_read_b128 v[48:51], v213 offset:35904
	ds_read_b128 v[52:55], v213 offset:40192
	ds_read_b128 v[56:59], v213 offset:40256
	ds_read_b128 v[60:63], v213 offset:44544
	ds_read_b128 v[64:67], v213 offset:44608
	ds_read_b128 v[68:71], v213 offset:48896
	ds_read_b128 v[72:75], v213 offset:48960
	s_waitcnt lgkmcnt(7)
	v_mfma_f32_16x16x32_bf16 v[44:47], v[44:47], v[4:7], v[76:79]
	v_add_f32_e32 v215, v205, v3
	s_waitcnt lgkmcnt(6)
	v_mfma_f32_16x16x32_bf16 v[48:51], v[48:51], v[8:11], v[76:79]
	s_waitcnt lgkmcnt(5)
	v_mfma_f32_16x16x32_bf16 v[52:55], v[52:55], v[4:7], v[96:99]
	s_nop 2
	v_exp_f32_e32 v164, v44
	v_exp_f32_e32 v165, v45
	v_exp_f32_e32 v168, v46
	s_waitcnt lgkmcnt(4)
	v_mfma_f32_16x16x32_bf16 v[56:59], v[56:59], v[8:11], v[96:99]
	v_exp_f32_e32 v169, v47
	v_exp_f32_e32 v162, v48
	v_exp_f32_e32 v163, v49
	s_waitcnt lgkmcnt(3)
	v_mfma_f32_16x16x32_bf16 v[60:63], v[60:63], v[4:7], v[104:107]
	v_exp_f32_e32 v166, v50
	v_exp_f32_e32 v167, v51
	v_exp_f32_e32 v172, v52
	s_waitcnt lgkmcnt(2)
	v_mfma_f32_16x16x32_bf16 v[44:47], v[64:67], v[8:11], v[104:107]
	v_exp_f32_e32 v170, v56
	v_exp_f32_e32 v173, v53
	v_exp_f32_e32 v176, v54
	s_waitcnt lgkmcnt(1)
	v_mfma_f32_16x16x32_bf16 v[48:51], v[68:71], v[4:7], v[80:83]
	v_exp_f32_e32 v177, v55
	v_exp_f32_e32 v174, v58
	v_exp_f32_e32 v175, v59
	s_waitcnt lgkmcnt(0)
	v_mfma_f32_16x16x32_bf16 v[64:67], v[72:75], v[8:11], v[80:83]
	v_exp_f32_e32 v171, v57
	v_exp_f32_e32 v180, v60
	v_exp_f32_e32 v178, v44
	v_exp_f32_e32 v181, v61
	v_exp_f32_e32 v179, v45
	v_exp_f32_e32 v184, v62
	v_exp_f32_e32 v185, v63
	v_exp_f32_e32 v182, v46
	v_exp_f32_e32 v183, v47
	v_exp_f32_e32 v188, v48
	v_exp_f32_e32 v186, v64
	v_exp_f32_e32 v189, v49
	v_exp_f32_e32 v192, v50
	v_exp_f32_e32 v193, v51
	v_exp_f32_e32 v190, v66
	v_exp_f32_e32 v191, v67
	v_exp_f32_e32 v187, v65
	v_pk_add_f32 v[84:85], v[164:165], 0 op_sel_hi:[1,0]
	v_pk_add_f32 v[86:87], v[168:169], 0 op_sel_hi:[1,0]
	v_pk_add_f32 v[68:69], v[162:163], 0 op_sel_hi:[1,0]
	v_pk_add_f32 v[70:71], v[166:167], 0 op_sel_hi:[1,0]
	v_pk_add_f32 v[52:53], v[86:87], v[176:177]
	v_pk_add_f32 v[54:55], v[84:85], v[172:173]
	v_pk_add_f32 v[56:57], v[70:71], v[174:175]
	v_pk_add_f32 v[58:59], v[68:69], v[170:171]
	v_pk_add_f32 v[44:45], v[54:55], v[180:181]
	v_pk_add_f32 v[46:47], v[52:53], v[184:185]
	v_pk_add_f32 v[52:53], v[58:59], v[178:179]
	v_pk_add_f32 v[54:55], v[56:57], v[182:183]
	v_pk_add_f32 v[46:47], v[46:47], v[192:193]
	v_pk_add_f32 v[44:45], v[44:45], v[188:189]
	v_pk_add_f32 v[48:49], v[54:55], v[190:191]
	v_pk_add_f32 v[50:51], v[52:53], v[186:187]
	v_mov_b32_e32 v53, v44
	v_mov_b32_e32 v52, v50
	v_mov_b32_e32 v44, v51
	v_mov_b32_e32 v50, v48
	v_mov_b32_e32 v51, v46
	v_mov_b32_e32 v46, v49
	v_pk_add_f32 v[44:45], v[52:53], v[44:45]
	v_pk_add_f32 v[46:47], v[50:51], v[46:47]
	s_nop 0
	v_pk_add_f32 v[194:195], v[44:45], v[46:47]
	s_nop 0
	v_add_f32_e32 v44, v195, v194
	v_cmp_ngt_f32_e32 vcc, s65, v44
	s_cbranch_vccz .LBB0_1395
	ds_read_b128 v[44:47], v213 offset:35840
	ds_read_b128 v[48:51], v213 offset:35904
	ds_read_b128 v[52:55], v213 offset:40192
	ds_read_b128 v[56:59], v213 offset:40256
	ds_read_b128 v[60:63], v213 offset:44544
	ds_read_b128 v[64:67], v213 offset:44608
	ds_read_b128 v[68:71], v213 offset:48896
	ds_read_b128 v[72:75], v213 offset:48960
	s_waitcnt lgkmcnt(7)
	v_mfma_f32_16x16x32_bf16 v[44:47], v[44:47], v[4:7], v[76:79]
	s_waitcnt lgkmcnt(6)
	v_mfma_f32_16x16x32_bf16 v[48:51], v[48:51], v[8:11], v[76:79]
	s_nop 5
	v_max_f32_e32 v85, v44, v44
	v_max_f32_e32 v86, v45, v45
	v_max_f32_e32 v87, v47, v47
	s_waitcnt lgkmcnt(5)
	v_mfma_f32_16x16x32_bf16 v[52:55], v[52:55], v[4:7], v[96:99]
	s_waitcnt lgkmcnt(4)
	v_mfma_f32_16x16x32_bf16 v[56:59], v[56:59], v[8:11], v[96:99]
	v_max_f32_e32 v84, v48, v48
	v_max_f32_e32 v84, v85, v84
	v_max_f32_e32 v85, v49, v49
	v_max_f32_e32 v85, v86, v85
	v_max3_f32 v84, v84, s60, v85
	v_max_f32_e32 v85, v50, v50
	v_max_f32_e32 v86, v46, v46
	v_max_f32_e32 v85, v86, v85
	v_max_f32_e32 v86, v51, v51
	v_max_f32_e32 v86, v87, v86
	v_max3_f32 v84, v84, v85, v86
	v_max_f32_e32 v85, v56, v56
	v_max_f32_e32 v86, v52, v52
	v_max_f32_e32 v85, v86, v85
	v_max_f32_e32 v86, v57, v57
	v_max_f32_e32 v87, v53, v53
	s_waitcnt lgkmcnt(3)
	v_mfma_f32_16x16x32_bf16 v[60:63], v[60:63], v[4:7], v[104:107]
	v_max_f32_e32 v86, v87, v86
	v_max3_f32 v84, v84, v85, v86
	v_max_f32_e32 v85, v58, v58
	s_waitcnt lgkmcnt(2)
	v_mfma_f32_16x16x32_bf16 v[64:67], v[64:67], v[8:11], v[104:107]
	v_max_f32_e32 v86, v54, v54
	v_max_f32_e32 v85, v86, v85
	v_max_f32_e32 v86, v59, v59
	v_max_f32_e32 v87, v55, v55
	v_max_f32_e32 v86, v87, v86
	v_max3_f32 v84, v84, v85, v86
	s_nop 1
	v_max_f32_e32 v85, v64, v64
	v_max_f32_e32 v86, v60, v60
	v_max_f32_e32 v85, v86, v85
	v_max_f32_e32 v86, v65, v65
	v_max_f32_e32 v87, v61, v61
	s_waitcnt lgkmcnt(1)
; #define LAS __attribute__((address_space(3)))
; DI float fast_exp2(float x) { return __builtin_amdgcn_exp2f(x); }
; DI u32x2 tr4(const LAS unsigned char* p) { return __builtin_bit_cast(u32x2, __builtin_amdgcn_ds_read_tr16_b64_v4i16((LAS v4i16_t*)p)); }
; DI bf16x8 packp(f32x4 a, f32x4 b) { return __builtin_bit_cast(bf16x8, pack8(a, b)); }
; DI void at_pv(AtState& S, const f32x4 (&s1)[4], const f32x4 (&s2)[4], float alpha, float ps1, float ps2, const LAS unsigned char* buf, int hh, int fq, int tq, int tp) {
;     S.l1 = S.l1 * alpha + ps1; S.l2 = S.l2 * alpha + ps2;
; #pragma unroll
;     for (int dt = 0; dt < 4; ++dt) { S.O1[dt] = S.O1[dt] * alpha; S.O2[dt] = S.O2[dt] * alpha; }
;     bf16x8 p1[2], p2[2];
; #pragma unroll
;     for (int s = 0; s < 2; ++s) { p1[s] = packp(s1[2 * s], s1[2 * s + 1]); p2[s] = packp(s2[2 * s], s2[2 * s + 1]); }
; #pragma unroll
;     for (int dh = 0; dh < 2; ++dh) {
;         bf16x8 vt[2][2];
; #pragma unroll
;         for (int d2 = 0; d2 < 2; ++d2)
; #pragma unroll
;             for (int s = 0; s < 2; ++s) { const int dt = 2 * dh + d2; const LAS unsigned char* vr = buf + AT_V + (32 * s + 4 * fq + tq) * 288 + (hh * 64 + 16 * dt + 4 * tp) * 2; vt[d2][s] = cat44(tr4(vr), tr4(vr + 16 * 288)); }
; template <int VAR>
; DI void attn_tile(AtState& S, const LAS unsigned char* buf, const bf16x8 q1, const bf16x8 q2, int kt, bool diag, int qpos0, int qpos_l, float slope2, float adv, float decay, int hh, int fr, int fq) {
;     ...
;             float lm = -1e30f;
; #pragma unroll
;             for (int k4 = 0; k4 < 4; ++k4)
; #pragma unroll
;                 for (int j = 0; j < 4; ++j) lm = fmaxf(lm, fmaxf(s1[k4][j], s2[k4][j]));
;             lm = fmaxf(lm, __shfl_xor(lm, 16)); lm = fmaxf(lm, __shfl_xor(lm, 32));
;             const float bump = fmaxf(lm, 0.f);
;             const float alpha = decay * fast_exp2(-bump); S.ref += bump;
; #pragma unroll
;             for (int k4 = 0; k4 < 4; ++k4) { s1[k4] = s1[k4] - bump; s2[k4] = s2[k4] - bump; S.cinit[k4] = S.cinit[k4] - bump; }
;             at_exp(s1, s2, ps1, ps2);
;             at_pv(S, s1, s2, alpha, ps1, ps2, buf, hh, fq, tq, tp);
	v_mfma_f32_16x16x32_bf16 v[68:71], v[68:71], v[4:7], v[80:83]
	v_max_f32_e32 v86, v87, v86
	v_max3_f32 v84, v84, v85, v86
	v_max_f32_e32 v85, v66, v66
	s_waitcnt lgkmcnt(0)
	v_mfma_f32_16x16x32_bf16 v[72:75], v[72:75], v[8:11], v[80:83]
	v_max_f32_e32 v86, v62, v62
	v_max_f32_e32 v85, v86, v85
	v_max_f32_e32 v86, v67, v67
	v_max_f32_e32 v87, v63, v63
	v_max_f32_e32 v86, v87, v86
	v_max3_f32 v84, v84, v85, v86
	s_nop 1
	v_max_f32_e32 v85, v72, v72
	v_max_f32_e32 v86, v68, v68
	v_max_f32_e32 v85, v86, v85
	v_max_f32_e32 v86, v73, v73
	v_max_f32_e32 v87, v69, v69
	v_max_f32_e32 v86, v87, v86
	v_max3_f32 v84, v84, v85, v86
	v_max_f32_e32 v85, v74, v74
	v_max_f32_e32 v86, v70, v70
	v_max_f32_e32 v85, v86, v85
	v_max_f32_e32 v86, v75, v75
	v_max_f32_e32 v87, v71, v71
	v_max_f32_e32 v86, v87, v86
	v_max3_f32 v84, v84, v85, v86
	v_and_b32_e32 v86, 64, v198
	v_xor_b32_e32 v85, 16, v198
	v_add_u32_e32 v86, 64, v86
	v_cmp_lt_i32_e32 vcc, v85, v86
	s_nop 1
	v_cndmask_b32_e32 v85, v198, v85, vcc
	v_lshlrev_b32_e32 v85, 2, v85
	ds_bpermute_b32 v85, v85, v84
	s_waitcnt lgkmcnt(0)
	v_max_f32_e32 v85, v85, v85
	v_max_f32_e32 v84, v84, v85
	v_xor_b32_e32 v85, 32, v198
	v_cmp_lt_i32_e32 vcc, v85, v86
	s_nop 1
	v_cndmask_b32_e32 v85, v198, v85, vcc
	v_lshlrev_b32_e32 v85, 2, v85
	ds_bpermute_b32 v85, v85, v84
	s_waitcnt lgkmcnt(0)
	v_max3_f32 v84, v84, v85, 0
	v_sub_f32_e32 v86, v47, v84
	v_sub_f32_e32 v87, v46, v84
	v_sub_f32_e32 v88, v45, v84
	v_sub_f32_e32 v89, v44, v84
	v_sub_f32_e32 v90, v51, v84
	v_sub_f32_e32 v91, v50, v84
	v_sub_f32_e32 v92, v49, v84
	v_sub_f32_e32 v93, v48, v84
	v_sub_f32_e32 v94, v55, v84
	v_sub_f32_e32 v95, v54, v84
	v_sub_f32_e32 v101, v53, v84
	v_sub_f32_e32 v102, v52, v84
	v_sub_f32_e32 v103, v59, v84
	v_sub_f32_e32 v151, v58, v84
	v_sub_f32_e32 v156, v57, v84
	v_sub_f32_e32 v157, v56, v84
	v_exp_f32_e32 v216, v89
	v_exp_f32_e32 v220, v93
	v_exp_f32_e32 v217, v88
	v_exp_f32_e32 v221, v92
	v_exp_f32_e32 v218, v87
	v_exp_f32_e32 v222, v91
	v_exp_f32_e32 v219, v86
	v_exp_f32_e32 v223, v90
	v_sub_f32_e32 v237, v63, v84
	v_sub_f32_e32 v236, v62, v84
	v_sub_f32_e32 v233, v61, v84
	v_sub_f32_e32 v232, v60, v84
	v_sub_f32_e32 v239, v67, v84
	v_sub_f32_e32 v238, v66, v84
	v_sub_f32_e32 v235, v65, v84
	v_sub_f32_e32 v234, v64, v84
	v_exp_f32_e32 v224, v102
	v_exp_f32_e32 v226, v157
	v_exp_f32_e32 v225, v101
	v_exp_f32_e32 v227, v156
	v_exp_f32_e32 v228, v95
	v_exp_f32_e32 v230, v151
	v_exp_f32_e32 v229, v94
	v_exp_f32_e32 v231, v103
	v_sub_f32_e32 v71, v71, v84
	v_sub_f32_e32 v70, v70, v84
	v_sub_f32_e32 v69, v69, v84
	v_sub_f32_e32 v68, v68, v84
	v_sub_f32_e32 v75, v75, v84
	v_sub_f32_e32 v74, v74, v84
	v_sub_f32_e32 v73, v73, v84
	v_sub_f32_e32 v72, v72, v84
	v_exp_f32_e32 v232, v232
	v_exp_f32_e32 v234, v234
	v_exp_f32_e32 v233, v233
	v_exp_f32_e32 v235, v235
	v_exp_f32_e32 v236, v236
	v_exp_f32_e32 v238, v238
	v_exp_f32_e32 v237, v237
	v_exp_f32_e32 v239, v239
	v_exp_f32_e32 v240, v68
	v_exp_f32_e32 v242, v72
	v_exp_f32_e32 v241, v69
	v_exp_f32_e32 v243, v73
	v_exp_f32_e32 v244, v70
	v_exp_f32_e32 v246, v74
	v_exp_f32_e32 v245, v71
	v_exp_f32_e32 v247, v75
	v_pk_add_f32 v[60:61], v[216:217], 0 op_sel_hi:[1,0]
	v_pk_add_f32 v[62:63], v[218:219], 0 op_sel_hi:[1,0]
	v_pk_add_f32 v[64:65], v[220:221], 0 op_sel_hi:[1,0]
	v_pk_add_f32 v[66:67], v[222:223], 0 op_sel_hi:[1,0]
	v_pk_add_f32 v[62:63], v[228:229], v[62:63]
	v_pk_add_f32 v[60:61], v[224:225], v[60:61]
	v_pk_add_f32 v[66:67], v[230:231], v[66:67]
	v_pk_add_f32 v[64:65], v[226:227], v[64:65]
	v_pk_add_f32 v[60:61], v[232:233], v[60:61]
	v_pk_add_f32 v[62:63], v[236:237], v[62:63]
	v_pk_add_f32 v[64:65], v[234:235], v[64:65]
	v_pk_add_f32 v[66:67], v[238:239], v[66:67]
	v_pk_add_f32 v[62:63], v[244:245], v[62:63]
	v_pk_add_f32 v[60:61], v[240:241], v[60:61]
	v_pk_add_f32 v[66:67], v[246:247], v[66:67]
	v_pk_add_f32 v[64:65], v[242:243], v[64:65]
	v_cvt_pk_bf16_f32 v216, v216, v217
	v_cvt_pk_bf16_f32 v217, v218, v219
	v_cvt_pk_bf16_f32 v218, v224, v225
	v_cvt_pk_bf16_f32 v219, v228, v229
	v_cvt_pk_bf16_f32 v220, v220, v221
	v_cvt_pk_bf16_f32 v221, v222, v223
	v_cvt_pk_bf16_f32 v222, v226, v227
	v_cvt_pk_bf16_f32 v223, v230, v231
	v_cvt_pk_bf16_f32 v224, v232, v233
	v_cvt_pk_bf16_f32 v225, v236, v237
	v_cvt_pk_bf16_f32 v226, v240, v241
	v_cvt_pk_bf16_f32 v227, v244, v245
	v_cvt_pk_bf16_f32 v228, v234, v235
	v_cvt_pk_bf16_f32 v229, v238, v239
	v_cvt_pk_bf16_f32 v230, v242, v243
	v_cvt_pk_bf16_f32 v231, v246, v247
	ds_read_b64_tr_b16 v[232:233], v208 offset:53248
	ds_read_b64_tr_b16 v[236:237], v208 offset:53280
	ds_read_b64_tr_b16 v[234:235], v208 offset:57856
	ds_read_b64_tr_b16 v[240:241], v208 offset:62464
	ds_read_b64_tr_b16 v[242:243], v209 offset:4608
	ds_read_b64_tr_b16 v[238:239], v208 offset:57888
	ds_read_b64_tr_b16 v[244:245], v208 offset:62496
	ds_read_b64_tr_b16 v[246:247], v210 offset:4608
	v_exp_f32_e64 v85, -v84
	v_mov_b32_e32 v68, v64
	v_mov_b32_e32 v69, v60
	v_mov_b32_e32 v60, v65
	v_mov_b32_e32 v64, v66
	v_mov_b32_e32 v65, v62
	v_mov_b32_e32 v62, v67
	v_pk_add_f32 v[60:61], v[68:69], v[60:61]
	v_pk_add_f32 v[62:63], v[64:65], v[62:63]
	v_mul_f32_e32 v100, v150, v85
	v_pk_add_f32 v[60:61], v[60:61], v[62:63]
	v_add_f32_e32 v214, v215, v84
	v_sub_f32_e32 v47, v79, v84
	v_sub_f32_e32 v46, v78, v84
	v_sub_f32_e32 v45, v77, v84
	v_sub_f32_e32 v44, v76, v84
	v_sub_f32_e32 v51, v99, v84
	v_sub_f32_e32 v50, v98, v84
	v_sub_f32_e32 v49, v97, v84
	v_sub_f32_e32 v48, v96, v84
	v_sub_f32_e32 v55, v107, v84
	v_sub_f32_e32 v54, v106, v84
	v_sub_f32_e32 v53, v105, v84
	v_sub_f32_e32 v52, v104, v84
	v_sub_f32_e32 v59, v83, v84
	v_sub_f32_e32 v58, v82, v84
	v_sub_f32_e32 v57, v81, v84
	v_sub_f32_e32 v56, v80, v84
	v_pk_fma_f32 v[156:157], v[158:159], v[100:101], v[60:61] op_sel_hi:[1,0,1]
	v_pk_mul_f32 v[62:63], v[122:123], v[100:101] op_sel_hi:[1,0]
	v_pk_mul_f32 v[60:61], v[120:121], v[100:101] op_sel_hi:[1,0]
	v_pk_mul_f32 v[66:67], v[118:119], v[100:101] op_sel_hi:[1,0]
	v_pk_mul_f32 v[64:65], v[116:117], v[100:101] op_sel_hi:[1,0]
	v_pk_mul_f32 v[70:71], v[114:115], v[100:101] op_sel_hi:[1,0]
	v_pk_mul_f32 v[68:69], v[112:113], v[100:101] op_sel_hi:[1,0]
	v_pk_mul_f32 v[74:75], v[110:111], v[100:101] op_sel_hi:[1,0]
	v_pk_mul_f32 v[72:73], v[108:109], v[100:101] op_sel_hi:[1,0]
	v_pk_mul_f32 v[86:87], v[138:139], v[100:101] op_sel_hi:[1,0]
	v_pk_mul_f32 v[84:85], v[136:137], v[100:101] op_sel_hi:[1,0]
	v_pk_mul_f32 v[90:91], v[134:135], v[100:101] op_sel_hi:[1,0]
	v_pk_mul_f32 v[88:89], v[132:133], v[100:101] op_sel_hi:[1,0]
	v_pk_mul_f32 v[94:95], v[130:131], v[100:101] op_sel_hi:[1,0]
	v_pk_mul_f32 v[92:93], v[128:129], v[100:101] op_sel_hi:[1,0]
	v_pk_mul_f32 v[102:103], v[126:127], v[100:101] op_sel_hi:[1,0]
	v_pk_mul_f32 v[100:101], v[124:125], v[100:101] op_sel_hi:[1,0]
	s_setprio 1
	s_waitcnt lgkmcnt(5)
; #define LAS __attribute__((address_space(3)))
; #define MFMA16(a, b, c) __builtin_amdgcn_mfma_f32_16x16x32_bf16((a), (b), (c), 0, 0, 0)
; DI u32x2 tr4(const LAS unsigned char* p) { return __builtin_bit_cast(u32x2, __builtin_amdgcn_ds_read_tr16_b64_v4i16((LAS v4i16_t*)p)); }
; DI void at_pv(AtState& S, const f32x4 (&s1)[4], const f32x4 (&s2)[4], float alpha, float ps1, float ps2, const LAS unsigned char* buf, int hh, int fq, int tq, int tp) {
;     ...
;     for (int dh = 0; dh < 2; ++dh) {
;         bf16x8 vt[2][2];
; #pragma unroll
;         for (int d2 = 0; d2 < 2; ++d2)
; #pragma unroll
;             for (int s = 0; s < 2; ++s) { const int dt = 2 * dh + d2; const LAS unsigned char* vr = buf + AT_V + (32 * s + 4 * fq + tq) * 288 + (hh * 64 + 16 * dt + 4 * tp) * 2; vt[d2][s] = cat44(tr4(vr), tr4(vr + 16 * 288)); }
;         __builtin_amdgcn_s_setprio(1);
; #pragma unroll
;         for (int s = 0; s < 2; ++s)
; #pragma unroll
;             for (int d2 = 0; d2 < 2; ++d2) { const int dt = 2 * dh + d2; S.O1[dt] = MFMA16(vt[d2][s], p1[s], S.O1[dt]); S.O2[dt] = MFMA16(vt[d2][s], p2[s], S.O2[dt]); }
;         __builtin_amdgcn_s_setprio(0);
;         __builtin_amdgcn_sched_barrier(0);
;     }
	v_mfma_f32_16x16x32_bf16 v[60:63], v[232:235], v[216:219], v[60:63]
	v_mfma_f32_16x16x32_bf16 v[232:235], v[232:235], v[220:223], v[64:67]
	s_waitcnt lgkmcnt(2)
	v_mfma_f32_16x16x32_bf16 v[68:71], v[236:239], v[216:219], v[68:71]
	v_mfma_f32_16x16x32_bf16 v[236:239], v[236:239], v[220:223], v[72:75]
	v_mfma_f32_16x16x32_bf16 v[64:67], v[240:243], v[224:227], v[60:63]
	v_mfma_f32_16x16x32_bf16 v[72:75], v[240:243], v[228:231], v[232:235]
	s_waitcnt lgkmcnt(0)
	v_mfma_f32_16x16x32_bf16 v[60:63], v[244:247], v[224:227], v[68:71]
	v_mfma_f32_16x16x32_bf16 v[68:71], v[244:247], v[228:231], v[236:239]
	s_setprio 0
	ds_read_b64_tr_b16 v[232:233], v208 offset:53312
	s_nop 0
	ds_read_b64_tr_b16 v[236:237], v208 offset:53344
	ds_read_b64_tr_b16 v[234:235], v208 offset:57920
	ds_read_b64_tr_b16 v[238:239], v208 offset:57952
	ds_read_b64_tr_b16 v[240:241], v208 offset:62528
	ds_read_b64_tr_b16 v[242:243], v211 offset:4608
	ds_read_b64_tr_b16 v[246:247], v212 offset:4608
	ds_read_b64_tr_b16 v[244:245], v208 offset:62560
	s_setprio 1
	s_waitcnt lgkmcnt(5)
	v_mfma_f32_16x16x32_bf16 v[84:87], v[232:235], v[216:219], v[84:87]
	v_mfma_f32_16x16x32_bf16 v[232:235], v[232:235], v[220:223], v[88:91]
	s_waitcnt lgkmcnt(4)
	v_mfma_f32_16x16x32_bf16 v[92:95], v[236:239], v[216:219], v[92:95]
	v_mfma_f32_16x16x32_bf16 v[216:219], v[236:239], v[220:223], v[100:103]
	s_waitcnt lgkmcnt(2)
	v_mfma_f32_16x16x32_bf16 v[88:91], v[240:243], v[224:227], v[84:87]
	v_mfma_f32_16x16x32_bf16 v[100:103], v[240:243], v[228:231], v[232:235]
	s_waitcnt lgkmcnt(0)
	v_mfma_f32_16x16x32_bf16 v[84:87], v[244:247], v[224:227], v[92:95]
	v_mfma_f32_16x16x32_bf16 v[92:95], v[244:247], v[228:231], v[216:219]
	s_setprio 0
	s_cbranch_execnz .LBB0_1390

; #define PG8_STAGE(bufoff, gbase, voff) do { _Pragma("unroll") for (int _i = 0; _i < 2; ++_i) \
;         __builtin_amdgcn_global_load_lds((const unsigned*)((const char*)(gbase) + (voff)[_i]), (LAS unsigned*)(lds + (bufoff) + ldsw + _i * 8192), 16, 0, 0); } while (0)
; #define PG8_LDA(dst, b, h) do { _Pragma("unroll") for (int m = 0; m < 4; ++m) _Pragma("unroll") for (int k = 0; k < 2; ++k) dst[m][k] = *(const LAS bf16x8*)(lds + PG8_SA(b, h) + aoff + m * 2048 + k * 1024); } while (0)
; #define PG8_LDB(dst, b, h) do { _Pragma("unroll") for (int n = 0; n < 2; ++n) _Pragma("unroll") for (int k = 0; k < 2; ++k) dst[n][k] = *(const LAS bf16x8*)(lds + PG8_SB(b, h) + boff + n * 2048 + k * 1024); } while (0)
; #define PG8_MMA(ai, bj, At, Bt) do { __builtin_amdgcn_s_setprio(1); _Pragma("unroll") for (int m = 0; m < 4; ++m) _Pragma("unroll") for (int n = 0; n < 2; ++n) _Pragma("unroll") for (int k = 0; k < 2; ++k) \
;         acc[ai][bj][m][n] = __builtin_amdgcn_mfma_f32_16x16x32_bf16(Bt[n][k], At[m][k], acc[ai][bj][m][n], 0, 0, 0); __builtin_amdgcn_s_setprio(0); } while (0)
; #define PG8_WAIT_V(n) asm volatile("s_waitcnt vmcnt(" #n ")" ::: "memory")
; #define PG8_WAIT_L(n) asm volatile("s_waitcnt lgkmcnt(" #n ")" ::: "memory")
; #define PG8_BAR __builtin_amdgcn_s_barrier()
; #define PG8_SCHED __builtin_amdgcn_sched_barrier(0)
; template <class Epi, bool ALIGN_EPI>
; DI void gemm_phase(LAS unsigned char* lds, const Sched& S, const Epi& E, int tid) {
;     ...
;         for (int t = 0; t < nt; t += 2) {
;             const bool last = (t == nt - 2);
;             const char* a1 = cA + (size_t)(t + 1) * kstep;
;             const char* a2 = last ? nA : cA + (size_t)(t + 2) * kstep; const char* b2 = last ? nB : cB + (size_t)(t + 2) * kstep;
;             const char* a3 = a2 + kstep; const char* b3 = b2 + kstep;
;             PG8_LDB(B0, 0, 0); PG8_LDB(B1, 0, 1); PG8_SCHED; PG8_LDA(At, 0, 0); PG8_STAGE(PG8_SA(1, 1), a1 + hstepA, voffA);
;             PG8_WAIT_V(8); PG8_WAIT_L(0); PG8_BAR; PG8_MMA(0, 0, At, B0); PG8_MMA(0, 1, At, B1); PG8_BAR; PG8_SCHED;
;             PG8_LDA(At, 0, 1); PG8_STAGE(PG8_SB(0, 0), b2, voffB); PG8_STAGE(PG8_SB(0, 1), b2 + hstepB, voffB); PG8_STAGE(PG8_SA(0, 0), a2, voffA);
;             PG8_WAIT_V(8); PG8_WAIT_L(0); PG8_BAR; PG8_MMA(1, 0, At, B0); PG8_MMA(1, 1, At, B1); PG8_BAR; PG8_SCHED;
.LBB0_1764:
	s_and_b64 s[28:29], s[18:19], exec
	s_cselect_b32 s54, s15, s25
	s_cselect_b32 s55, s14, s24
	s_cselect_b32 s56, s17, s27
	s_cselect_b32 s57, s16, s26
	s_add_i32 s58, s23, -2
	s_add_u32 s24, s24, 0x40080
	s_addc_u32 s25, s25, 0
	s_add_u32 s59, s26, 0x100
	s_mov_b32 s81, s63
	s_addc_u32 s60, s27, 0
	s_mov_b32 s26, 0
	s_waitcnt lgkmcnt(0)
	s_add_i32 s61, s26, 2
	s_add_u32 s27, s24, 0xfffc0080
	s_addc_u32 s28, s25, -1
	s_add_i32 s62, 0, 0x10000
	s_cmp_eq_u32 s58, s26
	s_cselect_b32 s29, s54, s28
	s_cselect_b32 s28, s55, s27
	s_cselect_b32 s27, s56, s60
	s_cselect_b32 s26, s57, s59
	s_add_i32 s64, 0, 0x14000
	v_add_u32_e32 v144, s62, v161
	v_add_u32_e32 v174, s64, v161
	ds_read_b128 v[132:135], v144
	ds_read_b128 v[136:139], v144 offset:1024
	ds_read_b128 v[140:143], v144 offset:2048
	ds_read_b128 v[144:147], v144 offset:3072
	ds_read_b128 v[148:151], v174
	ds_read_b128 v[152:155], v174 offset:1024
	ds_read_b128 v[156:159], v174 offset:2048
	ds_read_b128 v[174:177], v174 offset:3072
	v_lshl_add_u64 v[190:191], s[24:25], 0, v[170:171]
	s_add_i32 m0, s41, 0xc000
	ds_read_b128 v[178:181], v193
	ds_read_b128 v[182:185], v193 offset:1024
	ds_read_b128 v[186:189], v193 offset:2048
	ds_read_b128 v[202:205], v193 offset:3072
	ds_read_b128 v[206:209], v193 offset:4096
	ds_read_b128 v[210:213], v193 offset:5120
	ds_read_b128 v[214:217], v193 offset:6144
	ds_read_b128 v[218:221], v193 offset:7168
	global_load_lds_dwordx4 v[190:191], off
	v_lshl_add_u64 v[190:191], s[24:25], 0, v[172:173]
	s_add_i32 m0, s41, 0xe000
	s_nop 0
	global_load_lds_dwordx4 v[190:191], off
	s_waitcnt vmcnt(8)
	s_waitcnt lgkmcnt(0)
	s_barrier
	s_setprio 1
	s_waitcnt lgkmcnt(0)
	v_mfma_f32_16x16x32_bf16 v[128:131], v[132:135], v[178:181], 0
	v_mfma_f32_16x16x32_bf16 v[124:127], v[140:143], v[178:181], 0
	v_mfma_f32_16x16x32_bf16 v[112:115], v[132:135], v[186:189], 0
	v_mfma_f32_16x16x32_bf16 v[108:111], v[140:143], v[186:189], 0
	v_mfma_f32_16x16x32_bf16 v[96:99], v[132:135], v[206:209], 0
	v_mfma_f32_16x16x32_bf16 v[92:95], v[140:143], v[206:209], 0
	v_mfma_f32_16x16x32_bf16 v[80:83], v[132:135], v[214:217], 0
	v_mfma_f32_16x16x32_bf16 v[76:79], v[140:143], v[214:217], 0
	v_mfma_f32_16x16x32_bf16 v[128:131], v[136:139], v[182:185], v[128:131]
	v_mfma_f32_16x16x32_bf16 v[124:127], v[144:147], v[182:185], v[124:127]
	v_mfma_f32_16x16x32_bf16 v[112:115], v[136:139], v[202:205], v[112:115]
	v_mfma_f32_16x16x32_bf16 v[108:111], v[144:147], v[202:205], v[108:111]
	v_mfma_f32_16x16x32_bf16 v[96:99], v[136:139], v[210:213], v[96:99]
	v_mfma_f32_16x16x32_bf16 v[92:95], v[144:147], v[210:213], v[92:95]
	v_mfma_f32_16x16x32_bf16 v[80:83], v[136:139], v[218:221], v[80:83]
	v_mfma_f32_16x16x32_bf16 v[76:79], v[144:147], v[218:221], v[76:79]
	s_setprio 0
	s_setprio 1
	v_mfma_f32_16x16x32_bf16 v[120:123], v[148:151], v[178:181], 0
	v_mfma_f32_16x16x32_bf16 v[116:119], v[156:159], v[178:181], 0
	v_mfma_f32_16x16x32_bf16 v[104:107], v[148:151], v[186:189], 0
	v_mfma_f32_16x16x32_bf16 v[100:103], v[156:159], v[186:189], 0
	v_mfma_f32_16x16x32_bf16 v[88:91], v[148:151], v[206:209], 0
	v_mfma_f32_16x16x32_bf16 v[84:87], v[156:159], v[206:209], 0
	v_mfma_f32_16x16x32_bf16 v[72:75], v[148:151], v[214:217], 0
	v_mfma_f32_16x16x32_bf16 v[68:71], v[156:159], v[214:217], 0
	v_mfma_f32_16x16x32_bf16 v[120:123], v[152:155], v[182:185], v[120:123]
	v_mfma_f32_16x16x32_bf16 v[116:119], v[174:177], v[182:185], v[116:119]
	v_mfma_f32_16x16x32_bf16 v[104:107], v[152:155], v[202:205], v[104:107]
	v_mfma_f32_16x16x32_bf16 v[100:103], v[174:177], v[202:205], v[100:103]
	v_mfma_f32_16x16x32_bf16 v[88:91], v[152:155], v[210:213], v[88:91]
	v_mfma_f32_16x16x32_bf16 v[84:87], v[174:177], v[210:213], v[84:87]
	v_mfma_f32_16x16x32_bf16 v[72:75], v[152:155], v[218:221], v[72:75]
	v_mfma_f32_16x16x32_bf16 v[68:71], v[174:177], v[218:221], v[68:71]
	s_setprio 0
	s_barrier
	s_add_i32 s62, s62, s40
	v_lshl_add_u64 v[190:191], s[26:27], 0, v[164:165]
	s_mov_b32 m0, s62
	ds_read_b128 v[178:181], v193 offset:16384
	ds_read_b128 v[182:185], v193 offset:17408
	ds_read_b128 v[186:189], v193 offset:18432
	ds_read_b128 v[202:205], v193 offset:19456
	ds_read_b128 v[206:209], v193 offset:20480
	ds_read_b128 v[210:213], v193 offset:21504
	ds_read_b128 v[214:217], v193 offset:22528
	ds_read_b128 v[218:221], v193 offset:23552
	global_load_lds_dwordx4 v[190:191], off
	s_add_i32 m0, s62, 0x2000
	s_add_u32 s62, s26, 0x40000
	v_lshl_add_u64 v[194:195], s[26:27], 0, v[168:169]
	s_addc_u32 s63, s27, 0
	s_add_i32 s64, s64, s40
	global_load_lds_dwordx4 v[194:195], off
	v_lshl_add_u64 v[222:223], s[62:63], 0, v[164:165]
	s_mov_b32 m0, s64
	v_lshl_add_u64 v[224:225], s[28:29], 0, v[166:167]
	global_load_lds_dwordx4 v[222:223], off
	v_lshl_add_u64 v[222:223], s[62:63], 0, v[168:169]
	s_add_i32 m0, s64, 0x2000
	s_nop 0
	global_load_lds_dwordx4 v[222:223], off
	v_lshl_add_u64 v[222:223], s[28:29], 0, v[162:163]
	s_mov_b32 m0, s41
	s_nop 0
	global_load_lds_dwordx4 v[222:223], off
	s_mov_b32 m0, s42
	s_nop 0
	global_load_lds_dwordx4 v[224:225], off
	s_waitcnt vmcnt(8)
	s_waitcnt lgkmcnt(0)
	s_barrier
; #define PG8_STAGE(bufoff, gbase, voff) do { _Pragma("unroll") for (int _i = 0; _i < 2; ++_i) \
;         __builtin_amdgcn_global_load_lds((const unsigned*)((const char*)(gbase) + (voff)[_i]), (LAS unsigned*)(lds + (bufoff) + ldsw + _i * 8192), 16, 0, 0); } while (0)
; #define PG8_LDA(dst, b, h) do { _Pragma("unroll") for (int m = 0; m < 4; ++m) _Pragma("unroll") for (int k = 0; k < 2; ++k) dst[m][k] = *(const LAS bf16x8*)(lds + PG8_SA(b, h) + aoff + m * 2048 + k * 1024); } while (0)
; #define PG8_LDB(dst, b, h) do { _Pragma("unroll") for (int n = 0; n < 2; ++n) _Pragma("unroll") for (int k = 0; k < 2; ++k) dst[n][k] = *(const LAS bf16x8*)(lds + PG8_SB(b, h) + boff + n * 2048 + k * 1024); } while (0)
; #define PG8_MMA(ai, bj, At, Bt) do { __builtin_amdgcn_s_setprio(1); _Pragma("unroll") for (int m = 0; m < 4; ++m) _Pragma("unroll") for (int n = 0; n < 2; ++n) _Pragma("unroll") for (int k = 0; k < 2; ++k) \
;         acc[ai][bj][m][n] = __builtin_amdgcn_mfma_f32_16x16x32_bf16(Bt[n][k], At[m][k], acc[ai][bj][m][n], 0, 0, 0); __builtin_amdgcn_s_setprio(0); } while (0)
; #define PG8_WAIT_V(n) asm volatile("s_waitcnt vmcnt(" #n ")" ::: "memory")
; #define PG8_WAIT_L(n) asm volatile("s_waitcnt lgkmcnt(" #n ")" ::: "memory")
; #define PG8_BAR __builtin_amdgcn_s_barrier()
; #define PG8_SCHED __builtin_amdgcn_sched_barrier(0)
; template <class Epi, bool ALIGN_EPI>
; DI void gemm_phase(LAS unsigned char* lds, const Sched& S, const Epi& E, int tid) {
;     ...
;             PG8_WAIT_V(8); PG8_WAIT_L(0); PG8_BAR; PG8_MMA(1, 0, At, B0); PG8_MMA(1, 1, At, B1); PG8_BAR; PG8_SCHED;
;             PG8_LDB(B0, 1, 0); PG8_LDB(B1, 1, 1); PG8_SCHED; PG8_LDA(At, 1, 0); PG8_STAGE(PG8_SA(0, 1), a2 + hstepA, voffA);
;             PG8_WAIT_V(8); PG8_WAIT_L(0); PG8_BAR; PG8_MMA(0, 0, At, B0); PG8_MMA(0, 1, At, B1); PG8_BAR; PG8_SCHED;
	s_setprio 1
	s_waitcnt lgkmcnt(0)
	v_mfma_f32_16x16x32_bf16 v[64:67], v[132:135], v[178:181], 0
	v_mfma_f32_16x16x32_bf16 v[60:63], v[140:143], v[178:181], 0
	v_mfma_f32_16x16x32_bf16 v[48:51], v[132:135], v[186:189], 0
	v_mfma_f32_16x16x32_bf16 v[44:47], v[140:143], v[186:189], 0
	v_mfma_f32_16x16x32_bf16 v[32:35], v[132:135], v[206:209], 0
	v_mfma_f32_16x16x32_bf16 v[28:31], v[140:143], v[206:209], 0
	v_mfma_f32_16x16x32_bf16 v[16:19], v[132:135], v[214:217], 0
	v_mfma_f32_16x16x32_bf16 v[12:15], v[140:143], v[214:217], 0
	v_mfma_f32_16x16x32_bf16 v[64:67], v[136:139], v[182:185], v[64:67]
	v_mfma_f32_16x16x32_bf16 v[60:63], v[144:147], v[182:185], v[60:63]
	v_mfma_f32_16x16x32_bf16 v[48:51], v[136:139], v[202:205], v[48:51]
	v_mfma_f32_16x16x32_bf16 v[44:47], v[144:147], v[202:205], v[44:47]
	v_mfma_f32_16x16x32_bf16 v[32:35], v[136:139], v[210:213], v[32:35]
	v_mfma_f32_16x16x32_bf16 v[28:31], v[144:147], v[210:213], v[28:31]
	v_mfma_f32_16x16x32_bf16 v[16:19], v[136:139], v[218:221], v[16:19]
	v_mfma_f32_16x16x32_bf16 v[12:15], v[144:147], v[218:221], v[12:15]
	s_setprio 0
	s_setprio 1
	v_mfma_f32_16x16x32_bf16 v[56:59], v[148:151], v[178:181], 0
	v_mfma_f32_16x16x32_bf16 v[52:55], v[156:159], v[178:181], 0
	v_mfma_f32_16x16x32_bf16 v[40:43], v[148:151], v[186:189], 0
	v_mfma_f32_16x16x32_bf16 v[36:39], v[156:159], v[186:189], 0
	v_mfma_f32_16x16x32_bf16 v[24:27], v[148:151], v[206:209], 0
	v_mfma_f32_16x16x32_bf16 v[20:23], v[156:159], v[206:209], 0
	v_mfma_f32_16x16x32_bf16 v[8:11], v[148:151], v[214:217], 0
	v_mfma_f32_16x16x32_bf16 v[4:7], v[156:159], v[214:217], 0
	v_mfma_f32_16x16x32_bf16 v[56:59], v[152:155], v[182:185], v[56:59]
	v_mfma_f32_16x16x32_bf16 v[52:55], v[174:177], v[182:185], v[52:55]
	v_mfma_f32_16x16x32_bf16 v[40:43], v[152:155], v[202:205], v[40:43]
	v_mfma_f32_16x16x32_bf16 v[36:39], v[174:177], v[202:205], v[36:39]
	v_mfma_f32_16x16x32_bf16 v[24:27], v[152:155], v[210:213], v[24:27]
	v_mfma_f32_16x16x32_bf16 v[20:23], v[174:177], v[210:213], v[20:23]
	v_mfma_f32_16x16x32_bf16 v[8:11], v[152:155], v[218:221], v[8:11]
	v_mfma_f32_16x16x32_bf16 v[4:7], v[174:177], v[218:221], v[4:7]
	s_setprio 0
	s_barrier
	s_add_i32 s62, 0, 0x18000
	s_add_i32 s63, 0, 0x1c000
	v_add_u32_e32 v144, s62, v161
	v_add_u32_e32 v174, s63, v161
	ds_read_b128 v[132:135], v144
	ds_read_b128 v[136:139], v144 offset:1024
	ds_read_b128 v[140:143], v144 offset:2048
	ds_read_b128 v[144:147], v144 offset:3072
	ds_read_b128 v[148:151], v174
	ds_read_b128 v[152:155], v174 offset:1024
	ds_read_b128 v[156:159], v174 offset:2048
	ds_read_b128 v[174:177], v174 offset:3072
	s_add_u32 s28, s28, 0x40000
	s_addc_u32 s29, s29, 0
	s_mov_b32 m0, s43
	v_lshl_add_u64 v[226:227], s[28:29], 0, v[162:163]
	ds_read_b128 v[178:181], v193 offset:32768
	ds_read_b128 v[182:185], v193 offset:33792
	ds_read_b128 v[186:189], v193 offset:34816
	ds_read_b128 v[202:205], v193 offset:35840
	ds_read_b128 v[206:209], v193 offset:36864
	ds_read_b128 v[210:213], v193 offset:37888
	ds_read_b128 v[214:217], v193 offset:38912
	ds_read_b128 v[218:221], v193 offset:39936
	global_load_lds_dwordx4 v[226:227], off
	v_lshl_add_u64 v[226:227], s[28:29], 0, v[166:167]
	s_mov_b32 m0, s44
	s_nop 0
	global_load_lds_dwordx4 v[226:227], off
	s_waitcnt vmcnt(8)
	s_waitcnt lgkmcnt(0)
	s_barrier
	s_setprio 1
	s_waitcnt lgkmcnt(0)
	v_mfma_f32_16x16x32_bf16 v[128:131], v[132:135], v[178:181], v[128:131]
	v_mfma_f32_16x16x32_bf16 v[124:127], v[140:143], v[178:181], v[124:127]
	v_mfma_f32_16x16x32_bf16 v[112:115], v[132:135], v[186:189], v[112:115]
	v_mfma_f32_16x16x32_bf16 v[108:111], v[140:143], v[186:189], v[108:111]
	v_mfma_f32_16x16x32_bf16 v[96:99], v[132:135], v[206:209], v[96:99]
	v_mfma_f32_16x16x32_bf16 v[92:95], v[140:143], v[206:209], v[92:95]
	v_mfma_f32_16x16x32_bf16 v[80:83], v[132:135], v[214:217], v[80:83]
	v_mfma_f32_16x16x32_bf16 v[76:79], v[140:143], v[214:217], v[76:79]
	v_mfma_f32_16x16x32_bf16 v[128:131], v[136:139], v[182:185], v[128:131]
	v_mfma_f32_16x16x32_bf16 v[124:127], v[144:147], v[182:185], v[124:127]
	v_mfma_f32_16x16x32_bf16 v[112:115], v[136:139], v[202:205], v[112:115]
	v_mfma_f32_16x16x32_bf16 v[108:111], v[144:147], v[202:205], v[108:111]
	v_mfma_f32_16x16x32_bf16 v[96:99], v[136:139], v[210:213], v[96:99]
	v_mfma_f32_16x16x32_bf16 v[92:95], v[144:147], v[210:213], v[92:95]
	v_mfma_f32_16x16x32_bf16 v[80:83], v[136:139], v[218:221], v[80:83]
	v_mfma_f32_16x16x32_bf16 v[76:79], v[144:147], v[218:221], v[76:79]
	s_setprio 0
	s_setprio 1
	v_mfma_f32_16x16x32_bf16 v[120:123], v[148:151], v[178:181], v[120:123]
	v_mfma_f32_16x16x32_bf16 v[116:119], v[156:159], v[178:181], v[116:119]
	v_mfma_f32_16x16x32_bf16 v[104:107], v[148:151], v[186:189], v[104:107]
	v_mfma_f32_16x16x32_bf16 v[100:103], v[156:159], v[186:189], v[100:103]
	v_mfma_f32_16x16x32_bf16 v[88:91], v[148:151], v[206:209], v[88:91]
	v_mfma_f32_16x16x32_bf16 v[84:87], v[156:159], v[206:209], v[84:87]
	v_mfma_f32_16x16x32_bf16 v[72:75], v[148:151], v[214:217], v[72:75]
	v_mfma_f32_16x16x32_bf16 v[68:71], v[156:159], v[214:217], v[68:71]
	v_mfma_f32_16x16x32_bf16 v[120:123], v[152:155], v[182:185], v[120:123]
	v_mfma_f32_16x16x32_bf16 v[116:119], v[174:177], v[182:185], v[116:119]
	v_mfma_f32_16x16x32_bf16 v[104:107], v[152:155], v[202:205], v[104:107]
	v_mfma_f32_16x16x32_bf16 v[100:103], v[174:177], v[202:205], v[100:103]
	v_mfma_f32_16x16x32_bf16 v[88:91], v[152:155], v[210:213], v[88:91]
	v_mfma_f32_16x16x32_bf16 v[84:87], v[174:177], v[210:213], v[84:87]
	v_mfma_f32_16x16x32_bf16 v[72:75], v[152:155], v[218:221], v[72:75]
	v_mfma_f32_16x16x32_bf16 v[68:71], v[174:177], v[218:221], v[68:71]
	s_setprio 0
	s_barrier
; #define PG8_STAGE(bufoff, gbase, voff) do { _Pragma("unroll") for (int _i = 0; _i < 2; ++_i) \
;         __builtin_amdgcn_global_load_lds((const unsigned*)((const char*)(gbase) + (voff)[_i]), (LAS unsigned*)(lds + (bufoff) + ldsw + _i * 8192), 16, 0, 0); } while (0)
; #define PG8_LDA(dst, b, h) do { _Pragma("unroll") for (int m = 0; m < 4; ++m) _Pragma("unroll") for (int k = 0; k < 2; ++k) dst[m][k] = *(const LAS bf16x8*)(lds + PG8_SA(b, h) + aoff + m * 2048 + k * 1024); } while (0)
; #define PG8_MMA(ai, bj, At, Bt) do { __builtin_amdgcn_s_setprio(1); _Pragma("unroll") for (int m = 0; m < 4; ++m) _Pragma("unroll") for (int n = 0; n < 2; ++n) _Pragma("unroll") for (int k = 0; k < 2; ++k) \
;         acc[ai][bj][m][n] = __builtin_amdgcn_mfma_f32_16x16x32_bf16(Bt[n][k], At[m][k], acc[ai][bj][m][n], 0, 0, 0); __builtin_amdgcn_s_setprio(0); } while (0)
; #define PG8_WAIT_V(n) asm volatile("s_waitcnt vmcnt(" #n ")" ::: "memory")
; #define PG8_WAIT_L(n) asm volatile("s_waitcnt lgkmcnt(" #n ")" ::: "memory")
; #define PG8_BAR __builtin_amdgcn_s_barrier()
; #define PG8_SCHED __builtin_amdgcn_sched_barrier(0)
; template <class Epi, bool ALIGN_EPI>
; DI void gemm_phase(LAS unsigned char* lds, const Sched& S, const Epi& E, int tid) {
;     ...
;             PG8_LDA(At, 1, 1); PG8_STAGE(PG8_SB(1, 0), b3, voffB); PG8_STAGE(PG8_SB(1, 1), b3 + hstepB, voffB); PG8_STAGE(PG8_SA(1, 0), a3, voffA);
;             PG8_WAIT_V(8); PG8_WAIT_L(0); PG8_BAR; PG8_MMA(1, 0, At, B0); PG8_MMA(1, 1, At, B1); PG8_BAR; PG8_SCHED;
;         }
	s_add_i32 s28, s62, s40
	v_lshl_add_u64 v[190:191], v[190:191], 0, s[84:85]
	s_mov_b32 m0, s28
	ds_read_b128 v[178:181], v193 offset:49152
	ds_read_b128 v[182:185], v193 offset:50176
	ds_read_b128 v[186:189], v193 offset:51200
	ds_read_b128 v[202:205], v193 offset:52224
	ds_read_b128 v[206:209], v193 offset:53248
	ds_read_b128 v[210:213], v193 offset:54272
	ds_read_b128 v[214:217], v193 offset:55296
	ds_read_b128 v[218:221], v193 offset:56320
	global_load_lds_dwordx4 v[190:191], off
	s_add_i32 m0, s28, 0x2000
	s_add_u32 s26, s26, 0x40080
	v_lshl_add_u64 v[190:191], v[194:195], 0, s[84:85]
	s_addc_u32 s27, s27, 0
	s_add_i32 s28, s63, s40
	global_load_lds_dwordx4 v[190:191], off
	v_lshl_add_u64 v[190:191], s[26:27], 0, v[164:165]
	s_mov_b32 m0, s28
	s_nop 0
	global_load_lds_dwordx4 v[190:191], off
	v_lshl_add_u64 v[190:191], s[26:27], 0, v[168:169]
	s_add_i32 m0, s28, 0x2000
	s_nop 0
	global_load_lds_dwordx4 v[190:191], off
	v_lshl_add_u64 v[190:191], v[222:223], 0, s[84:85]
	s_mov_b32 m0, s46
	s_nop 0
	global_load_lds_dwordx4 v[190:191], off
	v_lshl_add_u64 v[190:191], v[224:225], 0, s[84:85]
	s_mov_b32 m0, s47
	s_nop 0
	global_load_lds_dwordx4 v[190:191], off
	s_waitcnt vmcnt(8)
	s_waitcnt lgkmcnt(0)
	s_barrier
	s_setprio 1
	s_waitcnt lgkmcnt(0)
	v_mfma_f32_16x16x32_bf16 v[64:67], v[132:135], v[178:181], v[64:67]
	v_mfma_f32_16x16x32_bf16 v[60:63], v[140:143], v[178:181], v[60:63]
	v_mfma_f32_16x16x32_bf16 v[48:51], v[132:135], v[186:189], v[48:51]
	v_mfma_f32_16x16x32_bf16 v[44:47], v[140:143], v[186:189], v[44:47]
	v_mfma_f32_16x16x32_bf16 v[32:35], v[132:135], v[206:209], v[32:35]
	v_mfma_f32_16x16x32_bf16 v[28:31], v[140:143], v[206:209], v[28:31]
	v_mfma_f32_16x16x32_bf16 v[16:19], v[132:135], v[214:217], v[16:19]
	v_mfma_f32_16x16x32_bf16 v[12:15], v[140:143], v[214:217], v[12:15]
	v_mfma_f32_16x16x32_bf16 v[64:67], v[136:139], v[182:185], v[64:67]
	v_mfma_f32_16x16x32_bf16 v[60:63], v[144:147], v[182:185], v[60:63]
	v_mfma_f32_16x16x32_bf16 v[48:51], v[136:139], v[202:205], v[48:51]
	v_mfma_f32_16x16x32_bf16 v[44:47], v[144:147], v[202:205], v[44:47]
	v_mfma_f32_16x16x32_bf16 v[32:35], v[136:139], v[210:213], v[32:35]
	v_mfma_f32_16x16x32_bf16 v[28:31], v[144:147], v[210:213], v[28:31]
	v_mfma_f32_16x16x32_bf16 v[16:19], v[136:139], v[218:221], v[16:19]
	v_mfma_f32_16x16x32_bf16 v[12:15], v[144:147], v[218:221], v[12:15]
	s_setprio 0
	s_setprio 1
	v_mfma_f32_16x16x32_bf16 v[56:59], v[148:151], v[178:181], v[56:59]
	v_mfma_f32_16x16x32_bf16 v[52:55], v[156:159], v[178:181], v[52:55]
	v_mfma_f32_16x16x32_bf16 v[40:43], v[148:151], v[186:189], v[40:43]
	v_mfma_f32_16x16x32_bf16 v[36:39], v[156:159], v[186:189], v[36:39]
	v_mfma_f32_16x16x32_bf16 v[24:27], v[148:151], v[206:209], v[24:27]
	v_mfma_f32_16x16x32_bf16 v[20:23], v[156:159], v[206:209], v[20:23]
	v_mfma_f32_16x16x32_bf16 v[8:11], v[148:151], v[214:217], v[8:11]
	v_mfma_f32_16x16x32_bf16 v[4:7], v[156:159], v[214:217], v[4:7]
	v_mfma_f32_16x16x32_bf16 v[56:59], v[152:155], v[182:185], v[56:59]
	v_mfma_f32_16x16x32_bf16 v[52:55], v[174:177], v[182:185], v[52:55]
	v_mfma_f32_16x16x32_bf16 v[40:43], v[152:155], v[202:205], v[40:43]
	v_mfma_f32_16x16x32_bf16 v[36:39], v[174:177], v[202:205], v[36:39]
	v_mfma_f32_16x16x32_bf16 v[24:27], v[152:155], v[210:213], v[24:27]
	v_mfma_f32_16x16x32_bf16 v[20:23], v[174:177], v[210:213], v[20:23]
	v_mfma_f32_16x16x32_bf16 v[8:11], v[152:155], v[218:221], v[8:11]
	v_mfma_f32_16x16x32_bf16 v[4:7], v[174:177], v[218:221], v[4:7]
	s_setprio 0
	s_barrier
	s_add_u32 s24, s24, 0x100
	s_addc_u32 s25, s25, 0
	s_add_u32 s59, s59, 0x100
	s_addc_u32 s60, s60, 0
	s_cmp_ge_i32 s61, s23
	s_mov_b32 s26, s61

; #define PG8_STAGE(bufoff, gbase, voff) do { _Pragma("unroll") for (int _i = 0; _i < 2; ++_i) \
;         __builtin_amdgcn_global_load_lds((const unsigned*)((const char*)(gbase) + (voff)[_i]), (LAS unsigned*)(lds + (bufoff) + ldsw + _i * 8192), 16, 0, 0); } while (0)
; #define PG8_LDA(dst, b, h) do { _Pragma("unroll") for (int m = 0; m < 4; ++m) _Pragma("unroll") for (int k = 0; k < 2; ++k) dst[m][k] = *(const LAS bf16x8*)(lds + PG8_SA(b, h) + aoff + m * 2048 + k * 1024); } while (0)
; #define PG8_LDB(dst, b, h) do { _Pragma("unroll") for (int n = 0; n < 2; ++n) _Pragma("unroll") for (int k = 0; k < 2; ++k) dst[n][k] = *(const LAS bf16x8*)(lds + PG8_SB(b, h) + boff + n * 2048 + k * 1024); } while (0)
; #define PG8_MMA(ai, bj, At, Bt) do { __builtin_amdgcn_s_setprio(1); _Pragma("unroll") for (int m = 0; m < 4; ++m) _Pragma("unroll") for (int n = 0; n < 2; ++n) _Pragma("unroll") for (int k = 0; k < 2; ++k) \
;         acc[ai][bj][m][n] = __builtin_amdgcn_mfma_f32_16x16x32_bf16(Bt[n][k], At[m][k], acc[ai][bj][m][n], 0, 0, 0); __builtin_amdgcn_s_setprio(0); } while (0)
; #define PG8_WAIT_V(n) asm volatile("s_waitcnt vmcnt(" #n ")" ::: "memory")
; #define PG8_WAIT_L(n) asm volatile("s_waitcnt lgkmcnt(" #n ")" ::: "memory")
; #define PG8_BAR __builtin_amdgcn_s_barrier()
; #define PG8_SCHED __builtin_amdgcn_sched_barrier(0)
; template <class Epi, bool ALIGN_EPI>
; DI void gemm_phase(LAS unsigned char* lds, const Sched& S, const Epi& E, int tid) {
;     ...
;         for (int t = 0; t < nt; t += 2) {
;             const bool last = (t == nt - 2);
;             const char* a1 = cA + (size_t)(t + 1) * kstep;
;             const char* a2 = last ? nA : cA + (size_t)(t + 2) * kstep; const char* b2 = last ? nB : cB + (size_t)(t + 2) * kstep;
;             const char* a3 = a2 + kstep; const char* b3 = b2 + kstep;
;             PG8_LDB(B0, 0, 0); PG8_LDB(B1, 0, 1); PG8_SCHED; PG8_LDA(At, 0, 0); PG8_STAGE(PG8_SA(1, 1), a1 + hstepA, voffA);
;             PG8_WAIT_V(8); PG8_WAIT_L(0); PG8_BAR; PG8_MMA(0, 0, At, B0); PG8_MMA(0, 1, At, B1); PG8_BAR; PG8_SCHED;
;             PG8_LDA(At, 0, 1); PG8_STAGE(PG8_SB(0, 0), b2, voffB); PG8_STAGE(PG8_SB(0, 1), b2 + hstepB, voffB); PG8_STAGE(PG8_SA(0, 0), a2, voffA);
;             PG8_WAIT_V(8); PG8_WAIT_L(0); PG8_BAR; PG8_MMA(1, 0, At, B0); PG8_MMA(1, 1, At, B1); PG8_BAR; PG8_SCHED;
.LBB0_1960:
	s_add_u32 s22, s22, 0x40080
	s_addc_u32 s23, s23, 0
	s_add_u32 s45, s24, 0x100
	s_addc_u32 s46, s25, 0
	s_mov_b32 s47, -2
	s_add_u32 s24, s22, 0xfffc0080
	s_addc_u32 s25, s23, -1
	s_add_i32 s48, 0, 0x10000
	s_cmp_eq_u32 s47, 12
	s_cselect_b32 s27, s19, s25
	s_cselect_b32 s26, s18, s24
	v_add_u32_e32 v161, s48, v144
	s_cselect_b32 s25, s21, s46
	s_cselect_b32 s24, s20, s45
	s_add_i32 s50, 0, 0x14000
	ds_read_b128 v[148:151], v161
	ds_read_b128 v[152:155], v161 offset:1024
	ds_read_b128 v[156:159], v161 offset:2048
	ds_read_b128 v[162:165], v161 offset:3072
	v_add_u32_e32 v161, s50, v144
	ds_read_b128 v[166:169], v161
	ds_read_b128 v[170:173], v161 offset:1024
	ds_read_b128 v[174:177], v161 offset:2048
	ds_read_b128 v[178:181], v161 offset:3072
	v_lshl_add_u64 v[194:195], s[22:23], 0, v[140:141]
	s_add_i32 m0, s17, 0xc000
	ds_read_b128 v[182:185], v147
	ds_read_b128 v[186:189], v147 offset:1024
	ds_read_b128 v[190:193], v147 offset:2048
	ds_read_b128 v[202:205], v147 offset:3072
	ds_read_b128 v[206:209], v147 offset:4096
	ds_read_b128 v[210:213], v147 offset:5120
	ds_read_b128 v[214:217], v147 offset:6144
	ds_read_b128 v[218:221], v147 offset:7168
	global_load_lds_dwordx4 v[194:195], off
	v_lshl_add_u64 v[194:195], s[22:23], 0, v[142:143]
	s_add_i32 m0, s17, 0xe000
	s_nop 0
	global_load_lds_dwordx4 v[194:195], off
	s_waitcnt vmcnt(8)
	s_waitcnt lgkmcnt(0)
	s_barrier
	s_setprio 1
	s_waitcnt lgkmcnt(0)
	v_mfma_f32_16x16x32_bf16 v[128:131], v[148:151], v[182:185], 0
	v_mfma_f32_16x16x32_bf16 v[124:127], v[156:159], v[182:185], 0
	v_mfma_f32_16x16x32_bf16 v[120:123], v[148:151], v[190:193], 0
	v_mfma_f32_16x16x32_bf16 v[112:115], v[156:159], v[190:193], 0
	v_mfma_f32_16x16x32_bf16 v[100:103], v[148:151], v[206:209], 0
	v_mfma_f32_16x16x32_bf16 v[92:95], v[156:159], v[206:209], 0
	v_mfma_f32_16x16x32_bf16 v[88:91], v[148:151], v[214:217], 0
	v_mfma_f32_16x16x32_bf16 v[80:83], v[156:159], v[214:217], 0
	v_mfma_f32_16x16x32_bf16 v[128:131], v[152:155], v[186:189], v[128:131]
	v_mfma_f32_16x16x32_bf16 v[124:127], v[162:165], v[186:189], v[124:127]
	v_mfma_f32_16x16x32_bf16 v[120:123], v[152:155], v[202:205], v[120:123]
	v_mfma_f32_16x16x32_bf16 v[112:115], v[162:165], v[202:205], v[112:115]
	v_mfma_f32_16x16x32_bf16 v[100:103], v[152:155], v[210:213], v[100:103]
	v_mfma_f32_16x16x32_bf16 v[92:95], v[162:165], v[210:213], v[92:95]
	v_mfma_f32_16x16x32_bf16 v[88:91], v[152:155], v[218:221], v[88:91]
	v_mfma_f32_16x16x32_bf16 v[80:83], v[162:165], v[218:221], v[80:83]
	s_setprio 0
	s_setprio 1
	v_mfma_f32_16x16x32_bf16 v[116:119], v[166:169], v[182:185], 0
	v_mfma_f32_16x16x32_bf16 v[108:111], v[174:177], v[182:185], 0
	v_mfma_f32_16x16x32_bf16 v[104:107], v[166:169], v[190:193], 0
	v_mfma_f32_16x16x32_bf16 v[96:99], v[174:177], v[190:193], 0
	v_mfma_f32_16x16x32_bf16 v[84:87], v[166:169], v[206:209], 0
	v_mfma_f32_16x16x32_bf16 v[76:79], v[174:177], v[206:209], 0
	v_mfma_f32_16x16x32_bf16 v[72:75], v[166:169], v[214:217], 0
	v_mfma_f32_16x16x32_bf16 v[68:71], v[174:177], v[214:217], 0
	v_mfma_f32_16x16x32_bf16 v[116:119], v[170:173], v[186:189], v[116:119]
	v_mfma_f32_16x16x32_bf16 v[108:111], v[178:181], v[186:189], v[108:111]
	v_mfma_f32_16x16x32_bf16 v[104:107], v[170:173], v[202:205], v[104:107]
	v_mfma_f32_16x16x32_bf16 v[96:99], v[178:181], v[202:205], v[96:99]
	v_mfma_f32_16x16x32_bf16 v[84:87], v[170:173], v[210:213], v[84:87]
	v_mfma_f32_16x16x32_bf16 v[76:79], v[178:181], v[210:213], v[76:79]
	v_mfma_f32_16x16x32_bf16 v[72:75], v[170:173], v[218:221], v[72:75]
	v_mfma_f32_16x16x32_bf16 v[68:71], v[178:181], v[218:221], v[68:71]
	s_setprio 0
	s_barrier
	s_add_i32 s48, s48, s28
	v_lshl_add_u64 v[194:195], s[24:25], 0, v[136:137]
	s_mov_b32 m0, s48
	ds_read_b128 v[182:185], v147 offset:16384
	ds_read_b128 v[186:189], v147 offset:17408
	ds_read_b128 v[190:193], v147 offset:18432
	ds_read_b128 v[202:205], v147 offset:19456
	ds_read_b128 v[206:209], v147 offset:20480
	ds_read_b128 v[210:213], v147 offset:21504
	ds_read_b128 v[214:217], v147 offset:22528
	ds_read_b128 v[218:221], v147 offset:23552
	global_load_lds_dwordx4 v[194:195], off
	s_add_i32 m0, s48, 0x2000
	s_add_u32 s48, s24, 0x40000
	v_lshl_add_u64 v[222:223], s[24:25], 0, v[132:133]
	s_addc_u32 s49, s25, 0
	s_add_i32 s50, s50, s28
	global_load_lds_dwordx4 v[222:223], off
	v_lshl_add_u64 v[224:225], s[48:49], 0, v[136:137]
	s_mov_b32 m0, s50
	v_lshl_add_u64 v[226:227], s[26:27], 0, v[134:135]
	global_load_lds_dwordx4 v[224:225], off
	v_lshl_add_u64 v[224:225], s[48:49], 0, v[132:133]
	s_add_i32 m0, s50, 0x2000
	s_nop 0
	global_load_lds_dwordx4 v[224:225], off
	v_lshl_add_u64 v[224:225], s[26:27], 0, v[138:139]
	s_mov_b32 m0, s17
	s_nop 0
	global_load_lds_dwordx4 v[224:225], off
	s_mov_b32 m0, s36
	s_nop 0
	global_load_lds_dwordx4 v[226:227], off
	s_waitcnt vmcnt(8)
	s_waitcnt lgkmcnt(0)
	s_barrier
; #define PG8_STAGE(bufoff, gbase, voff) do { _Pragma("unroll") for (int _i = 0; _i < 2; ++_i) \
;         __builtin_amdgcn_global_load_lds((const unsigned*)((const char*)(gbase) + (voff)[_i]), (LAS unsigned*)(lds + (bufoff) + ldsw + _i * 8192), 16, 0, 0); } while (0)
; #define PG8_LDA(dst, b, h) do { _Pragma("unroll") for (int m = 0; m < 4; ++m) _Pragma("unroll") for (int k = 0; k < 2; ++k) dst[m][k] = *(const LAS bf16x8*)(lds + PG8_SA(b, h) + aoff + m * 2048 + k * 1024); } while (0)
; #define PG8_LDB(dst, b, h) do { _Pragma("unroll") for (int n = 0; n < 2; ++n) _Pragma("unroll") for (int k = 0; k < 2; ++k) dst[n][k] = *(const LAS bf16x8*)(lds + PG8_SB(b, h) + boff + n * 2048 + k * 1024); } while (0)
; #define PG8_MMA(ai, bj, At, Bt) do { __builtin_amdgcn_s_setprio(1); _Pragma("unroll") for (int m = 0; m < 4; ++m) _Pragma("unroll") for (int n = 0; n < 2; ++n) _Pragma("unroll") for (int k = 0; k < 2; ++k) \
;         acc[ai][bj][m][n] = __builtin_amdgcn_mfma_f32_16x16x32_bf16(Bt[n][k], At[m][k], acc[ai][bj][m][n], 0, 0, 0); __builtin_amdgcn_s_setprio(0); } while (0)
; #define PG8_WAIT_V(n) asm volatile("s_waitcnt vmcnt(" #n ")" ::: "memory")
; #define PG8_WAIT_L(n) asm volatile("s_waitcnt lgkmcnt(" #n ")" ::: "memory")
; #define PG8_BAR __builtin_amdgcn_s_barrier()
; #define PG8_SCHED __builtin_amdgcn_sched_barrier(0)
; template <class Epi, bool ALIGN_EPI>
; DI void gemm_phase(LAS unsigned char* lds, const Sched& S, const Epi& E, int tid) {
;     ...
;             PG8_WAIT_V(8); PG8_WAIT_L(0); PG8_BAR; PG8_MMA(1, 0, At, B0); PG8_MMA(1, 1, At, B1); PG8_BAR; PG8_SCHED;
;             PG8_LDB(B0, 1, 0); PG8_LDB(B1, 1, 1); PG8_SCHED; PG8_LDA(At, 1, 0); PG8_STAGE(PG8_SA(0, 1), a2 + hstepA, voffA);
;             PG8_WAIT_V(8); PG8_WAIT_L(0); PG8_BAR; PG8_MMA(0, 0, At, B0); PG8_MMA(0, 1, At, B1); PG8_BAR; PG8_SCHED;
	s_setprio 1
	s_waitcnt lgkmcnt(0)
	v_mfma_f32_16x16x32_bf16 v[64:67], v[148:151], v[182:185], 0
	v_mfma_f32_16x16x32_bf16 v[60:63], v[156:159], v[182:185], 0
	v_mfma_f32_16x16x32_bf16 v[56:59], v[148:151], v[190:193], 0
	v_mfma_f32_16x16x32_bf16 v[48:51], v[156:159], v[190:193], 0
	v_mfma_f32_16x16x32_bf16 v[40:43], v[148:151], v[206:209], 0
	v_mfma_f32_16x16x32_bf16 v[32:35], v[156:159], v[206:209], 0
	v_mfma_f32_16x16x32_bf16 v[24:27], v[148:151], v[214:217], 0
	v_mfma_f32_16x16x32_bf16 v[16:19], v[156:159], v[214:217], 0
	v_mfma_f32_16x16x32_bf16 v[64:67], v[152:155], v[186:189], v[64:67]
	v_mfma_f32_16x16x32_bf16 v[60:63], v[162:165], v[186:189], v[60:63]
	v_mfma_f32_16x16x32_bf16 v[56:59], v[152:155], v[202:205], v[56:59]
	v_mfma_f32_16x16x32_bf16 v[48:51], v[162:165], v[202:205], v[48:51]
	v_mfma_f32_16x16x32_bf16 v[40:43], v[152:155], v[210:213], v[40:43]
	v_mfma_f32_16x16x32_bf16 v[32:35], v[162:165], v[210:213], v[32:35]
	v_mfma_f32_16x16x32_bf16 v[24:27], v[152:155], v[218:221], v[24:27]
	v_mfma_f32_16x16x32_bf16 v[16:19], v[162:165], v[218:221], v[16:19]
	s_setprio 0
	s_setprio 1
	v_mfma_f32_16x16x32_bf16 v[52:55], v[166:169], v[182:185], 0
	v_mfma_f32_16x16x32_bf16 v[44:47], v[174:177], v[182:185], 0
	v_mfma_f32_16x16x32_bf16 v[36:39], v[166:169], v[190:193], 0
	v_mfma_f32_16x16x32_bf16 v[28:31], v[174:177], v[190:193], 0
	v_mfma_f32_16x16x32_bf16 v[20:23], v[166:169], v[206:209], 0
	v_mfma_f32_16x16x32_bf16 v[12:15], v[174:177], v[206:209], 0
	v_mfma_f32_16x16x32_bf16 v[8:11], v[166:169], v[214:217], 0
	v_mfma_f32_16x16x32_bf16 v[4:7], v[174:177], v[214:217], 0
	v_mfma_f32_16x16x32_bf16 v[52:55], v[170:173], v[186:189], v[52:55]
	v_mfma_f32_16x16x32_bf16 v[44:47], v[178:181], v[186:189], v[44:47]
	v_mfma_f32_16x16x32_bf16 v[36:39], v[170:173], v[202:205], v[36:39]
	v_mfma_f32_16x16x32_bf16 v[28:31], v[178:181], v[202:205], v[28:31]
	v_mfma_f32_16x16x32_bf16 v[20:23], v[170:173], v[210:213], v[20:23]
	v_mfma_f32_16x16x32_bf16 v[12:15], v[178:181], v[210:213], v[12:15]
	v_mfma_f32_16x16x32_bf16 v[8:11], v[170:173], v[218:221], v[8:11]
	v_mfma_f32_16x16x32_bf16 v[4:7], v[178:181], v[218:221], v[4:7]
	s_setprio 0
	s_barrier
	s_add_i32 s48, 0, 0x18000
	v_add_u32_e32 v161, s48, v144
	s_add_i32 s49, 0, 0x1c000
	ds_read_b128 v[148:151], v161
	ds_read_b128 v[152:155], v161 offset:1024
	ds_read_b128 v[156:159], v161 offset:2048
	ds_read_b128 v[162:165], v161 offset:3072
	v_add_u32_e32 v161, s49, v144
	ds_read_b128 v[166:169], v161
	ds_read_b128 v[170:173], v161 offset:1024
	ds_read_b128 v[174:177], v161 offset:2048
	ds_read_b128 v[178:181], v161 offset:3072
	s_add_u32 s26, s26, 0x40000
	s_addc_u32 s27, s27, 0
	s_mov_b32 m0, s37
	v_lshl_add_u64 v[228:229], s[26:27], 0, v[138:139]
	ds_read_b128 v[182:185], v147 offset:32768
	ds_read_b128 v[186:189], v147 offset:33792
	ds_read_b128 v[190:193], v147 offset:34816
	ds_read_b128 v[202:205], v147 offset:35840
	ds_read_b128 v[206:209], v147 offset:36864
	ds_read_b128 v[210:213], v147 offset:37888
	ds_read_b128 v[214:217], v147 offset:38912
	ds_read_b128 v[218:221], v147 offset:39936
	global_load_lds_dwordx4 v[228:229], off
	v_lshl_add_u64 v[228:229], s[26:27], 0, v[134:135]
	s_mov_b32 m0, s38
	s_nop 0
	global_load_lds_dwordx4 v[228:229], off
	s_waitcnt vmcnt(8)
	s_waitcnt lgkmcnt(0)
	s_barrier
	s_setprio 1
	s_waitcnt lgkmcnt(0)
	v_mfma_f32_16x16x32_bf16 v[128:131], v[148:151], v[182:185], v[128:131]
	v_mfma_f32_16x16x32_bf16 v[124:127], v[156:159], v[182:185], v[124:127]
	v_mfma_f32_16x16x32_bf16 v[120:123], v[148:151], v[190:193], v[120:123]
	v_mfma_f32_16x16x32_bf16 v[112:115], v[156:159], v[190:193], v[112:115]
	v_mfma_f32_16x16x32_bf16 v[100:103], v[148:151], v[206:209], v[100:103]
	v_mfma_f32_16x16x32_bf16 v[92:95], v[156:159], v[206:209], v[92:95]
	v_mfma_f32_16x16x32_bf16 v[88:91], v[148:151], v[214:217], v[88:91]
	v_mfma_f32_16x16x32_bf16 v[80:83], v[156:159], v[214:217], v[80:83]
	v_mfma_f32_16x16x32_bf16 v[128:131], v[152:155], v[186:189], v[128:131]
	v_mfma_f32_16x16x32_bf16 v[124:127], v[162:165], v[186:189], v[124:127]
	v_mfma_f32_16x16x32_bf16 v[120:123], v[152:155], v[202:205], v[120:123]
	v_mfma_f32_16x16x32_bf16 v[112:115], v[162:165], v[202:205], v[112:115]
	v_mfma_f32_16x16x32_bf16 v[100:103], v[152:155], v[210:213], v[100:103]
	v_mfma_f32_16x16x32_bf16 v[92:95], v[162:165], v[210:213], v[92:95]
	v_mfma_f32_16x16x32_bf16 v[88:91], v[152:155], v[218:221], v[88:91]
	v_mfma_f32_16x16x32_bf16 v[80:83], v[162:165], v[218:221], v[80:83]
	s_setprio 0
	s_setprio 1
	v_mfma_f32_16x16x32_bf16 v[116:119], v[166:169], v[182:185], v[116:119]
	v_mfma_f32_16x16x32_bf16 v[108:111], v[174:177], v[182:185], v[108:111]
	v_mfma_f32_16x16x32_bf16 v[104:107], v[166:169], v[190:193], v[104:107]
	v_mfma_f32_16x16x32_bf16 v[96:99], v[174:177], v[190:193], v[96:99]
	v_mfma_f32_16x16x32_bf16 v[84:87], v[166:169], v[206:209], v[84:87]
	v_mfma_f32_16x16x32_bf16 v[76:79], v[174:177], v[206:209], v[76:79]
	v_mfma_f32_16x16x32_bf16 v[72:75], v[166:169], v[214:217], v[72:75]
	v_mfma_f32_16x16x32_bf16 v[68:71], v[174:177], v[214:217], v[68:71]
	v_mfma_f32_16x16x32_bf16 v[116:119], v[170:173], v[186:189], v[116:119]
	v_mfma_f32_16x16x32_bf16 v[108:111], v[178:181], v[186:189], v[108:111]
	v_mfma_f32_16x16x32_bf16 v[104:107], v[170:173], v[202:205], v[104:107]
	v_mfma_f32_16x16x32_bf16 v[96:99], v[178:181], v[202:205], v[96:99]
	v_mfma_f32_16x16x32_bf16 v[84:87], v[170:173], v[210:213], v[84:87]
	v_mfma_f32_16x16x32_bf16 v[76:79], v[178:181], v[210:213], v[76:79]
	v_mfma_f32_16x16x32_bf16 v[72:75], v[170:173], v[218:221], v[72:75]
	v_mfma_f32_16x16x32_bf16 v[68:71], v[178:181], v[218:221], v[68:71]
	s_setprio 0
	s_barrier
; #define PG8_STAGE(bufoff, gbase, voff) do { _Pragma("unroll") for (int _i = 0; _i < 2; ++_i) \
;         __builtin_amdgcn_global_load_lds((const unsigned*)((const char*)(gbase) + (voff)[_i]), (LAS unsigned*)(lds + (bufoff) + ldsw + _i * 8192), 16, 0, 0); } while (0)
; #define PG8_LDA(dst, b, h) do { _Pragma("unroll") for (int m = 0; m < 4; ++m) _Pragma("unroll") for (int k = 0; k < 2; ++k) dst[m][k] = *(const LAS bf16x8*)(lds + PG8_SA(b, h) + aoff + m * 2048 + k * 1024); } while (0)
; #define PG8_MMA(ai, bj, At, Bt) do { __builtin_amdgcn_s_setprio(1); _Pragma("unroll") for (int m = 0; m < 4; ++m) _Pragma("unroll") for (int n = 0; n < 2; ++n) _Pragma("unroll") for (int k = 0; k < 2; ++k) \
;         acc[ai][bj][m][n] = __builtin_amdgcn_mfma_f32_16x16x32_bf16(Bt[n][k], At[m][k], acc[ai][bj][m][n], 0, 0, 0); __builtin_amdgcn_s_setprio(0); } while (0)
; #define PG8_WAIT_V(n) asm volatile("s_waitcnt vmcnt(" #n ")" ::: "memory")
; #define PG8_WAIT_L(n) asm volatile("s_waitcnt lgkmcnt(" #n ")" ::: "memory")
; #define PG8_BAR __builtin_amdgcn_s_barrier()
; #define PG8_SCHED __builtin_amdgcn_sched_barrier(0)
; template <class Epi, bool ALIGN_EPI>
; DI void gemm_phase(LAS unsigned char* lds, const Sched& S, const Epi& E, int tid) {
;     ...
;             PG8_LDA(At, 1, 1); PG8_STAGE(PG8_SB(1, 0), b3, voffB); PG8_STAGE(PG8_SB(1, 1), b3 + hstepB, voffB); PG8_STAGE(PG8_SA(1, 0), a3, voffA);
;             PG8_WAIT_V(8); PG8_WAIT_L(0); PG8_BAR; PG8_MMA(1, 0, At, B0); PG8_MMA(1, 1, At, B1); PG8_BAR; PG8_SCHED;
;         }
	s_add_i32 s26, s48, s28
	v_lshl_add_u64 v[194:195], v[194:195], 0, s[84:85]
	s_mov_b32 m0, s26
	ds_read_b128 v[182:185], v147 offset:49152
	ds_read_b128 v[186:189], v147 offset:50176
	ds_read_b128 v[190:193], v147 offset:51200
	ds_read_b128 v[202:205], v147 offset:52224
	ds_read_b128 v[206:209], v147 offset:53248
	ds_read_b128 v[210:213], v147 offset:54272
	ds_read_b128 v[214:217], v147 offset:55296
	ds_read_b128 v[218:221], v147 offset:56320
	global_load_lds_dwordx4 v[194:195], off
	s_add_i32 m0, s26, 0x2000
	s_add_u32 s24, s24, 0x40080
	v_lshl_add_u64 v[194:195], v[222:223], 0, s[84:85]
	s_addc_u32 s25, s25, 0
	s_add_i32 s26, s49, s28
	global_load_lds_dwordx4 v[194:195], off
	v_lshl_add_u64 v[194:195], s[24:25], 0, v[136:137]
	s_mov_b32 m0, s26
	s_nop 0
	global_load_lds_dwordx4 v[194:195], off
	v_lshl_add_u64 v[194:195], s[24:25], 0, v[132:133]
	s_add_i32 m0, s26, 0x2000
	s_nop 0
	global_load_lds_dwordx4 v[194:195], off
	v_lshl_add_u64 v[194:195], v[224:225], 0, s[84:85]
	s_mov_b32 m0, s39
	s_nop 0
	global_load_lds_dwordx4 v[194:195], off
	v_lshl_add_u64 v[194:195], v[226:227], 0, s[84:85]
	s_mov_b32 m0, s40
	s_nop 0
	global_load_lds_dwordx4 v[194:195], off
	s_waitcnt vmcnt(8)
	s_waitcnt lgkmcnt(0)
	s_barrier
	s_setprio 1
	s_waitcnt lgkmcnt(0)
	v_mfma_f32_16x16x32_bf16 v[64:67], v[148:151], v[182:185], v[64:67]
	v_mfma_f32_16x16x32_bf16 v[60:63], v[156:159], v[182:185], v[60:63]
	v_mfma_f32_16x16x32_bf16 v[56:59], v[148:151], v[190:193], v[56:59]
	v_mfma_f32_16x16x32_bf16 v[48:51], v[156:159], v[190:193], v[48:51]
	v_mfma_f32_16x16x32_bf16 v[40:43], v[148:151], v[206:209], v[40:43]
	v_mfma_f32_16x16x32_bf16 v[32:35], v[156:159], v[206:209], v[32:35]
	v_mfma_f32_16x16x32_bf16 v[24:27], v[148:151], v[214:217], v[24:27]
	v_mfma_f32_16x16x32_bf16 v[16:19], v[156:159], v[214:217], v[16:19]
	v_mfma_f32_16x16x32_bf16 v[64:67], v[152:155], v[186:189], v[64:67]
	v_mfma_f32_16x16x32_bf16 v[60:63], v[162:165], v[186:189], v[60:63]
	v_mfma_f32_16x16x32_bf16 v[56:59], v[152:155], v[202:205], v[56:59]
	v_mfma_f32_16x16x32_bf16 v[48:51], v[162:165], v[202:205], v[48:51]
	v_mfma_f32_16x16x32_bf16 v[40:43], v[152:155], v[210:213], v[40:43]
	v_mfma_f32_16x16x32_bf16 v[32:35], v[162:165], v[210:213], v[32:35]
	v_mfma_f32_16x16x32_bf16 v[24:27], v[152:155], v[218:221], v[24:27]
	v_mfma_f32_16x16x32_bf16 v[16:19], v[162:165], v[218:221], v[16:19]
	s_setprio 0
	s_setprio 1
	v_mfma_f32_16x16x32_bf16 v[52:55], v[166:169], v[182:185], v[52:55]
	v_mfma_f32_16x16x32_bf16 v[44:47], v[174:177], v[182:185], v[44:47]
	v_mfma_f32_16x16x32_bf16 v[36:39], v[166:169], v[190:193], v[36:39]
	v_mfma_f32_16x16x32_bf16 v[28:31], v[174:177], v[190:193], v[28:31]
	v_mfma_f32_16x16x32_bf16 v[20:23], v[166:169], v[206:209], v[20:23]
	v_mfma_f32_16x16x32_bf16 v[12:15], v[174:177], v[206:209], v[12:15]
	v_mfma_f32_16x16x32_bf16 v[8:11], v[166:169], v[214:217], v[8:11]
	v_mfma_f32_16x16x32_bf16 v[4:7], v[174:177], v[214:217], v[4:7]
	v_mfma_f32_16x16x32_bf16 v[52:55], v[170:173], v[186:189], v[52:55]
	v_mfma_f32_16x16x32_bf16 v[44:47], v[178:181], v[186:189], v[44:47]
	v_mfma_f32_16x16x32_bf16 v[36:39], v[170:173], v[202:205], v[36:39]
	v_mfma_f32_16x16x32_bf16 v[28:31], v[178:181], v[202:205], v[28:31]
	v_mfma_f32_16x16x32_bf16 v[20:23], v[170:173], v[210:213], v[20:23]
	v_mfma_f32_16x16x32_bf16 v[12:15], v[178:181], v[210:213], v[12:15]
	v_mfma_f32_16x16x32_bf16 v[8:11], v[170:173], v[218:221], v[8:11]
	v_mfma_f32_16x16x32_bf16 v[4:7], v[178:181], v[218:221], v[4:7]
	s_setprio 0
	s_barrier
	s_add_i32 s47, s47, 2
	s_add_u32 s22, s22, 0x100
	s_addc_u32 s23, s23, 0
	s_add_u32 s45, s45, 0x100
	s_addc_u32 s46, s46, 0
	s_cmp_gt_u32 s47, 13

; #define PG8_STAGE(bufoff, gbase, voff) do { _Pragma("unroll") for (int _i = 0; _i < 2; ++_i) \
;         __builtin_amdgcn_global_load_lds((const unsigned*)((const char*)(gbase) + (voff)[_i]), (LAS unsigned*)(lds + (bufoff) + ldsw + _i * 8192), 16, 0, 0); } while (0)
; #define PG8_LDA(dst, b, h) do { _Pragma("unroll") for (int m = 0; m < 4; ++m) _Pragma("unroll") for (int k = 0; k < 2; ++k) dst[m][k] = *(const LAS bf16x8*)(lds + PG8_SA(b, h) + aoff + m * 2048 + k * 1024); } while (0)
; #define PG8_LDB(dst, b, h) do { _Pragma("unroll") for (int n = 0; n < 2; ++n) _Pragma("unroll") for (int k = 0; k < 2; ++k) dst[n][k] = *(const LAS bf16x8*)(lds + PG8_SB(b, h) + boff + n * 2048 + k * 1024); } while (0)
; #define PG8_MMA(ai, bj, At, Bt) do { __builtin_amdgcn_s_setprio(1); _Pragma("unroll") for (int m = 0; m < 4; ++m) _Pragma("unroll") for (int n = 0; n < 2; ++n) _Pragma("unroll") for (int k = 0; k < 2; ++k) \
;         acc[ai][bj][m][n] = __builtin_amdgcn_mfma_f32_16x16x32_bf16(Bt[n][k], At[m][k], acc[ai][bj][m][n], 0, 0, 0); __builtin_amdgcn_s_setprio(0); } while (0)
; #define PG8_WAIT_V(n) asm volatile("s_waitcnt vmcnt(" #n ")" ::: "memory")
; #define PG8_WAIT_L(n) asm volatile("s_waitcnt lgkmcnt(" #n ")" ::: "memory")
; #define PG8_BAR __builtin_amdgcn_s_barrier()
; #define PG8_SCHED __builtin_amdgcn_sched_barrier(0)
; template <class Epi, bool ALIGN_EPI>
; DI void gemm_phase(LAS unsigned char* lds, const Sched& S, const Epi& E, int tid) {
;     ...
;         for (int t = 0; t < nt; t += 2) {
;             const bool last = (t == nt - 2);
;             const char* a1 = cA + (size_t)(t + 1) * kstep;
;             const char* a2 = last ? nA : cA + (size_t)(t + 2) * kstep; const char* b2 = last ? nB : cB + (size_t)(t + 2) * kstep;
;             const char* a3 = a2 + kstep; const char* b3 = b2 + kstep;
;             PG8_LDB(B0, 0, 0); PG8_LDB(B1, 0, 1); PG8_SCHED; PG8_LDA(At, 0, 0); PG8_STAGE(PG8_SA(1, 1), a1 + hstepA, voffA);
;             PG8_WAIT_V(8); PG8_WAIT_L(0); PG8_BAR; PG8_MMA(0, 0, At, B0); PG8_MMA(0, 1, At, B1); PG8_BAR; PG8_SCHED;
;             PG8_LDA(At, 0, 1); PG8_STAGE(PG8_SB(0, 0), b2, voffB); PG8_STAGE(PG8_SB(0, 1), b2 + hstepB, voffB); PG8_STAGE(PG8_SA(0, 0), a2, voffA);
;             PG8_WAIT_V(8); PG8_WAIT_L(0); PG8_BAR; PG8_MMA(1, 0, At, B0); PG8_MMA(1, 1, At, B1); PG8_BAR; PG8_SCHED;
.LBB0_2124:
	s_and_b64 s[28:29], s[18:19], exec
	s_cselect_b32 s54, s15, s25
	s_cselect_b32 s55, s14, s24
	s_cselect_b32 s56, s17, s27
	s_cselect_b32 s57, s16, s26
	s_add_i32 s58, s23, -2
	s_add_u32 s24, s24, 0x20080
	s_addc_u32 s25, s25, 0
	s_add_u32 s59, s26, 0x100
	s_mov_b32 s81, s63
	s_addc_u32 s60, s27, 0
	s_mov_b32 s26, 0
	s_waitcnt lgkmcnt(0)
	s_add_i32 s61, s26, 2
	s_add_u32 s27, s24, 0xfffe0080
	s_addc_u32 s28, s25, -1
	s_add_i32 s62, 0, 0x10000
	s_cmp_eq_u32 s58, s26
	s_cselect_b32 s29, s54, s28
	s_cselect_b32 s28, s55, s27
	s_cselect_b32 s27, s56, s60
	s_cselect_b32 s26, s57, s59
	s_add_i32 s64, 0, 0x14000
	v_add_u32_e32 v144, s62, v161
	v_add_u32_e32 v174, s64, v161
	ds_read_b128 v[132:135], v144
	ds_read_b128 v[136:139], v144 offset:1024
	ds_read_b128 v[140:143], v144 offset:2048
	ds_read_b128 v[144:147], v144 offset:3072
	ds_read_b128 v[148:151], v174
	ds_read_b128 v[152:155], v174 offset:1024
	ds_read_b128 v[156:159], v174 offset:2048
	ds_read_b128 v[174:177], v174 offset:3072
	v_lshl_add_u64 v[190:191], s[24:25], 0, v[170:171]
	s_add_i32 m0, s41, 0xc000
	ds_read_b128 v[178:181], v193
	ds_read_b128 v[182:185], v193 offset:1024
	ds_read_b128 v[186:189], v193 offset:2048
	ds_read_b128 v[202:205], v193 offset:3072
	ds_read_b128 v[206:209], v193 offset:4096
	ds_read_b128 v[210:213], v193 offset:5120
	ds_read_b128 v[214:217], v193 offset:6144
	ds_read_b128 v[218:221], v193 offset:7168
	global_load_lds_dwordx4 v[190:191], off
	v_lshl_add_u64 v[190:191], s[24:25], 0, v[172:173]
	s_add_i32 m0, s41, 0xe000
	s_nop 0
	global_load_lds_dwordx4 v[190:191], off
	s_waitcnt vmcnt(8)
	s_waitcnt lgkmcnt(0)
	s_barrier
	s_setprio 1
	s_waitcnt lgkmcnt(0)
	v_mfma_f32_16x16x32_bf16 v[128:131], v[132:135], v[178:181], 0
	v_mfma_f32_16x16x32_bf16 v[124:127], v[140:143], v[178:181], 0
	v_mfma_f32_16x16x32_bf16 v[112:115], v[132:135], v[186:189], 0
	v_mfma_f32_16x16x32_bf16 v[108:111], v[140:143], v[186:189], 0
	v_mfma_f32_16x16x32_bf16 v[96:99], v[132:135], v[206:209], 0
	v_mfma_f32_16x16x32_bf16 v[92:95], v[140:143], v[206:209], 0
	v_mfma_f32_16x16x32_bf16 v[80:83], v[132:135], v[214:217], 0
	v_mfma_f32_16x16x32_bf16 v[76:79], v[140:143], v[214:217], 0
	v_mfma_f32_16x16x32_bf16 v[128:131], v[136:139], v[182:185], v[128:131]
	v_mfma_f32_16x16x32_bf16 v[124:127], v[144:147], v[182:185], v[124:127]
	v_mfma_f32_16x16x32_bf16 v[112:115], v[136:139], v[202:205], v[112:115]
	v_mfma_f32_16x16x32_bf16 v[108:111], v[144:147], v[202:205], v[108:111]
	v_mfma_f32_16x16x32_bf16 v[96:99], v[136:139], v[210:213], v[96:99]
	v_mfma_f32_16x16x32_bf16 v[92:95], v[144:147], v[210:213], v[92:95]
	v_mfma_f32_16x16x32_bf16 v[80:83], v[136:139], v[218:221], v[80:83]
	v_mfma_f32_16x16x32_bf16 v[76:79], v[144:147], v[218:221], v[76:79]
	s_setprio 0
	s_setprio 1
	v_mfma_f32_16x16x32_bf16 v[120:123], v[148:151], v[178:181], 0
	v_mfma_f32_16x16x32_bf16 v[116:119], v[156:159], v[178:181], 0
	v_mfma_f32_16x16x32_bf16 v[104:107], v[148:151], v[186:189], 0
	v_mfma_f32_16x16x32_bf16 v[100:103], v[156:159], v[186:189], 0
	v_mfma_f32_16x16x32_bf16 v[88:91], v[148:151], v[206:209], 0
	v_mfma_f32_16x16x32_bf16 v[84:87], v[156:159], v[206:209], 0
	v_mfma_f32_16x16x32_bf16 v[72:75], v[148:151], v[214:217], 0
	v_mfma_f32_16x16x32_bf16 v[68:71], v[156:159], v[214:217], 0
	v_mfma_f32_16x16x32_bf16 v[120:123], v[152:155], v[182:185], v[120:123]
	v_mfma_f32_16x16x32_bf16 v[116:119], v[174:177], v[182:185], v[116:119]
	v_mfma_f32_16x16x32_bf16 v[104:107], v[152:155], v[202:205], v[104:107]
	v_mfma_f32_16x16x32_bf16 v[100:103], v[174:177], v[202:205], v[100:103]
	v_mfma_f32_16x16x32_bf16 v[88:91], v[152:155], v[210:213], v[88:91]
	v_mfma_f32_16x16x32_bf16 v[84:87], v[174:177], v[210:213], v[84:87]
	v_mfma_f32_16x16x32_bf16 v[72:75], v[152:155], v[218:221], v[72:75]
	v_mfma_f32_16x16x32_bf16 v[68:71], v[174:177], v[218:221], v[68:71]
	s_setprio 0
	s_barrier
	s_add_i32 s62, s62, s40
	v_lshl_add_u64 v[190:191], s[26:27], 0, v[164:165]
	s_mov_b32 m0, s62
	ds_read_b128 v[178:181], v193 offset:16384
	ds_read_b128 v[182:185], v193 offset:17408
	ds_read_b128 v[186:189], v193 offset:18432
	ds_read_b128 v[202:205], v193 offset:19456
	ds_read_b128 v[206:209], v193 offset:20480
	ds_read_b128 v[210:213], v193 offset:21504
	ds_read_b128 v[214:217], v193 offset:22528
	ds_read_b128 v[218:221], v193 offset:23552
	global_load_lds_dwordx4 v[190:191], off
	s_add_i32 m0, s62, 0x2000
	s_add_u32 s62, s26, 0x20000
	v_lshl_add_u64 v[194:195], s[26:27], 0, v[168:169]
	s_addc_u32 s63, s27, 0
	s_add_i32 s64, s64, s40
	global_load_lds_dwordx4 v[194:195], off
	v_lshl_add_u64 v[222:223], s[62:63], 0, v[164:165]
	s_mov_b32 m0, s64
	v_lshl_add_u64 v[224:225], s[28:29], 0, v[166:167]
	global_load_lds_dwordx4 v[222:223], off
	v_lshl_add_u64 v[222:223], s[62:63], 0, v[168:169]
	s_add_i32 m0, s64, 0x2000
	s_nop 0
	global_load_lds_dwordx4 v[222:223], off
	v_lshl_add_u64 v[222:223], s[28:29], 0, v[162:163]
	s_mov_b32 m0, s41
	s_nop 0
	global_load_lds_dwordx4 v[222:223], off
	s_mov_b32 m0, s42
	s_nop 0
	global_load_lds_dwordx4 v[224:225], off
	s_waitcnt vmcnt(8)
	s_waitcnt lgkmcnt(0)
	s_barrier
; #define PG8_STAGE(bufoff, gbase, voff) do { _Pragma("unroll") for (int _i = 0; _i < 2; ++_i) \
;         __builtin_amdgcn_global_load_lds((const unsigned*)((const char*)(gbase) + (voff)[_i]), (LAS unsigned*)(lds + (bufoff) + ldsw + _i * 8192), 16, 0, 0); } while (0)
; #define PG8_LDA(dst, b, h) do { _Pragma("unroll") for (int m = 0; m < 4; ++m) _Pragma("unroll") for (int k = 0; k < 2; ++k) dst[m][k] = *(const LAS bf16x8*)(lds + PG8_SA(b, h) + aoff + m * 2048 + k * 1024); } while (0)
; #define PG8_LDB(dst, b, h) do { _Pragma("unroll") for (int n = 0; n < 2; ++n) _Pragma("unroll") for (int k = 0; k < 2; ++k) dst[n][k] = *(const LAS bf16x8*)(lds + PG8_SB(b, h) + boff + n * 2048 + k * 1024); } while (0)
; #define PG8_MMA(ai, bj, At, Bt) do { __builtin_amdgcn_s_setprio(1); _Pragma("unroll") for (int m = 0; m < 4; ++m) _Pragma("unroll") for (int n = 0; n < 2; ++n) _Pragma("unroll") for (int k = 0; k < 2; ++k) \
;         acc[ai][bj][m][n] = __builtin_amdgcn_mfma_f32_16x16x32_bf16(Bt[n][k], At[m][k], acc[ai][bj][m][n], 0, 0, 0); __builtin_amdgcn_s_setprio(0); } while (0)
; #define PG8_WAIT_V(n) asm volatile("s_waitcnt vmcnt(" #n ")" ::: "memory")
; #define PG8_WAIT_L(n) asm volatile("s_waitcnt lgkmcnt(" #n ")" ::: "memory")
; #define PG8_BAR __builtin_amdgcn_s_barrier()
; #define PG8_SCHED __builtin_amdgcn_sched_barrier(0)
; template <class Epi, bool ALIGN_EPI>
; DI void gemm_phase(LAS unsigned char* lds, const Sched& S, const Epi& E, int tid) {
;     ...
;             PG8_WAIT_V(8); PG8_WAIT_L(0); PG8_BAR; PG8_MMA(1, 0, At, B0); PG8_MMA(1, 1, At, B1); PG8_BAR; PG8_SCHED;
;             PG8_LDB(B0, 1, 0); PG8_LDB(B1, 1, 1); PG8_SCHED; PG8_LDA(At, 1, 0); PG8_STAGE(PG8_SA(0, 1), a2 + hstepA, voffA);
;             PG8_WAIT_V(8); PG8_WAIT_L(0); PG8_BAR; PG8_MMA(0, 0, At, B0); PG8_MMA(0, 1, At, B1); PG8_BAR; PG8_SCHED;
	s_setprio 1
	s_waitcnt lgkmcnt(0)
	v_mfma_f32_16x16x32_bf16 v[64:67], v[132:135], v[178:181], 0
	v_mfma_f32_16x16x32_bf16 v[60:63], v[140:143], v[178:181], 0
	v_mfma_f32_16x16x32_bf16 v[48:51], v[132:135], v[186:189], 0
	v_mfma_f32_16x16x32_bf16 v[44:47], v[140:143], v[186:189], 0
	v_mfma_f32_16x16x32_bf16 v[32:35], v[132:135], v[206:209], 0
	v_mfma_f32_16x16x32_bf16 v[28:31], v[140:143], v[206:209], 0
	v_mfma_f32_16x16x32_bf16 v[16:19], v[132:135], v[214:217], 0
	v_mfma_f32_16x16x32_bf16 v[12:15], v[140:143], v[214:217], 0
	v_mfma_f32_16x16x32_bf16 v[64:67], v[136:139], v[182:185], v[64:67]
	v_mfma_f32_16x16x32_bf16 v[60:63], v[144:147], v[182:185], v[60:63]
	v_mfma_f32_16x16x32_bf16 v[48:51], v[136:139], v[202:205], v[48:51]
	v_mfma_f32_16x16x32_bf16 v[44:47], v[144:147], v[202:205], v[44:47]
	v_mfma_f32_16x16x32_bf16 v[32:35], v[136:139], v[210:213], v[32:35]
	v_mfma_f32_16x16x32_bf16 v[28:31], v[144:147], v[210:213], v[28:31]
	v_mfma_f32_16x16x32_bf16 v[16:19], v[136:139], v[218:221], v[16:19]
	v_mfma_f32_16x16x32_bf16 v[12:15], v[144:147], v[218:221], v[12:15]
	s_setprio 0
	s_setprio 1
	v_mfma_f32_16x16x32_bf16 v[56:59], v[148:151], v[178:181], 0
	v_mfma_f32_16x16x32_bf16 v[52:55], v[156:159], v[178:181], 0
	v_mfma_f32_16x16x32_bf16 v[40:43], v[148:151], v[186:189], 0
	v_mfma_f32_16x16x32_bf16 v[36:39], v[156:159], v[186:189], 0
	v_mfma_f32_16x16x32_bf16 v[24:27], v[148:151], v[206:209], 0
	v_mfma_f32_16x16x32_bf16 v[20:23], v[156:159], v[206:209], 0
	v_mfma_f32_16x16x32_bf16 v[8:11], v[148:151], v[214:217], 0
	v_mfma_f32_16x16x32_bf16 v[4:7], v[156:159], v[214:217], 0
	v_mfma_f32_16x16x32_bf16 v[56:59], v[152:155], v[182:185], v[56:59]
	v_mfma_f32_16x16x32_bf16 v[52:55], v[174:177], v[182:185], v[52:55]
	v_mfma_f32_16x16x32_bf16 v[40:43], v[152:155], v[202:205], v[40:43]
	v_mfma_f32_16x16x32_bf16 v[36:39], v[174:177], v[202:205], v[36:39]
	v_mfma_f32_16x16x32_bf16 v[24:27], v[152:155], v[210:213], v[24:27]
	v_mfma_f32_16x16x32_bf16 v[20:23], v[174:177], v[210:213], v[20:23]
	v_mfma_f32_16x16x32_bf16 v[8:11], v[152:155], v[218:221], v[8:11]
	v_mfma_f32_16x16x32_bf16 v[4:7], v[174:177], v[218:221], v[4:7]
	s_setprio 0
	s_barrier
	s_add_i32 s62, 0, 0x18000
	s_add_i32 s63, 0, 0x1c000
	v_add_u32_e32 v144, s62, v161
	v_add_u32_e32 v174, s63, v161
	ds_read_b128 v[132:135], v144
	ds_read_b128 v[136:139], v144 offset:1024
	ds_read_b128 v[140:143], v144 offset:2048
	ds_read_b128 v[144:147], v144 offset:3072
	ds_read_b128 v[148:151], v174
	ds_read_b128 v[152:155], v174 offset:1024
	ds_read_b128 v[156:159], v174 offset:2048
	ds_read_b128 v[174:177], v174 offset:3072
	s_add_u32 s28, s28, 0x20000
	s_addc_u32 s29, s29, 0
	s_mov_b32 m0, s43
	v_lshl_add_u64 v[226:227], s[28:29], 0, v[162:163]
	ds_read_b128 v[178:181], v193 offset:32768
	ds_read_b128 v[182:185], v193 offset:33792
	ds_read_b128 v[186:189], v193 offset:34816
	ds_read_b128 v[202:205], v193 offset:35840
	ds_read_b128 v[206:209], v193 offset:36864
	ds_read_b128 v[210:213], v193 offset:37888
	ds_read_b128 v[214:217], v193 offset:38912
	ds_read_b128 v[218:221], v193 offset:39936
	global_load_lds_dwordx4 v[226:227], off
	v_lshl_add_u64 v[226:227], s[28:29], 0, v[166:167]
	s_mov_b32 m0, s44
	s_nop 0
	global_load_lds_dwordx4 v[226:227], off
	s_waitcnt vmcnt(8)
	s_waitcnt lgkmcnt(0)
	s_barrier
	s_setprio 1
	s_waitcnt lgkmcnt(0)
	v_mfma_f32_16x16x32_bf16 v[128:131], v[132:135], v[178:181], v[128:131]
	v_mfma_f32_16x16x32_bf16 v[124:127], v[140:143], v[178:181], v[124:127]
	v_mfma_f32_16x16x32_bf16 v[112:115], v[132:135], v[186:189], v[112:115]
	v_mfma_f32_16x16x32_bf16 v[108:111], v[140:143], v[186:189], v[108:111]
	v_mfma_f32_16x16x32_bf16 v[96:99], v[132:135], v[206:209], v[96:99]
	v_mfma_f32_16x16x32_bf16 v[92:95], v[140:143], v[206:209], v[92:95]
	v_mfma_f32_16x16x32_bf16 v[80:83], v[132:135], v[214:217], v[80:83]
	v_mfma_f32_16x16x32_bf16 v[76:79], v[140:143], v[214:217], v[76:79]
	v_mfma_f32_16x16x32_bf16 v[128:131], v[136:139], v[182:185], v[128:131]
	v_mfma_f32_16x16x32_bf16 v[124:127], v[144:147], v[182:185], v[124:127]
	v_mfma_f32_16x16x32_bf16 v[112:115], v[136:139], v[202:205], v[112:115]
	v_mfma_f32_16x16x32_bf16 v[108:111], v[144:147], v[202:205], v[108:111]
	v_mfma_f32_16x16x32_bf16 v[96:99], v[136:139], v[210:213], v[96:99]
	v_mfma_f32_16x16x32_bf16 v[92:95], v[144:147], v[210:213], v[92:95]
	v_mfma_f32_16x16x32_bf16 v[80:83], v[136:139], v[218:221], v[80:83]
	v_mfma_f32_16x16x32_bf16 v[76:79], v[144:147], v[218:221], v[76:79]
	s_setprio 0
	s_setprio 1
	v_mfma_f32_16x16x32_bf16 v[120:123], v[148:151], v[178:181], v[120:123]
	v_mfma_f32_16x16x32_bf16 v[116:119], v[156:159], v[178:181], v[116:119]
	v_mfma_f32_16x16x32_bf16 v[104:107], v[148:151], v[186:189], v[104:107]
	v_mfma_f32_16x16x32_bf16 v[100:103], v[156:159], v[186:189], v[100:103]
	v_mfma_f32_16x16x32_bf16 v[88:91], v[148:151], v[206:209], v[88:91]
	v_mfma_f32_16x16x32_bf16 v[84:87], v[156:159], v[206:209], v[84:87]
	v_mfma_f32_16x16x32_bf16 v[72:75], v[148:151], v[214:217], v[72:75]
	v_mfma_f32_16x16x32_bf16 v[68:71], v[156:159], v[214:217], v[68:71]
	v_mfma_f32_16x16x32_bf16 v[120:123], v[152:155], v[182:185], v[120:123]
	v_mfma_f32_16x16x32_bf16 v[116:119], v[174:177], v[182:185], v[116:119]
	v_mfma_f32_16x16x32_bf16 v[104:107], v[152:155], v[202:205], v[104:107]
	v_mfma_f32_16x16x32_bf16 v[100:103], v[174:177], v[202:205], v[100:103]
	v_mfma_f32_16x16x32_bf16 v[88:91], v[152:155], v[210:213], v[88:91]
	v_mfma_f32_16x16x32_bf16 v[84:87], v[174:177], v[210:213], v[84:87]
	v_mfma_f32_16x16x32_bf16 v[72:75], v[152:155], v[218:221], v[72:75]
	v_mfma_f32_16x16x32_bf16 v[68:71], v[174:177], v[218:221], v[68:71]
	s_setprio 0
	s_barrier
; #define PG8_STAGE(bufoff, gbase, voff) do { _Pragma("unroll") for (int _i = 0; _i < 2; ++_i) \
;         __builtin_amdgcn_global_load_lds((const unsigned*)((const char*)(gbase) + (voff)[_i]), (LAS unsigned*)(lds + (bufoff) + ldsw + _i * 8192), 16, 0, 0); } while (0)
; #define PG8_LDA(dst, b, h) do { _Pragma("unroll") for (int m = 0; m < 4; ++m) _Pragma("unroll") for (int k = 0; k < 2; ++k) dst[m][k] = *(const LAS bf16x8*)(lds + PG8_SA(b, h) + aoff + m * 2048 + k * 1024); } while (0)
; #define PG8_MMA(ai, bj, At, Bt) do { __builtin_amdgcn_s_setprio(1); _Pragma("unroll") for (int m = 0; m < 4; ++m) _Pragma("unroll") for (int n = 0; n < 2; ++n) _Pragma("unroll") for (int k = 0; k < 2; ++k) \
;         acc[ai][bj][m][n] = __builtin_amdgcn_mfma_f32_16x16x32_bf16(Bt[n][k], At[m][k], acc[ai][bj][m][n], 0, 0, 0); __builtin_amdgcn_s_setprio(0); } while (0)
; #define PG8_WAIT_V(n) asm volatile("s_waitcnt vmcnt(" #n ")" ::: "memory")
; #define PG8_WAIT_L(n) asm volatile("s_waitcnt lgkmcnt(" #n ")" ::: "memory")
; #define PG8_BAR __builtin_amdgcn_s_barrier()
; #define PG8_SCHED __builtin_amdgcn_sched_barrier(0)
; template <class Epi, bool ALIGN_EPI>
; DI void gemm_phase(LAS unsigned char* lds, const Sched& S, const Epi& E, int tid) {
;     ...
;             PG8_LDA(At, 1, 1); PG8_STAGE(PG8_SB(1, 0), b3, voffB); PG8_STAGE(PG8_SB(1, 1), b3 + hstepB, voffB); PG8_STAGE(PG8_SA(1, 0), a3, voffA);
;             PG8_WAIT_V(8); PG8_WAIT_L(0); PG8_BAR; PG8_MMA(1, 0, At, B0); PG8_MMA(1, 1, At, B1); PG8_BAR; PG8_SCHED;
;         }
	s_add_i32 s28, s62, s40
	v_lshl_add_u64 v[190:191], v[190:191], 0, s[84:85]
	s_mov_b32 m0, s28
	ds_read_b128 v[178:181], v193 offset:49152
	ds_read_b128 v[182:185], v193 offset:50176
	ds_read_b128 v[186:189], v193 offset:51200
	ds_read_b128 v[202:205], v193 offset:52224
	ds_read_b128 v[206:209], v193 offset:53248
	ds_read_b128 v[210:213], v193 offset:54272
	ds_read_b128 v[214:217], v193 offset:55296
	ds_read_b128 v[218:221], v193 offset:56320
	global_load_lds_dwordx4 v[190:191], off
	s_add_i32 m0, s28, 0x2000
	s_add_u32 s26, s26, 0x20080
	v_lshl_add_u64 v[190:191], v[194:195], 0, s[84:85]
	s_addc_u32 s27, s27, 0
	s_add_i32 s28, s63, s40
	global_load_lds_dwordx4 v[190:191], off
	v_lshl_add_u64 v[190:191], s[26:27], 0, v[164:165]
	s_mov_b32 m0, s28
	s_nop 0
	global_load_lds_dwordx4 v[190:191], off
	v_lshl_add_u64 v[190:191], s[26:27], 0, v[168:169]
	s_add_i32 m0, s28, 0x2000
	s_nop 0
	global_load_lds_dwordx4 v[190:191], off
	v_lshl_add_u64 v[190:191], v[222:223], 0, s[84:85]
	s_mov_b32 m0, s46
	s_nop 0
	global_load_lds_dwordx4 v[190:191], off
	v_lshl_add_u64 v[190:191], v[224:225], 0, s[84:85]
	s_mov_b32 m0, s47
	s_nop 0
	global_load_lds_dwordx4 v[190:191], off
	s_waitcnt vmcnt(8)
	s_waitcnt lgkmcnt(0)
	s_barrier
	s_setprio 1
	s_waitcnt lgkmcnt(0)
	v_mfma_f32_16x16x32_bf16 v[64:67], v[132:135], v[178:181], v[64:67]
	v_mfma_f32_16x16x32_bf16 v[60:63], v[140:143], v[178:181], v[60:63]
	v_mfma_f32_16x16x32_bf16 v[48:51], v[132:135], v[186:189], v[48:51]
	v_mfma_f32_16x16x32_bf16 v[44:47], v[140:143], v[186:189], v[44:47]
	v_mfma_f32_16x16x32_bf16 v[32:35], v[132:135], v[206:209], v[32:35]
	v_mfma_f32_16x16x32_bf16 v[28:31], v[140:143], v[206:209], v[28:31]
	v_mfma_f32_16x16x32_bf16 v[16:19], v[132:135], v[214:217], v[16:19]
	v_mfma_f32_16x16x32_bf16 v[12:15], v[140:143], v[214:217], v[12:15]
	v_mfma_f32_16x16x32_bf16 v[64:67], v[136:139], v[182:185], v[64:67]
	v_mfma_f32_16x16x32_bf16 v[60:63], v[144:147], v[182:185], v[60:63]
	v_mfma_f32_16x16x32_bf16 v[48:51], v[136:139], v[202:205], v[48:51]
	v_mfma_f32_16x16x32_bf16 v[44:47], v[144:147], v[202:205], v[44:47]
	v_mfma_f32_16x16x32_bf16 v[32:35], v[136:139], v[210:213], v[32:35]
	v_mfma_f32_16x16x32_bf16 v[28:31], v[144:147], v[210:213], v[28:31]
	v_mfma_f32_16x16x32_bf16 v[16:19], v[136:139], v[218:221], v[16:19]
	v_mfma_f32_16x16x32_bf16 v[12:15], v[144:147], v[218:221], v[12:15]
	s_setprio 0
	s_setprio 1
	v_mfma_f32_16x16x32_bf16 v[56:59], v[148:151], v[178:181], v[56:59]
	v_mfma_f32_16x16x32_bf16 v[52:55], v[156:159], v[178:181], v[52:55]
	v_mfma_f32_16x16x32_bf16 v[40:43], v[148:151], v[186:189], v[40:43]
	v_mfma_f32_16x16x32_bf16 v[36:39], v[156:159], v[186:189], v[36:39]
	v_mfma_f32_16x16x32_bf16 v[24:27], v[148:151], v[206:209], v[24:27]
	v_mfma_f32_16x16x32_bf16 v[20:23], v[156:159], v[206:209], v[20:23]
	v_mfma_f32_16x16x32_bf16 v[8:11], v[148:151], v[214:217], v[8:11]
	v_mfma_f32_16x16x32_bf16 v[4:7], v[156:159], v[214:217], v[4:7]
	v_mfma_f32_16x16x32_bf16 v[56:59], v[152:155], v[182:185], v[56:59]
	v_mfma_f32_16x16x32_bf16 v[52:55], v[174:177], v[182:185], v[52:55]
	v_mfma_f32_16x16x32_bf16 v[40:43], v[152:155], v[202:205], v[40:43]
	v_mfma_f32_16x16x32_bf16 v[36:39], v[174:177], v[202:205], v[36:39]
	v_mfma_f32_16x16x32_bf16 v[24:27], v[152:155], v[210:213], v[24:27]
	v_mfma_f32_16x16x32_bf16 v[20:23], v[174:177], v[210:213], v[20:23]
	v_mfma_f32_16x16x32_bf16 v[8:11], v[152:155], v[218:221], v[8:11]
	v_mfma_f32_16x16x32_bf16 v[4:7], v[174:177], v[218:221], v[4:7]
	s_setprio 0
	s_barrier
	s_add_u32 s24, s24, 0x100
	s_addc_u32 s25, s25, 0
	s_add_u32 s59, s59, 0x100
	s_addc_u32 s60, s60, 0
	s_cmp_ge_i32 s61, s23
	s_mov_b32 s26, s61

; #define PG8_STAGE(bufoff, gbase, voff) do { _Pragma("unroll") for (int _i = 0; _i < 2; ++_i) \
;         __builtin_amdgcn_global_load_lds((const unsigned*)((const char*)(gbase) + (voff)[_i]), (LAS unsigned*)(lds + (bufoff) + ldsw + _i * 8192), 16, 0, 0); } while (0)
; #define PG8_LDA(dst, b, h) do { _Pragma("unroll") for (int m = 0; m < 4; ++m) _Pragma("unroll") for (int k = 0; k < 2; ++k) dst[m][k] = *(const LAS bf16x8*)(lds + PG8_SA(b, h) + aoff + m * 2048 + k * 1024); } while (0)
; #define PG8_LDB(dst, b, h) do { _Pragma("unroll") for (int n = 0; n < 2; ++n) _Pragma("unroll") for (int k = 0; k < 2; ++k) dst[n][k] = *(const LAS bf16x8*)(lds + PG8_SB(b, h) + boff + n * 2048 + k * 1024); } while (0)
; #define PG8_MMA(ai, bj, At, Bt) do { __builtin_amdgcn_s_setprio(1); _Pragma("unroll") for (int m = 0; m < 4; ++m) _Pragma("unroll") for (int n = 0; n < 2; ++n) _Pragma("unroll") for (int k = 0; k < 2; ++k) \
;         acc[ai][bj][m][n] = __builtin_amdgcn_mfma_f32_16x16x32_bf16(Bt[n][k], At[m][k], acc[ai][bj][m][n], 0, 0, 0); __builtin_amdgcn_s_setprio(0); } while (0)
; #define PG8_WAIT_V(n) asm volatile("s_waitcnt vmcnt(" #n ")" ::: "memory")
; #define PG8_WAIT_L(n) asm volatile("s_waitcnt lgkmcnt(" #n ")" ::: "memory")
; #define PG8_BAR __builtin_amdgcn_s_barrier()
; #define PG8_SCHED __builtin_amdgcn_sched_barrier(0)
; template <class Epi, bool ALIGN_EPI>
; DI void gemm_phase(LAS unsigned char* lds, const Sched& S, const Epi& E, int tid) {
;     ...
;         for (int t = 0; t < nt; t += 2) {
;             const bool last = (t == nt - 2);
;             const char* a1 = cA + (size_t)(t + 1) * kstep;
;             const char* a2 = last ? nA : cA + (size_t)(t + 2) * kstep; const char* b2 = last ? nB : cB + (size_t)(t + 2) * kstep;
;             const char* a3 = a2 + kstep; const char* b3 = b2 + kstep;
;             PG8_LDB(B0, 0, 0); PG8_LDB(B1, 0, 1); PG8_SCHED; PG8_LDA(At, 0, 0); PG8_STAGE(PG8_SA(1, 1), a1 + hstepA, voffA);
;             PG8_WAIT_V(8); PG8_WAIT_L(0); PG8_BAR; PG8_MMA(0, 0, At, B0); PG8_MMA(0, 1, At, B1); PG8_BAR; PG8_SCHED;
;             PG8_LDA(At, 0, 1); PG8_STAGE(PG8_SB(0, 0), b2, voffB); PG8_STAGE(PG8_SB(0, 1), b2 + hstepB, voffB); PG8_STAGE(PG8_SA(0, 0), a2, voffA);
;             PG8_WAIT_V(8); PG8_WAIT_L(0); PG8_BAR; PG8_MMA(1, 0, At, B0); PG8_MMA(1, 1, At, B1); PG8_BAR; PG8_SCHED;
.LBB0_2407:
	s_and_b64 s[24:25], s[16:17], exec
	s_cselect_b32 s56, s13, s21
	s_cselect_b32 s57, s12, s20
	s_cselect_b32 s58, s15, s23
	s_cselect_b32 s59, s14, s22
	s_add_i32 s60, s55, -2
	s_add_u32 s61, s22, 0x100
	s_mov_b32 s81, s63
	s_addc_u32 s62, s23, 0
	s_mov_b32 s24, 0
	s_waitcnt lgkmcnt(0)
	s_add_i32 s63, s24, 2
	s_add_u32 s22, s20, 0x100
	s_addc_u32 s23, s21, 0
	s_add_i32 s64, 0, 0x10000
	s_cmp_eq_u32 s60, s24
	s_cselect_b32 s27, s56, s23
	s_cselect_b32 s26, s57, s22
	s_cselect_b32 s25, s58, s62
	s_cselect_b32 s24, s59, s61
	s_add_i32 s65, 0, 0x14000
	v_add_u32_e32 v144, s64, v161
	v_add_u32_e32 v174, s65, v161
	ds_read_b128 v[132:135], v144
	ds_read_b128 v[136:139], v144 offset:1024
	ds_read_b128 v[140:143], v144 offset:2048
	ds_read_b128 v[144:147], v144 offset:3072
	ds_read_b128 v[148:151], v174
	ds_read_b128 v[152:155], v174 offset:1024
	ds_read_b128 v[156:159], v174 offset:2048
	ds_read_b128 v[174:177], v174 offset:3072
	v_lshl_add_u64 v[190:191], s[20:21], 0, v[170:171]
	s_add_i32 m0, s39, 0xc000
	ds_read_b128 v[178:181], v193
	ds_read_b128 v[182:185], v193 offset:1024
	ds_read_b128 v[186:189], v193 offset:2048
	ds_read_b128 v[202:205], v193 offset:3072
	ds_read_b128 v[206:209], v193 offset:4096
	ds_read_b128 v[210:213], v193 offset:5120
	ds_read_b128 v[214:217], v193 offset:6144
	ds_read_b128 v[218:221], v193 offset:7168
	global_load_lds_dwordx4 v[190:191], off
	v_lshl_add_u64 v[190:191], s[20:21], 0, v[172:173]
	s_add_i32 m0, s39, 0xe000
	s_nop 0
	global_load_lds_dwordx4 v[190:191], off
	s_waitcnt vmcnt(8)
	s_waitcnt lgkmcnt(0)
	s_barrier
	s_setprio 1
	s_waitcnt lgkmcnt(0)
	v_mfma_f32_16x16x32_bf16 v[128:131], v[132:135], v[178:181], 0
	v_mfma_f32_16x16x32_bf16 v[124:127], v[140:143], v[178:181], 0
	v_mfma_f32_16x16x32_bf16 v[112:115], v[132:135], v[186:189], 0
	v_mfma_f32_16x16x32_bf16 v[108:111], v[140:143], v[186:189], 0
	v_mfma_f32_16x16x32_bf16 v[96:99], v[132:135], v[206:209], 0
	v_mfma_f32_16x16x32_bf16 v[92:95], v[140:143], v[206:209], 0
	v_mfma_f32_16x16x32_bf16 v[80:83], v[132:135], v[214:217], 0
	v_mfma_f32_16x16x32_bf16 v[76:79], v[140:143], v[214:217], 0
	v_mfma_f32_16x16x32_bf16 v[128:131], v[136:139], v[182:185], v[128:131]
	v_mfma_f32_16x16x32_bf16 v[124:127], v[144:147], v[182:185], v[124:127]
	v_mfma_f32_16x16x32_bf16 v[112:115], v[136:139], v[202:205], v[112:115]
	v_mfma_f32_16x16x32_bf16 v[108:111], v[144:147], v[202:205], v[108:111]
	v_mfma_f32_16x16x32_bf16 v[96:99], v[136:139], v[210:213], v[96:99]
	v_mfma_f32_16x16x32_bf16 v[92:95], v[144:147], v[210:213], v[92:95]
	v_mfma_f32_16x16x32_bf16 v[80:83], v[136:139], v[218:221], v[80:83]
	v_mfma_f32_16x16x32_bf16 v[76:79], v[144:147], v[218:221], v[76:79]
	s_setprio 0
	s_setprio 1
	v_mfma_f32_16x16x32_bf16 v[120:123], v[148:151], v[178:181], 0
	v_mfma_f32_16x16x32_bf16 v[116:119], v[156:159], v[178:181], 0
	v_mfma_f32_16x16x32_bf16 v[104:107], v[148:151], v[186:189], 0
	v_mfma_f32_16x16x32_bf16 v[100:103], v[156:159], v[186:189], 0
	v_mfma_f32_16x16x32_bf16 v[88:91], v[148:151], v[206:209], 0
	v_mfma_f32_16x16x32_bf16 v[84:87], v[156:159], v[206:209], 0
	v_mfma_f32_16x16x32_bf16 v[72:75], v[148:151], v[214:217], 0
	v_mfma_f32_16x16x32_bf16 v[68:71], v[156:159], v[214:217], 0
	v_mfma_f32_16x16x32_bf16 v[120:123], v[152:155], v[182:185], v[120:123]
	v_mfma_f32_16x16x32_bf16 v[116:119], v[174:177], v[182:185], v[116:119]
	v_mfma_f32_16x16x32_bf16 v[104:107], v[152:155], v[202:205], v[104:107]
	v_mfma_f32_16x16x32_bf16 v[100:103], v[174:177], v[202:205], v[100:103]
	v_mfma_f32_16x16x32_bf16 v[88:91], v[152:155], v[210:213], v[88:91]
	v_mfma_f32_16x16x32_bf16 v[84:87], v[174:177], v[210:213], v[84:87]
	v_mfma_f32_16x16x32_bf16 v[72:75], v[152:155], v[218:221], v[72:75]
	v_mfma_f32_16x16x32_bf16 v[68:71], v[174:177], v[218:221], v[68:71]
	s_setprio 0
	s_barrier
	s_add_i32 s20, s64, s38
	v_lshl_add_u64 v[190:191], s[24:25], 0, v[164:165]
	s_mov_b32 m0, s20
	ds_read_b128 v[178:181], v193 offset:16384
	ds_read_b128 v[182:185], v193 offset:17408
	ds_read_b128 v[186:189], v193 offset:18432
	ds_read_b128 v[202:205], v193 offset:19456
	ds_read_b128 v[206:209], v193 offset:20480
	ds_read_b128 v[210:213], v193 offset:21504
	ds_read_b128 v[214:217], v193 offset:22528
	ds_read_b128 v[218:221], v193 offset:23552
	global_load_lds_dwordx4 v[190:191], off
	s_add_i32 m0, s20, 0x2000
	s_add_u32 s20, s24, 0x104000
	v_lshl_add_u64 v[194:195], s[24:25], 0, v[168:169]
	s_addc_u32 s21, s25, 0
	s_add_i32 s64, s65, s38
	global_load_lds_dwordx4 v[194:195], off
	v_lshl_add_u64 v[222:223], s[20:21], 0, v[164:165]
	s_mov_b32 m0, s64
	v_lshl_add_u64 v[224:225], s[26:27], 0, v[166:167]
	global_load_lds_dwordx4 v[222:223], off
	v_lshl_add_u64 v[222:223], s[20:21], 0, v[168:169]
	s_add_i32 m0, s64, 0x2000
	s_nop 0
	global_load_lds_dwordx4 v[222:223], off
	v_lshl_add_u64 v[222:223], s[26:27], 0, v[162:163]
	s_mov_b32 m0, s39
	s_nop 0
	global_load_lds_dwordx4 v[222:223], off
	s_mov_b32 m0, s40
	s_nop 0
	global_load_lds_dwordx4 v[224:225], off
	s_waitcnt vmcnt(8)
	s_waitcnt lgkmcnt(0)
	s_barrier
; #define PG8_STAGE(bufoff, gbase, voff) do { _Pragma("unroll") for (int _i = 0; _i < 2; ++_i) \
;         __builtin_amdgcn_global_load_lds((const unsigned*)((const char*)(gbase) + (voff)[_i]), (LAS unsigned*)(lds + (bufoff) + ldsw + _i * 8192), 16, 0, 0); } while (0)
; #define PG8_LDA(dst, b, h) do { _Pragma("unroll") for (int m = 0; m < 4; ++m) _Pragma("unroll") for (int k = 0; k < 2; ++k) dst[m][k] = *(const LAS bf16x8*)(lds + PG8_SA(b, h) + aoff + m * 2048 + k * 1024); } while (0)
; #define PG8_LDB(dst, b, h) do { _Pragma("unroll") for (int n = 0; n < 2; ++n) _Pragma("unroll") for (int k = 0; k < 2; ++k) dst[n][k] = *(const LAS bf16x8*)(lds + PG8_SB(b, h) + boff + n * 2048 + k * 1024); } while (0)
; #define PG8_MMA(ai, bj, At, Bt) do { __builtin_amdgcn_s_setprio(1); _Pragma("unroll") for (int m = 0; m < 4; ++m) _Pragma("unroll") for (int n = 0; n < 2; ++n) _Pragma("unroll") for (int k = 0; k < 2; ++k) \
;         acc[ai][bj][m][n] = __builtin_amdgcn_mfma_f32_16x16x32_bf16(Bt[n][k], At[m][k], acc[ai][bj][m][n], 0, 0, 0); __builtin_amdgcn_s_setprio(0); } while (0)
; #define PG8_WAIT_V(n) asm volatile("s_waitcnt vmcnt(" #n ")" ::: "memory")
; #define PG8_WAIT_L(n) asm volatile("s_waitcnt lgkmcnt(" #n ")" ::: "memory")
; #define PG8_BAR __builtin_amdgcn_s_barrier()
; #define PG8_SCHED __builtin_amdgcn_sched_barrier(0)
; template <class Epi, bool ALIGN_EPI>
; DI void gemm_phase(LAS unsigned char* lds, const Sched& S, const Epi& E, int tid) {
;     ...
;             PG8_WAIT_V(8); PG8_WAIT_L(0); PG8_BAR; PG8_MMA(1, 0, At, B0); PG8_MMA(1, 1, At, B1); PG8_BAR; PG8_SCHED;
;             PG8_LDB(B0, 1, 0); PG8_LDB(B1, 1, 1); PG8_SCHED; PG8_LDA(At, 1, 0); PG8_STAGE(PG8_SA(0, 1), a2 + hstepA, voffA);
;             PG8_WAIT_V(8); PG8_WAIT_L(0); PG8_BAR; PG8_MMA(0, 0, At, B0); PG8_MMA(0, 1, At, B1); PG8_BAR; PG8_SCHED;
	s_setprio 1
	s_waitcnt lgkmcnt(0)
	v_mfma_f32_16x16x32_bf16 v[64:67], v[132:135], v[178:181], 0
	v_mfma_f32_16x16x32_bf16 v[60:63], v[140:143], v[178:181], 0
	v_mfma_f32_16x16x32_bf16 v[48:51], v[132:135], v[186:189], 0
	v_mfma_f32_16x16x32_bf16 v[44:47], v[140:143], v[186:189], 0
	v_mfma_f32_16x16x32_bf16 v[32:35], v[132:135], v[206:209], 0
	v_mfma_f32_16x16x32_bf16 v[28:31], v[140:143], v[206:209], 0
	v_mfma_f32_16x16x32_bf16 v[16:19], v[132:135], v[214:217], 0
	v_mfma_f32_16x16x32_bf16 v[12:15], v[140:143], v[214:217], 0
	v_mfma_f32_16x16x32_bf16 v[64:67], v[136:139], v[182:185], v[64:67]
	v_mfma_f32_16x16x32_bf16 v[60:63], v[144:147], v[182:185], v[60:63]
	v_mfma_f32_16x16x32_bf16 v[48:51], v[136:139], v[202:205], v[48:51]
	v_mfma_f32_16x16x32_bf16 v[44:47], v[144:147], v[202:205], v[44:47]
	v_mfma_f32_16x16x32_bf16 v[32:35], v[136:139], v[210:213], v[32:35]
	v_mfma_f32_16x16x32_bf16 v[28:31], v[144:147], v[210:213], v[28:31]
	v_mfma_f32_16x16x32_bf16 v[16:19], v[136:139], v[218:221], v[16:19]
	v_mfma_f32_16x16x32_bf16 v[12:15], v[144:147], v[218:221], v[12:15]
	s_setprio 0
	s_setprio 1
	v_mfma_f32_16x16x32_bf16 v[56:59], v[148:151], v[178:181], 0
	v_mfma_f32_16x16x32_bf16 v[52:55], v[156:159], v[178:181], 0
	v_mfma_f32_16x16x32_bf16 v[40:43], v[148:151], v[186:189], 0
	v_mfma_f32_16x16x32_bf16 v[36:39], v[156:159], v[186:189], 0
	v_mfma_f32_16x16x32_bf16 v[24:27], v[148:151], v[206:209], 0
	v_mfma_f32_16x16x32_bf16 v[20:23], v[156:159], v[206:209], 0
	v_mfma_f32_16x16x32_bf16 v[8:11], v[148:151], v[214:217], 0
	v_mfma_f32_16x16x32_bf16 v[4:7], v[156:159], v[214:217], 0
	v_mfma_f32_16x16x32_bf16 v[56:59], v[152:155], v[182:185], v[56:59]
	v_mfma_f32_16x16x32_bf16 v[52:55], v[174:177], v[182:185], v[52:55]
	v_mfma_f32_16x16x32_bf16 v[40:43], v[152:155], v[202:205], v[40:43]
	v_mfma_f32_16x16x32_bf16 v[36:39], v[174:177], v[202:205], v[36:39]
	v_mfma_f32_16x16x32_bf16 v[24:27], v[152:155], v[210:213], v[24:27]
	v_mfma_f32_16x16x32_bf16 v[20:23], v[174:177], v[210:213], v[20:23]
	v_mfma_f32_16x16x32_bf16 v[8:11], v[152:155], v[218:221], v[8:11]
	v_mfma_f32_16x16x32_bf16 v[4:7], v[174:177], v[218:221], v[4:7]
	s_setprio 0
	s_barrier
	s_add_i32 s64, 0, 0x18000
	s_add_i32 s65, 0, 0x1c000
	v_add_u32_e32 v144, s64, v161
	v_add_u32_e32 v174, s65, v161
	ds_read_b128 v[132:135], v144
	ds_read_b128 v[136:139], v144 offset:1024
	ds_read_b128 v[140:143], v144 offset:2048
	ds_read_b128 v[144:147], v144 offset:3072
	ds_read_b128 v[148:151], v174
	ds_read_b128 v[152:155], v174 offset:1024
	ds_read_b128 v[156:159], v174 offset:2048
	ds_read_b128 v[174:177], v174 offset:3072
	s_add_u32 s20, s26, 0x104000
	s_addc_u32 s21, s27, 0
	s_mov_b32 m0, s41
	v_lshl_add_u64 v[226:227], s[20:21], 0, v[162:163]
	ds_read_b128 v[178:181], v193 offset:32768
	ds_read_b128 v[182:185], v193 offset:33792
	ds_read_b128 v[186:189], v193 offset:34816
	ds_read_b128 v[202:205], v193 offset:35840
	ds_read_b128 v[206:209], v193 offset:36864
	ds_read_b128 v[210:213], v193 offset:37888
	ds_read_b128 v[214:217], v193 offset:38912
	ds_read_b128 v[218:221], v193 offset:39936
	global_load_lds_dwordx4 v[226:227], off
	v_lshl_add_u64 v[226:227], s[20:21], 0, v[166:167]
	s_mov_b32 m0, s42
	s_nop 0
	global_load_lds_dwordx4 v[226:227], off
	s_waitcnt vmcnt(8)
	s_waitcnt lgkmcnt(0)
	s_barrier
	s_setprio 1
	s_waitcnt lgkmcnt(0)
	v_mfma_f32_16x16x32_bf16 v[128:131], v[132:135], v[178:181], v[128:131]
	v_mfma_f32_16x16x32_bf16 v[124:127], v[140:143], v[178:181], v[124:127]
	v_mfma_f32_16x16x32_bf16 v[112:115], v[132:135], v[186:189], v[112:115]
	v_mfma_f32_16x16x32_bf16 v[108:111], v[140:143], v[186:189], v[108:111]
	v_mfma_f32_16x16x32_bf16 v[96:99], v[132:135], v[206:209], v[96:99]
	v_mfma_f32_16x16x32_bf16 v[92:95], v[140:143], v[206:209], v[92:95]
	v_mfma_f32_16x16x32_bf16 v[80:83], v[132:135], v[214:217], v[80:83]
	v_mfma_f32_16x16x32_bf16 v[76:79], v[140:143], v[214:217], v[76:79]
	v_mfma_f32_16x16x32_bf16 v[128:131], v[136:139], v[182:185], v[128:131]
	v_mfma_f32_16x16x32_bf16 v[124:127], v[144:147], v[182:185], v[124:127]
	v_mfma_f32_16x16x32_bf16 v[112:115], v[136:139], v[202:205], v[112:115]
	v_mfma_f32_16x16x32_bf16 v[108:111], v[144:147], v[202:205], v[108:111]
	v_mfma_f32_16x16x32_bf16 v[96:99], v[136:139], v[210:213], v[96:99]
	v_mfma_f32_16x16x32_bf16 v[92:95], v[144:147], v[210:213], v[92:95]
	v_mfma_f32_16x16x32_bf16 v[80:83], v[136:139], v[218:221], v[80:83]
	v_mfma_f32_16x16x32_bf16 v[76:79], v[144:147], v[218:221], v[76:79]
	s_setprio 0
	s_setprio 1
	v_mfma_f32_16x16x32_bf16 v[120:123], v[148:151], v[178:181], v[120:123]
	v_mfma_f32_16x16x32_bf16 v[116:119], v[156:159], v[178:181], v[116:119]
	v_mfma_f32_16x16x32_bf16 v[104:107], v[148:151], v[186:189], v[104:107]
	v_mfma_f32_16x16x32_bf16 v[100:103], v[156:159], v[186:189], v[100:103]
	v_mfma_f32_16x16x32_bf16 v[88:91], v[148:151], v[206:209], v[88:91]
	v_mfma_f32_16x16x32_bf16 v[84:87], v[156:159], v[206:209], v[84:87]
	v_mfma_f32_16x16x32_bf16 v[72:75], v[148:151], v[214:217], v[72:75]
	v_mfma_f32_16x16x32_bf16 v[68:71], v[156:159], v[214:217], v[68:71]
	v_mfma_f32_16x16x32_bf16 v[120:123], v[152:155], v[182:185], v[120:123]
	v_mfma_f32_16x16x32_bf16 v[116:119], v[174:177], v[182:185], v[116:119]
	v_mfma_f32_16x16x32_bf16 v[104:107], v[152:155], v[202:205], v[104:107]
	v_mfma_f32_16x16x32_bf16 v[100:103], v[174:177], v[202:205], v[100:103]
	v_mfma_f32_16x16x32_bf16 v[88:91], v[152:155], v[210:213], v[88:91]
	v_mfma_f32_16x16x32_bf16 v[84:87], v[174:177], v[210:213], v[84:87]
	v_mfma_f32_16x16x32_bf16 v[72:75], v[152:155], v[218:221], v[72:75]
	v_mfma_f32_16x16x32_bf16 v[68:71], v[174:177], v[218:221], v[68:71]
	s_setprio 0
	s_barrier
; #define PG8_STAGE(bufoff, gbase, voff) do { _Pragma("unroll") for (int _i = 0; _i < 2; ++_i) \
;         __builtin_amdgcn_global_load_lds((const unsigned*)((const char*)(gbase) + (voff)[_i]), (LAS unsigned*)(lds + (bufoff) + ldsw + _i * 8192), 16, 0, 0); } while (0)
; #define PG8_LDA(dst, b, h) do { _Pragma("unroll") for (int m = 0; m < 4; ++m) _Pragma("unroll") for (int k = 0; k < 2; ++k) dst[m][k] = *(const LAS bf16x8*)(lds + PG8_SA(b, h) + aoff + m * 2048 + k * 1024); } while (0)
; #define PG8_MMA(ai, bj, At, Bt) do { __builtin_amdgcn_s_setprio(1); _Pragma("unroll") for (int m = 0; m < 4; ++m) _Pragma("unroll") for (int n = 0; n < 2; ++n) _Pragma("unroll") for (int k = 0; k < 2; ++k) \
;         acc[ai][bj][m][n] = __builtin_amdgcn_mfma_f32_16x16x32_bf16(Bt[n][k], At[m][k], acc[ai][bj][m][n], 0, 0, 0); __builtin_amdgcn_s_setprio(0); } while (0)
; #define PG8_WAIT_V(n) asm volatile("s_waitcnt vmcnt(" #n ")" ::: "memory")
; #define PG8_WAIT_L(n) asm volatile("s_waitcnt lgkmcnt(" #n ")" ::: "memory")
; #define PG8_BAR __builtin_amdgcn_s_barrier()
; #define PG8_SCHED __builtin_amdgcn_sched_barrier(0)
; template <class Epi, bool ALIGN_EPI>
; DI void gemm_phase(LAS unsigned char* lds, const Sched& S, const Epi& E, int tid) {
;     ...
;             PG8_LDA(At, 1, 1); PG8_STAGE(PG8_SB(1, 0), b3, voffB); PG8_STAGE(PG8_SB(1, 1), b3 + hstepB, voffB); PG8_STAGE(PG8_SA(1, 0), a3, voffA);
;             PG8_WAIT_V(8); PG8_WAIT_L(0); PG8_BAR; PG8_MMA(1, 0, At, B0); PG8_MMA(1, 1, At, B1); PG8_BAR; PG8_SCHED;
;         }
	s_add_i32 s20, s64, s38
	v_lshl_add_u64 v[190:191], v[190:191], 0, s[84:85]
	s_mov_b32 m0, s20
	ds_read_b128 v[178:181], v193 offset:49152
	ds_read_b128 v[182:185], v193 offset:50176
	ds_read_b128 v[186:189], v193 offset:51200
	ds_read_b128 v[202:205], v193 offset:52224
	ds_read_b128 v[206:209], v193 offset:53248
	ds_read_b128 v[210:213], v193 offset:54272
	ds_read_b128 v[214:217], v193 offset:55296
	ds_read_b128 v[218:221], v193 offset:56320
	global_load_lds_dwordx4 v[190:191], off
	s_add_i32 m0, s20, 0x2000
	s_add_u32 s20, s24, 0x104080
	v_lshl_add_u64 v[190:191], v[194:195], 0, s[84:85]
	s_addc_u32 s21, s25, 0
	s_add_i32 s24, s65, s38
	global_load_lds_dwordx4 v[190:191], off
	v_lshl_add_u64 v[190:191], s[20:21], 0, v[164:165]
	s_mov_b32 m0, s24
	s_nop 0
	global_load_lds_dwordx4 v[190:191], off
	v_lshl_add_u64 v[190:191], s[20:21], 0, v[168:169]
	s_add_i32 m0, s24, 0x2000
	s_nop 0
	global_load_lds_dwordx4 v[190:191], off
	v_lshl_add_u64 v[190:191], v[222:223], 0, s[84:85]
	s_mov_b32 m0, s44
	s_nop 0
	global_load_lds_dwordx4 v[190:191], off
	v_lshl_add_u64 v[190:191], v[224:225], 0, s[84:85]
	s_mov_b32 m0, s45
	s_nop 0
	global_load_lds_dwordx4 v[190:191], off
	s_waitcnt vmcnt(8)
	s_waitcnt lgkmcnt(0)
	s_barrier
	s_setprio 1
	s_waitcnt lgkmcnt(0)
	v_mfma_f32_16x16x32_bf16 v[64:67], v[132:135], v[178:181], v[64:67]
	v_mfma_f32_16x16x32_bf16 v[60:63], v[140:143], v[178:181], v[60:63]
	v_mfma_f32_16x16x32_bf16 v[48:51], v[132:135], v[186:189], v[48:51]
	v_mfma_f32_16x16x32_bf16 v[44:47], v[140:143], v[186:189], v[44:47]
	v_mfma_f32_16x16x32_bf16 v[32:35], v[132:135], v[206:209], v[32:35]
	v_mfma_f32_16x16x32_bf16 v[28:31], v[140:143], v[206:209], v[28:31]
	v_mfma_f32_16x16x32_bf16 v[16:19], v[132:135], v[214:217], v[16:19]
	v_mfma_f32_16x16x32_bf16 v[12:15], v[140:143], v[214:217], v[12:15]
	v_mfma_f32_16x16x32_bf16 v[64:67], v[136:139], v[182:185], v[64:67]
	v_mfma_f32_16x16x32_bf16 v[60:63], v[144:147], v[182:185], v[60:63]
	v_mfma_f32_16x16x32_bf16 v[48:51], v[136:139], v[202:205], v[48:51]
	v_mfma_f32_16x16x32_bf16 v[44:47], v[144:147], v[202:205], v[44:47]
	v_mfma_f32_16x16x32_bf16 v[32:35], v[136:139], v[210:213], v[32:35]
	v_mfma_f32_16x16x32_bf16 v[28:31], v[144:147], v[210:213], v[28:31]
	v_mfma_f32_16x16x32_bf16 v[16:19], v[136:139], v[218:221], v[16:19]
	v_mfma_f32_16x16x32_bf16 v[12:15], v[144:147], v[218:221], v[12:15]
	s_setprio 0
	s_setprio 1
	v_mfma_f32_16x16x32_bf16 v[56:59], v[148:151], v[178:181], v[56:59]
	v_mfma_f32_16x16x32_bf16 v[52:55], v[156:159], v[178:181], v[52:55]
	v_mfma_f32_16x16x32_bf16 v[40:43], v[148:151], v[186:189], v[40:43]
	v_mfma_f32_16x16x32_bf16 v[36:39], v[156:159], v[186:189], v[36:39]
	v_mfma_f32_16x16x32_bf16 v[24:27], v[148:151], v[206:209], v[24:27]
	v_mfma_f32_16x16x32_bf16 v[20:23], v[156:159], v[206:209], v[20:23]
	v_mfma_f32_16x16x32_bf16 v[8:11], v[148:151], v[214:217], v[8:11]
	v_mfma_f32_16x16x32_bf16 v[4:7], v[156:159], v[214:217], v[4:7]
	v_mfma_f32_16x16x32_bf16 v[56:59], v[152:155], v[182:185], v[56:59]
	v_mfma_f32_16x16x32_bf16 v[52:55], v[174:177], v[182:185], v[52:55]
	v_mfma_f32_16x16x32_bf16 v[40:43], v[152:155], v[202:205], v[40:43]
	v_mfma_f32_16x16x32_bf16 v[36:39], v[174:177], v[202:205], v[36:39]
	v_mfma_f32_16x16x32_bf16 v[24:27], v[152:155], v[210:213], v[24:27]
	v_mfma_f32_16x16x32_bf16 v[20:23], v[174:177], v[210:213], v[20:23]
	v_mfma_f32_16x16x32_bf16 v[8:11], v[152:155], v[218:221], v[8:11]
	v_mfma_f32_16x16x32_bf16 v[4:7], v[174:177], v[218:221], v[4:7]
	s_setprio 0
	s_barrier
	s_add_u32 s61, s61, 0x100
	s_addc_u32 s62, s62, 0
	s_cmp_ge_i32 s63, s55
	s_mov_b64 s[20:21], s[22:23]
	s_mov_b32 s24, s63
